# residual-add GEMM epilogues: counted per-load waits for the 16 residual loads instead of one vmcnt(0), on top of the LRU/SSD/HGRN wait counts
# speedup vs baseline: 1.0015x; 1.0015x over previous
; #define PG8_STAGE(bufoff, gbase, voff) do { _Pragma("unroll") for (int _i = 0; _i < 2; ++_i) \
;         __builtin_amdgcn_global_load_lds((const unsigned*)((const char*)(gbase) + (voff)[_i]), (LAS unsigned*)(lds + (bufoff) + ldsw + _i * 8192), 16, 0, 0); } while (0)
; #define PG8_LDA(dst, b, h) do { _Pragma("unroll") for (int m = 0; m < 4; ++m) _Pragma("unroll") for (int k = 0; k < 2; ++k) dst[m][k] = *(const LAS bf16x8*)(lds + PG8_SA(b, h) + aoff + m * 2048 + k * 1024); } while (0)
; #define PG8_LDB(dst, b, h) do { _Pragma("unroll") for (int n = 0; n < 2; ++n) _Pragma("unroll") for (int k = 0; k < 2; ++k) dst[n][k] = *(const LAS bf16x8*)(lds + PG8_SB(b, h) + boff + n * 2048 + k * 1024); } while (0)
; #define PG8_MMA(ai, bj, At, Bt) do { __builtin_amdgcn_s_setprio(1); _Pragma("unroll") for (int m = 0; m < 4; ++m) _Pragma("unroll") for (int n = 0; n < 2; ++n) _Pragma("unroll") for (int k = 0; k < 2; ++k) \
;         acc[ai][bj][m][n] = __builtin_amdgcn_mfma_f32_16x16x32_bf16(Bt[n][k], At[m][k], acc[ai][bj][m][n], 0, 0, 0); __builtin_amdgcn_s_setprio(0); } while (0)
; #define PG8_WAIT_L(n) asm volatile("s_waitcnt lgkmcnt(" #n ")" ::: "memory")
; #define PG8_BAR __builtin_amdgcn_s_barrier()
; #define PG8_SCHED __builtin_amdgcn_sched_barrier(0)
; template <class Epi>
; __device__ __forceinline__ void gemm_phase(LAS unsigned char* lds, const Gemm g, const StaticOrder& S, const Epi& E) {
;     ...
;             PG8_LDB(B0, 0, 0); PG8_SCHED; PG8_LDA(At, 0, 0); PG8_STAGE(PG8_SA(1, 1), a1 + hstepA, voffA);
;             PG8_WAIT_L(8); PG8_BAR; PG8_WAIT_L(0); PG8_MMA(0, 0, At, B0); PG8_BAR; PG8_SCHED;
;             PG8_LDB(B1, 0, 1); PG8_STAGE(PG8_SB(0, 0), b2, voffB);
;             PG8_BAR; PG8_WAIT_L(0); PG8_MMA(0, 1, At, B1); PG8_BAR;
;             PG8_LDA(At, 0, 1); PG8_STAGE(PG8_SA(0, 0), a2, voffA);
;             PG8_BAR; PG8_WAIT_L(0); PG8_MMA(1, 0, At, B0); PG8_BAR; PG8_SCHED;
;             PG8_STAGE(PG8_SB(0, 1), b2 + hstepB, voffB);
.LBB0_684:
	ds_read_b128 v[128:131], v191
	ds_read_b128 v[132:135], v191 offset:1024
	ds_read_b128 v[136:139], v191 offset:2048
	ds_read_b128 v[140:143], v191 offset:3072
	s_add_u32 s22, s4, 0xffec0080
	s_addc_u32 s23, s5, -1
	s_cmp_eq_u32 s48, 28
	s_cselect_b32 s25, s19, s23
	s_cselect_b32 s24, s18, s22
	s_cselect_b32 s23, s17, s47
	s_cselect_b32 s22, s45, s46
	v_lshl_add_u64 v[186:187], s[4:5], 0, v[162:163]
	s_add_i32 m0, s11, 0xc000
	ds_read_b128 v[144:147], v192
	ds_read_b128 v[148:151], v192 offset:1024
	ds_read_b128 v[170:173], v192 offset:2048
	ds_read_b128 v[174:177], v192 offset:3072
	ds_read_b128 v[178:181], v192 offset:4096
	ds_read_b128 v[182:185], v192 offset:5120
	ds_read_b128 v[196:199], v192 offset:6144
	ds_read_b128 v[200:203], v192 offset:7168
	global_load_lds_dwordx4 v[186:187], off
	v_lshl_add_u64 v[186:187], s[4:5], 0, v[164:165]
	s_add_i32 m0, s11, 0xe000
	s_nop 0
	global_load_lds_dwordx4 v[186:187], off
	s_waitcnt lgkmcnt(8)
	s_barrier
	s_waitcnt lgkmcnt(0)
	s_setprio 1
	s_waitcnt lgkmcnt(0)
	v_mfma_f32_16x16x32_bf16 v[124:127], v[128:131], v[144:147], v[124:127]
	v_mfma_f32_16x16x32_bf16 v[120:123], v[136:139], v[144:147], v[120:123]
	v_mfma_f32_16x16x32_bf16 v[108:111], v[128:131], v[170:173], v[108:111]
	v_mfma_f32_16x16x32_bf16 v[104:107], v[136:139], v[170:173], v[104:107]
	v_mfma_f32_16x16x32_bf16 v[92:95], v[128:131], v[178:181], v[92:95]
	v_mfma_f32_16x16x32_bf16 v[88:91], v[136:139], v[178:181], v[88:91]
	v_mfma_f32_16x16x32_bf16 v[76:79], v[128:131], v[196:199], v[76:79]
	v_mfma_f32_16x16x32_bf16 v[72:75], v[136:139], v[196:199], v[72:75]
	v_mfma_f32_16x16x32_bf16 v[124:127], v[132:135], v[148:151], v[124:127]
	v_mfma_f32_16x16x32_bf16 v[120:123], v[140:143], v[148:151], v[120:123]
	v_mfma_f32_16x16x32_bf16 v[108:111], v[132:135], v[174:177], v[108:111]
	v_mfma_f32_16x16x32_bf16 v[104:107], v[140:143], v[174:177], v[104:107]
	v_mfma_f32_16x16x32_bf16 v[92:95], v[132:135], v[182:185], v[92:95]
	v_mfma_f32_16x16x32_bf16 v[88:91], v[140:143], v[182:185], v[88:91]
	v_mfma_f32_16x16x32_bf16 v[76:79], v[132:135], v[200:203], v[76:79]
	v_mfma_f32_16x16x32_bf16 v[72:75], v[140:143], v[200:203], v[72:75]
	s_setprio 0
	s_barrier
	s_add_i32 s49, s42, s31
	v_lshl_add_u64 v[186:187], s[22:23], 0, v[156:157]
	s_mov_b32 m0, s49
	ds_read_b128 v[204:207], v193
	ds_read_b128 v[208:211], v193 offset:1024
	ds_read_b128 v[212:215], v193 offset:2048
	ds_read_b128 v[216:219], v193 offset:3072
	global_load_lds_dwordx4 v[186:187], off
	v_lshl_add_u64 v[220:221], s[22:23], 0, v[160:161]
	s_add_i32 m0, s49, 0x2000
	s_nop 0
	global_load_lds_dwordx4 v[220:221], off
	s_barrier
	s_waitcnt lgkmcnt(0)
	s_setprio 1
	s_waitcnt lgkmcnt(0)
	v_mfma_f32_16x16x32_bf16 v[116:119], v[204:207], v[144:147], v[116:119]
	v_mfma_f32_16x16x32_bf16 v[112:115], v[212:215], v[144:147], v[112:115]
	v_mfma_f32_16x16x32_bf16 v[100:103], v[204:207], v[170:173], v[100:103]
	v_mfma_f32_16x16x32_bf16 v[96:99], v[212:215], v[170:173], v[96:99]
	v_mfma_f32_16x16x32_bf16 v[84:87], v[204:207], v[178:181], v[84:87]
	v_mfma_f32_16x16x32_bf16 v[80:83], v[212:215], v[178:181], v[80:83]
	v_mfma_f32_16x16x32_bf16 v[68:71], v[204:207], v[196:199], v[68:71]
	v_mfma_f32_16x16x32_bf16 v[64:67], v[212:215], v[196:199], v[64:67]
	v_mfma_f32_16x16x32_bf16 v[116:119], v[208:211], v[148:151], v[116:119]
	v_mfma_f32_16x16x32_bf16 v[112:115], v[216:219], v[148:151], v[112:115]
	v_mfma_f32_16x16x32_bf16 v[100:103], v[208:211], v[174:177], v[100:103]
	v_mfma_f32_16x16x32_bf16 v[96:99], v[216:219], v[174:177], v[96:99]
	v_mfma_f32_16x16x32_bf16 v[84:87], v[208:211], v[182:185], v[84:87]
	v_mfma_f32_16x16x32_bf16 v[80:83], v[216:219], v[182:185], v[80:83]
	v_mfma_f32_16x16x32_bf16 v[68:71], v[208:211], v[200:203], v[68:71]
	v_mfma_f32_16x16x32_bf16 v[64:67], v[216:219], v[200:203], v[64:67]
	s_setprio 0
	s_mov_b32 m0, s11
	v_lshl_add_u64 v[222:223], s[24:25], 0, v[154:155]
	s_barrier
	ds_read_b128 v[144:147], v192 offset:16384
	ds_read_b128 v[148:151], v192 offset:17408
	ds_read_b128 v[170:173], v192 offset:18432
	ds_read_b128 v[174:177], v192 offset:19456
	ds_read_b128 v[178:181], v192 offset:20480
	ds_read_b128 v[182:185], v192 offset:21504
	ds_read_b128 v[196:199], v192 offset:22528
	ds_read_b128 v[200:203], v192 offset:23552
	global_load_lds_dwordx4 v[222:223], off
	v_lshl_add_u64 v[224:225], s[24:25], 0, v[158:159]
	s_mov_b32 m0, s34
	s_nop 0
	global_load_lds_dwordx4 v[224:225], off
	s_barrier
	s_waitcnt lgkmcnt(0)
	s_setprio 1
	s_waitcnt lgkmcnt(0)
	v_mfma_f32_16x16x32_bf16 v[60:63], v[128:131], v[144:147], v[60:63]
	v_mfma_f32_16x16x32_bf16 v[56:59], v[136:139], v[144:147], v[56:59]
	v_mfma_f32_16x16x32_bf16 v[44:47], v[128:131], v[170:173], v[44:47]
	v_mfma_f32_16x16x32_bf16 v[40:43], v[136:139], v[170:173], v[40:43]
	v_mfma_f32_16x16x32_bf16 v[28:31], v[128:131], v[178:181], v[28:31]
	v_mfma_f32_16x16x32_bf16 v[24:27], v[136:139], v[178:181], v[24:27]
	v_mfma_f32_16x16x32_bf16 v[12:15], v[128:131], v[196:199], v[12:15]
	v_mfma_f32_16x16x32_bf16 v[8:11], v[136:139], v[196:199], v[8:11]
	v_mfma_f32_16x16x32_bf16 v[60:63], v[132:135], v[148:151], v[60:63]
	v_mfma_f32_16x16x32_bf16 v[56:59], v[140:143], v[148:151], v[56:59]
	v_mfma_f32_16x16x32_bf16 v[44:47], v[132:135], v[174:177], v[44:47]
	v_mfma_f32_16x16x32_bf16 v[40:43], v[140:143], v[174:177], v[40:43]
	v_mfma_f32_16x16x32_bf16 v[28:31], v[132:135], v[182:185], v[28:31]
	v_mfma_f32_16x16x32_bf16 v[24:27], v[140:143], v[182:185], v[24:27]
	v_mfma_f32_16x16x32_bf16 v[12:15], v[132:135], v[200:203], v[12:15]
	v_mfma_f32_16x16x32_bf16 v[8:11], v[140:143], v[200:203], v[8:11]
	s_setprio 0
	s_barrier
; #define PG8_STAGE(bufoff, gbase, voff) do { _Pragma("unroll") for (int _i = 0; _i < 2; ++_i) \
;         __builtin_amdgcn_global_load_lds((const unsigned*)((const char*)(gbase) + (voff)[_i]), (LAS unsigned*)(lds + (bufoff) + ldsw + _i * 8192), 16, 0, 0); } while (0)
; #define PG8_LDA(dst, b, h) do { _Pragma("unroll") for (int m = 0; m < 4; ++m) _Pragma("unroll") for (int k = 0; k < 2; ++k) dst[m][k] = *(const LAS bf16x8*)(lds + PG8_SA(b, h) + aoff + m * 2048 + k * 1024); } while (0)
; #define PG8_LDB(dst, b, h) do { _Pragma("unroll") for (int n = 0; n < 2; ++n) _Pragma("unroll") for (int k = 0; k < 2; ++k) dst[n][k] = *(const LAS bf16x8*)(lds + PG8_SB(b, h) + boff + n * 2048 + k * 1024); } while (0)
; #define PG8_MMA(ai, bj, At, Bt) do { __builtin_amdgcn_s_setprio(1); _Pragma("unroll") for (int m = 0; m < 4; ++m) _Pragma("unroll") for (int n = 0; n < 2; ++n) _Pragma("unroll") for (int k = 0; k < 2; ++k) \
;         acc[ai][bj][m][n] = __builtin_amdgcn_mfma_f32_16x16x32_bf16(Bt[n][k], At[m][k], acc[ai][bj][m][n], 0, 0, 0); __builtin_amdgcn_s_setprio(0); } while (0)
; #define PG8_WAIT_V(n) asm volatile("s_waitcnt vmcnt(" #n ")" ::: "memory")
; #define PG8_WAIT_L(n) asm volatile("s_waitcnt lgkmcnt(" #n ")" ::: "memory")
; #define PG8_BAR __builtin_amdgcn_s_barrier()
; #define PG8_SCHED __builtin_amdgcn_sched_barrier(0)
; template <class Epi>
; __device__ __forceinline__ void gemm_phase(LAS unsigned char* lds, const Gemm g, const StaticOrder& S, const Epi& E) {
;     ...
;             PG8_STAGE(PG8_SB(0, 1), b2 + hstepB, voffB);
;             PG8_WAIT_V(6); PG8_BAR; PG8_MMA(1, 1, At, B1); PG8_BAR;
;             PG8_LDB(B0, 1, 0); PG8_SCHED; PG8_LDA(At, 1, 0); PG8_STAGE(PG8_SA(0, 1), a2 + hstepA, voffA);
;             PG8_WAIT_L(8); PG8_BAR; PG8_WAIT_L(0); PG8_MMA(0, 0, At, B0); PG8_BAR; PG8_SCHED;
;             PG8_LDB(B1, 1, 1); PG8_STAGE(PG8_SB(1, 0), b3, voffB);
;             PG8_BAR; PG8_WAIT_L(0); PG8_MMA(0, 1, At, B1); PG8_BAR;
;             PG8_LDA(At, 1, 1); PG8_STAGE(PG8_SA(1, 0), a3, voffA);
;             PG8_BAR; PG8_WAIT_L(0); PG8_MMA(1, 0, At, B0); PG8_BAR; PG8_SCHED;
	s_add_u32 s50, s22, 0x80000
	s_addc_u32 s51, s23, 0
	s_add_i32 s49, s43, s31
	v_lshl_add_u64 v[128:129], s[50:51], 0, v[156:157]
	s_mov_b32 m0, s49
	s_nop 0
	global_load_lds_dwordx4 v[128:129], off
	v_lshl_add_u64 v[128:129], s[50:51], 0, v[160:161]
	s_add_i32 m0, s49, 0x2000
	s_nop 0
	global_load_lds_dwordx4 v[128:129], off
	s_waitcnt vmcnt(6)
	s_barrier
	s_setprio 1
	v_mfma_f32_16x16x32_bf16 v[52:55], v[204:207], v[144:147], v[52:55]
	v_mfma_f32_16x16x32_bf16 v[48:51], v[212:215], v[144:147], v[48:51]
	v_mfma_f32_16x16x32_bf16 v[36:39], v[204:207], v[170:173], v[36:39]
	v_mfma_f32_16x16x32_bf16 v[32:35], v[212:215], v[170:173], v[32:35]
	v_mfma_f32_16x16x32_bf16 v[20:23], v[204:207], v[178:181], v[20:23]
	v_mfma_f32_16x16x32_bf16 v[16:19], v[212:215], v[178:181], v[16:19]
	v_mfma_f32_16x16x32_bf16 v[4:7], v[204:207], v[196:199], v[4:7]
	v_mfma_f32_16x16x32_bf16 v[0:3], v[212:215], v[196:199], v[0:3]
	v_mfma_f32_16x16x32_bf16 v[52:55], v[208:211], v[148:151], v[52:55]
	v_mfma_f32_16x16x32_bf16 v[48:51], v[216:219], v[148:151], v[48:51]
	v_mfma_f32_16x16x32_bf16 v[36:39], v[208:211], v[174:177], v[36:39]
	v_mfma_f32_16x16x32_bf16 v[32:35], v[216:219], v[174:177], v[32:35]
	v_mfma_f32_16x16x32_bf16 v[20:23], v[208:211], v[182:185], v[20:23]
	v_mfma_f32_16x16x32_bf16 v[16:19], v[216:219], v[182:185], v[16:19]
	v_mfma_f32_16x16x32_bf16 v[4:7], v[208:211], v[200:203], v[4:7]
	v_mfma_f32_16x16x32_bf16 v[0:3], v[216:219], v[200:203], v[0:3]
	s_setprio 0
	s_add_i32 s49, 0, 0x18000
	v_add_u32_e32 v140, s49, v189
	s_barrier
	ds_read_b128 v[128:131], v140
	ds_read_b128 v[132:135], v140 offset:1024
	ds_read_b128 v[136:139], v140 offset:2048
	ds_read_b128 v[140:143], v140 offset:3072
	s_add_u32 s24, s24, 0x140000
	s_addc_u32 s25, s25, 0
	s_mov_b32 m0, s35
	v_lshl_add_u64 v[204:205], s[24:25], 0, v[154:155]
	ds_read_b128 v[144:147], v192 offset:32768
	ds_read_b128 v[148:151], v192 offset:33792
	ds_read_b128 v[170:173], v192 offset:34816
	ds_read_b128 v[174:177], v192 offset:35840
	ds_read_b128 v[178:181], v192 offset:36864
	ds_read_b128 v[182:185], v192 offset:37888
	ds_read_b128 v[196:199], v192 offset:38912
	ds_read_b128 v[200:203], v192 offset:39936
	global_load_lds_dwordx4 v[204:205], off
	v_lshl_add_u64 v[204:205], s[24:25], 0, v[158:159]
	s_mov_b32 m0, s36
	s_nop 0
	global_load_lds_dwordx4 v[204:205], off
	s_waitcnt lgkmcnt(8)
	s_barrier
	s_waitcnt lgkmcnt(0)
	s_setprio 1
	s_waitcnt lgkmcnt(0)
	v_mfma_f32_16x16x32_bf16 v[124:127], v[128:131], v[144:147], v[124:127]
	v_mfma_f32_16x16x32_bf16 v[120:123], v[136:139], v[144:147], v[120:123]
	v_mfma_f32_16x16x32_bf16 v[108:111], v[128:131], v[170:173], v[108:111]
	v_mfma_f32_16x16x32_bf16 v[104:107], v[136:139], v[170:173], v[104:107]
	v_mfma_f32_16x16x32_bf16 v[92:95], v[128:131], v[178:181], v[92:95]
	v_mfma_f32_16x16x32_bf16 v[88:91], v[136:139], v[178:181], v[88:91]
	v_mfma_f32_16x16x32_bf16 v[76:79], v[128:131], v[196:199], v[76:79]
	v_mfma_f32_16x16x32_bf16 v[72:75], v[136:139], v[196:199], v[72:75]
	v_mfma_f32_16x16x32_bf16 v[124:127], v[132:135], v[148:151], v[124:127]
	v_mfma_f32_16x16x32_bf16 v[120:123], v[140:143], v[148:151], v[120:123]
	v_mfma_f32_16x16x32_bf16 v[108:111], v[132:135], v[174:177], v[108:111]
	v_mfma_f32_16x16x32_bf16 v[104:107], v[140:143], v[174:177], v[104:107]
	v_mfma_f32_16x16x32_bf16 v[92:95], v[132:135], v[182:185], v[92:95]
	v_mfma_f32_16x16x32_bf16 v[88:91], v[140:143], v[182:185], v[88:91]
	v_mfma_f32_16x16x32_bf16 v[76:79], v[132:135], v[200:203], v[76:79]
	v_mfma_f32_16x16x32_bf16 v[72:75], v[140:143], v[200:203], v[72:75]
	s_setprio 0
	s_barrier
	s_add_i32 s24, 0, 0x1c000
	s_add_i32 s25, s49, s31
	v_add_u32_e32 v195, s24, v189
	v_lshl_add_u64 v[186:187], v[186:187], 0, s[14:15]
	s_mov_b32 m0, s25
	ds_read_b128 v[204:207], v195
	ds_read_b128 v[208:211], v195 offset:1024
	ds_read_b128 v[212:215], v195 offset:2048
	ds_read_b128 v[216:219], v195 offset:3072
	global_load_lds_dwordx4 v[186:187], off
	v_lshl_add_u64 v[186:187], v[220:221], 0, s[14:15]
	s_add_i32 m0, s25, 0x2000
	s_nop 0
	global_load_lds_dwordx4 v[186:187], off
	s_barrier
	s_waitcnt lgkmcnt(0)
	s_setprio 1
	s_waitcnt lgkmcnt(0)
	v_mfma_f32_16x16x32_bf16 v[116:119], v[204:207], v[144:147], v[116:119]
	v_mfma_f32_16x16x32_bf16 v[112:115], v[212:215], v[144:147], v[112:115]
	v_mfma_f32_16x16x32_bf16 v[100:103], v[204:207], v[170:173], v[100:103]
	v_mfma_f32_16x16x32_bf16 v[96:99], v[212:215], v[170:173], v[96:99]
	v_mfma_f32_16x16x32_bf16 v[84:87], v[204:207], v[178:181], v[84:87]
	v_mfma_f32_16x16x32_bf16 v[80:83], v[212:215], v[178:181], v[80:83]
	v_mfma_f32_16x16x32_bf16 v[68:71], v[204:207], v[196:199], v[68:71]
	v_mfma_f32_16x16x32_bf16 v[64:67], v[212:215], v[196:199], v[64:67]
	v_mfma_f32_16x16x32_bf16 v[116:119], v[208:211], v[148:151], v[116:119]
	v_mfma_f32_16x16x32_bf16 v[112:115], v[216:219], v[148:151], v[112:115]
	v_mfma_f32_16x16x32_bf16 v[100:103], v[208:211], v[174:177], v[100:103]
	v_mfma_f32_16x16x32_bf16 v[96:99], v[216:219], v[174:177], v[96:99]
	v_mfma_f32_16x16x32_bf16 v[84:87], v[208:211], v[182:185], v[84:87]
	v_mfma_f32_16x16x32_bf16 v[80:83], v[216:219], v[182:185], v[80:83]
	v_mfma_f32_16x16x32_bf16 v[68:71], v[208:211], v[200:203], v[68:71]
	v_mfma_f32_16x16x32_bf16 v[64:67], v[216:219], v[200:203], v[64:67]
	s_setprio 0
	s_mov_b32 m0, s38
	v_lshl_add_u64 v[186:187], v[222:223], 0, s[14:15]
	s_barrier
	ds_read_b128 v[144:147], v192 offset:49152
	ds_read_b128 v[148:151], v192 offset:50176
	ds_read_b128 v[170:173], v192 offset:51200
	ds_read_b128 v[174:177], v192 offset:52224
	ds_read_b128 v[178:181], v192 offset:53248
	ds_read_b128 v[182:185], v192 offset:54272
	ds_read_b128 v[196:199], v192 offset:55296
	ds_read_b128 v[200:203], v192 offset:56320
	global_load_lds_dwordx4 v[186:187], off
	v_lshl_add_u64 v[186:187], v[224:225], 0, s[14:15]
	s_mov_b32 m0, s39
	s_nop 0
	global_load_lds_dwordx4 v[186:187], off
	s_barrier
; __device__ __forceinline__ void unpack8(const u32x4 v, float* f) { f[0] = bf_lo(v.x); f[1] = bf_hi(v.x); f[2] = bf_lo(v.y); f[3] = bf_hi(v.y); f[4] = bf_lo(v.z); f[5] = bf_hi(v.z); f[6] = bf_lo(v.w); f[7] = bf_hi(v.w); }
; #define PG8_STAGE(bufoff, gbase, voff) do { _Pragma("unroll") for (int _i = 0; _i < 2; ++_i) \
;         __builtin_amdgcn_global_load_lds((const unsigned*)((const char*)(gbase) + (voff)[_i]), (LAS unsigned*)(lds + (bufoff) + ldsw + _i * 8192), 16, 0, 0); } while (0)
; #define PG8_MMA(ai, bj, At, Bt) do { __builtin_amdgcn_s_setprio(1); _Pragma("unroll") for (int m = 0; m < 4; ++m) _Pragma("unroll") for (int n = 0; n < 2; ++n) _Pragma("unroll") for (int k = 0; k < 2; ++k) \
;         acc[ai][bj][m][n] = __builtin_amdgcn_mfma_f32_16x16x32_bf16(Bt[n][k], At[m][k], acc[ai][bj][m][n], 0, 0, 0); __builtin_amdgcn_s_setprio(0); } while (0)
; #define PG8_WAIT_V(n) asm volatile("s_waitcnt vmcnt(" #n ")" ::: "memory")
; #define PG8_WAIT_L(n) asm volatile("s_waitcnt lgkmcnt(" #n ")" ::: "memory")
;     __device__ __forceinline__ void operator()(const f32x4 (&acc)[2][2][4][2], const Unit& u, int wr, int wc, int fr, int fq, const float (&)[8]) const {
;         const int row0 = u.pm * BM + wr * 64 + fr, col0 = u.pn * BM + wc * 32 + 8 * fq;
; #pragma unroll
;         for (int ai = 0; ai < 2; ++ai) {
;             u32x4 bv[4][2];
; #pragma unroll
;             for (int m = 0; m < 4; ++m)
; #pragma unroll
;                 for (int bj = 0; bj < 2; ++bj) bv[m][bj] = *(const u32x4*)(xb + (size_t)(row0 + ai * HALF + m * 16) * DM + col0 + bj * HALF);
; #pragma unroll
;             for (int m = 0; m < 4; ++m) { const int row = row0 + ai * HALF + m * 16; const size_t ro = (size_t)row * DM + col0; float s = 0.f;
; #pragma unroll
;                 for (int bj = 0; bj < 2; ++bj) { float b8[8]; unpack8(bv[m][bj], b8);
;                     const f32x4 v0 = (f32x4){b8[0], b8[1], b8[2], b8[3]} + acc[ai][bj][m][0], v1 = (f32x4){b8[4], b8[5], b8[6], b8[7]} + acc[ai][bj][m][1];
; template <class Epi>
; __device__ __forceinline__ void gemm_phase(LAS unsigned char* lds, const Gemm g, const StaticOrder& S, const Epi& E) {
;     ...
;             PG8_BAR; PG8_WAIT_L(0); PG8_MMA(1, 0, At, B0); PG8_BAR; PG8_SCHED;
;             PG8_STAGE(PG8_SB(1, 1), b3 + hstepB, voffB);
;             PG8_WAIT_V(6); PG8_BAR; PG8_MMA(1, 1, At, B1); PG8_BAR;
	s_waitcnt lgkmcnt(0)
	s_setprio 1
	s_waitcnt lgkmcnt(0)
	v_mfma_f32_16x16x32_bf16 v[60:63], v[128:131], v[144:147], v[60:63]
	v_mfma_f32_16x16x32_bf16 v[56:59], v[136:139], v[144:147], v[56:59]
	v_mfma_f32_16x16x32_bf16 v[44:47], v[128:131], v[170:173], v[44:47]
	v_mfma_f32_16x16x32_bf16 v[40:43], v[136:139], v[170:173], v[40:43]
	v_mfma_f32_16x16x32_bf16 v[28:31], v[128:131], v[178:181], v[28:31]
	v_mfma_f32_16x16x32_bf16 v[24:27], v[136:139], v[178:181], v[24:27]
	v_mfma_f32_16x16x32_bf16 v[12:15], v[128:131], v[196:199], v[12:15]
	v_mfma_f32_16x16x32_bf16 v[8:11], v[136:139], v[196:199], v[8:11]
	v_mfma_f32_16x16x32_bf16 v[60:63], v[132:135], v[148:151], v[60:63]
	v_mfma_f32_16x16x32_bf16 v[56:59], v[140:143], v[148:151], v[56:59]
	v_mfma_f32_16x16x32_bf16 v[44:47], v[132:135], v[174:177], v[44:47]
	v_mfma_f32_16x16x32_bf16 v[40:43], v[140:143], v[174:177], v[40:43]
	v_mfma_f32_16x16x32_bf16 v[28:31], v[132:135], v[182:185], v[28:31]
	v_mfma_f32_16x16x32_bf16 v[24:27], v[140:143], v[182:185], v[24:27]
	v_mfma_f32_16x16x32_bf16 v[12:15], v[132:135], v[200:203], v[12:15]
	v_mfma_f32_16x16x32_bf16 v[8:11], v[140:143], v[200:203], v[8:11]
	s_setprio 0
	s_barrier
	s_add_u32 s22, s22, 0x80080
	s_addc_u32 s23, s23, 0
	s_add_i32 s24, s24, s31
	v_lshl_add_u64 v[128:129], s[22:23], 0, v[156:157]
	s_mov_b32 m0, s24
	s_nop 0
	global_load_lds_dwordx4 v[128:129], off
	v_lshl_add_u64 v[128:129], s[22:23], 0, v[160:161]
	s_add_i32 m0, s24, 0x2000
	s_nop 0
	global_load_lds_dwordx4 v[128:129], off
	s_waitcnt vmcnt(6)
	s_barrier
	s_setprio 1
	v_mfma_f32_16x16x32_bf16 v[52:55], v[204:207], v[144:147], v[52:55]
	v_mfma_f32_16x16x32_bf16 v[48:51], v[212:215], v[144:147], v[48:51]
	v_mfma_f32_16x16x32_bf16 v[36:39], v[204:207], v[170:173], v[36:39]
	v_mfma_f32_16x16x32_bf16 v[32:35], v[212:215], v[170:173], v[32:35]
	v_mfma_f32_16x16x32_bf16 v[20:23], v[204:207], v[178:181], v[20:23]
	v_mfma_f32_16x16x32_bf16 v[16:19], v[212:215], v[178:181], v[16:19]
	v_mfma_f32_16x16x32_bf16 v[4:7], v[204:207], v[196:199], v[4:7]
	v_mfma_f32_16x16x32_bf16 v[0:3], v[212:215], v[196:199], v[0:3]
	v_mfma_f32_16x16x32_bf16 v[52:55], v[208:211], v[148:151], v[52:55]
	v_mfma_f32_16x16x32_bf16 v[48:51], v[216:219], v[148:151], v[48:51]
	v_mfma_f32_16x16x32_bf16 v[36:39], v[208:211], v[174:177], v[36:39]
	v_mfma_f32_16x16x32_bf16 v[32:35], v[216:219], v[174:177], v[32:35]
	v_mfma_f32_16x16x32_bf16 v[20:23], v[208:211], v[182:185], v[20:23]
	v_mfma_f32_16x16x32_bf16 v[16:19], v[216:219], v[182:185], v[16:19]
	v_mfma_f32_16x16x32_bf16 v[4:7], v[208:211], v[200:203], v[4:7]
	v_mfma_f32_16x16x32_bf16 v[0:3], v[216:219], v[200:203], v[0:3]
	s_setprio 0
	s_add_i32 s48, s48, 2
	s_add_u32 s4, s4, 0x100
	s_addc_u32 s5, s5, 0
	s_add_u32 s46, s46, 0x100
	s_addc_u32 s47, s47, 0
	s_cmp_gt_u32 s48, 29
	s_barrier
	s_cbranch_scc0 .LBB0_684
	v_lshl_or_b32 v170, s10, 8, v190
	v_lshl_add_u32 v172, s12, 8, v188
	v_ashrrev_i32_e32 v171, 31, v170
	v_lshlrev_b64 v[206:207], 1, v[170:171]
	v_ashrrev_i32_e32 v173, 31, v172
	v_lshl_add_u64 v[174:175], s[76:77], 0, v[206:207]
	v_lshlrev_b64 v[208:209], 11, v[172:173]
	v_lshl_add_u64 v[128:129], v[174:175], 0, v[208:209]
	global_load_dwordx4 v[198:201], v[128:129], off
	global_load_dwordx4 v[202:205], v[128:129], off offset:256
	v_or_b32_e32 v184, 16, v172
	v_or_b32_e32 v180, 32, v172
	v_or_b32_e32 v176, 48, v172
	v_ashrrev_i32_e32 v185, 31, v184
	v_ashrrev_i32_e32 v181, 31, v180
	v_ashrrev_i32_e32 v177, 31, v176
	v_lshlrev_b64 v[186:187], 11, v[184:185]
	v_lshlrev_b64 v[182:183], 11, v[180:181]
	v_lshlrev_b64 v[178:179], 11, v[176:177]
	v_lshl_add_u64 v[128:129], v[174:175], 0, v[186:187]
	v_lshl_add_u64 v[130:131], v[174:175], 0, v[182:183]
	v_lshl_add_u64 v[196:197], v[174:175], 0, v[178:179]
	global_load_dwordx4 v[148:151], v[128:129], off
	global_load_dwordx4 v[144:147], v[128:129], off offset:256
	global_load_dwordx4 v[140:143], v[130:131], off
	global_load_dwordx4 v[136:139], v[130:131], off offset:256
	global_load_dwordx4 v[132:135], v[196:197], off
	s_nop 0
	global_load_dwordx4 v[128:131], v[196:197], off offset:256
	v_add_u32_e32 v218, 0x80, v172
	v_ashrrev_i32_e32 v219, 31, v218
	v_lshlrev_b64 v[218:219], 11, v[218:219]
	v_lshl_add_u64 v[218:219], v[174:175], 0, v[218:219]
	global_load_dwordx4 v[220:223], v[218:219], off
	global_load_dwordx4 v[224:227], v[218:219], off offset:256
	v_add_u32_e32 v218, 0x90, v172
	v_ashrrev_i32_e32 v219, 31, v218
	v_lshlrev_b64 v[218:219], 11, v[218:219]
	v_lshl_add_u64 v[218:219], v[174:175], 0, v[218:219]
	global_load_dwordx4 v[228:231], v[218:219], off
	global_load_dwordx4 v[232:235], v[218:219], off offset:256
	v_add_u32_e32 v218, 0xa0, v172
	v_ashrrev_i32_e32 v219, 31, v218
	v_lshlrev_b64 v[218:219], 11, v[218:219]
	v_lshl_add_u64 v[218:219], v[174:175], 0, v[218:219]
	global_load_dwordx4 v[236:239], v[218:219], off
	global_load_dwordx4 v[240:243], v[218:219], off offset:256
	v_add_u32_e32 v218, 0xb0, v172
	v_ashrrev_i32_e32 v219, 31, v218
	v_lshlrev_b64 v[218:219], 11, v[218:219]
	v_lshl_add_u64 v[218:219], v[174:175], 0, v[218:219]
	global_load_dwordx4 v[244:247], v[218:219], off
	global_load_dwordx4 v[252:255], v[218:219], off offset:256
	v_and_b32_e32 v196, 64, v194
	v_xor_b32_e32 v195, 16, v194
	v_add_u32_e32 v196, 64, v196
	v_xor_b32_e32 v197, 32, v194
	v_cmp_lt_i32_e32 vcc, v195, v196
	s_waitcnt vmcnt(15)
	v_lshlrev_b32_e32 v210, 16, v198
	v_cndmask_b32_e32 v195, v194, v195, vcc
	v_cmp_lt_i32_e32 vcc, v197, v196
	v_and_b32_e32 v211, 0xffff0000, v198
	s_waitcnt vmcnt(14)
; __device__ __forceinline__ unsigned pk2(float lo, float hi) { const f32x2 v = (f32x2){lo, hi}; const bf16x2_t b = __builtin_convertvector(v, bf16x2_t); return __builtin_bit_cast(unsigned, b); }
; __device__ __forceinline__ void unpack8(const u32x4 v, float* f) { f[0] = bf_lo(v.x); f[1] = bf_hi(v.x); f[2] = bf_lo(v.y); f[3] = bf_hi(v.y); f[4] = bf_lo(v.z); f[5] = bf_hi(v.z); f[6] = bf_lo(v.w); f[7] = bf_hi(v.w); }
;     __device__ __forceinline__ void operator()(const f32x4 (&acc)[2][2][4][2], const Unit& u, int wr, int wc, int fr, int fq, const float (&)[8]) const {
;     ...
;             for (int m = 0; m < 4; ++m) { const int row = row0 + ai * HALF + m * 16; const size_t ro = (size_t)row * DM + col0; float s = 0.f;
; #pragma unroll
;                 for (int bj = 0; bj < 2; ++bj) { float b8[8]; unpack8(bv[m][bj], b8);
;                     const f32x4 v0 = (f32x4){b8[0], b8[1], b8[2], b8[3]} + acc[ai][bj][m][0], v1 = (f32x4){b8[4], b8[5], b8[6], b8[7]} + acc[ai][bj][m][1];
;                     s += v0[0] * v0[0] + v0[1] * v0[1] + v0[2] * v0[2] + v0[3] * v0[3] + v1[0] * v1[0] + v1[1] * v1[1] + v1[2] * v1[2] + v1[3] * v1[3];
;                     if (LAST) { *(f32x4*)(out + ro + bj * HALF) = v0; *(f32x4*)(out + ro + bj * HALF + 4) = v1; }
;                     else { u32x4 w; w.x = pk2(v0[0], v0[1]); w.y = pk2(v0[2], v0[3]); w.z = pk2(v1[0], v1[1]); w.w = pk2(v1[2], v1[3]); *(u32x4*)(xb + ro + bj * HALF) = w; } }
;                 s += __shfl_xor(s, 16); s += __shfl_xor(s, 32);
;                 if (fq == 0) ss[(size_t)row * 16 + u.pn * 4 + wc] = s; }
	v_lshlrev_b32_e32 v214, 16, v202
	v_and_b32_e32 v215, 0xffff0000, v202
	v_cndmask_b32_e32 v197, v194, v197, vcc
	v_lshlrev_b32_e32 v212, 16, v200
	v_and_b32_e32 v213, 0xffff0000, v200
	v_lshlrev_b32_e32 v200, 16, v201
	v_and_b32_e32 v201, 0xffff0000, v201
	v_lshlrev_b32_e32 v216, 16, v204
	v_and_b32_e32 v217, 0xffff0000, v204
	v_pk_add_f32 v[124:125], v[124:125], v[210:211]
	v_pk_add_f32 v[116:117], v[116:117], v[214:215]
	v_lshlrev_b32_e32 v196, 2, v195
	v_lshlrev_b32_e32 v195, 2, v197
	v_lshlrev_b32_e32 v198, 16, v199
	v_and_b32_e32 v199, 0xffff0000, v199
	v_lshlrev_b32_e32 v202, 16, v203
	v_and_b32_e32 v203, 0xffff0000, v203
	v_pk_add_f32 v[122:123], v[122:123], v[200:201]
	v_pk_add_f32 v[200:201], v[112:113], v[216:217]
	v_mul_f32_e32 v197, v125, v125
	v_cvt_pk_bf16_f32 v112, v124, v125
	v_mul_f32_e32 v125, v117, v117
	v_pk_add_f32 v[126:127], v[126:127], v[198:199]
	v_pk_add_f32 v[118:119], v[118:119], v[202:203]
	v_fmac_f32_e32 v197, v124, v124
	v_fmac_f32_e32 v125, v116, v116
	v_fmac_f32_e32 v197, v126, v126
	v_fmac_f32_e32 v125, v118, v118
	v_pk_add_f32 v[120:121], v[120:121], v[212:213]
	v_fmac_f32_e32 v197, v127, v127
	v_fmac_f32_e32 v125, v119, v119
	v_lshlrev_b32_e32 v204, 16, v205
	v_and_b32_e32 v205, 0xffff0000, v205
	v_fmac_f32_e32 v197, v120, v120
	v_fmac_f32_e32 v125, v200, v200
	v_pk_add_f32 v[198:199], v[114:115], v[204:205]
	v_fmac_f32_e32 v197, v121, v121
	v_fmac_f32_e32 v125, v201, v201
	v_fmac_f32_e32 v197, v122, v122
	v_fmac_f32_e32 v125, v198, v198
	v_fmac_f32_e32 v197, v123, v123
	v_fmac_f32_e32 v125, v199, v199
	v_cvt_pk_bf16_f32 v115, v122, v123
	v_add_f32_e32 v122, v197, v125
	ds_bpermute_b32 v123, v196, v122
	v_cvt_pk_bf16_f32 v114, v120, v121
	v_lshl_add_u64 v[120:121], s[76:77], 0, v[208:209]
	v_cvt_pk_bf16_f32 v113, v126, v127
	v_lshl_add_u64 v[120:121], v[120:121], 0, v[206:207]
	global_store_dwordx4 v[120:121], v[112:115], off
	s_waitcnt lgkmcnt(0)
	s_nop 0
	v_add_f32_e32 v112, v122, v123
	ds_bpermute_b32 v113, v195, v112
	v_cvt_pk_bf16_f32 v114, v116, v117
	v_cvt_pk_bf16_f32 v115, v118, v119
	v_cvt_pk_bf16_f32 v116, v200, v201
	v_cvt_pk_bf16_f32 v117, v198, v199
	global_store_dwordx4 v[120:121], v[114:117], off offset:256
	s_and_saveexec_b64 s[4:5], s[0:1]
	s_cbranch_execz .LBB0_687
	s_waitcnt lgkmcnt(0)
	v_add_f32_e32 v114, v112, v113
	s_lshl_b32 s22, s10, 2
	v_lshlrev_b64 v[112:113], 6, v[172:173]
	s_ashr_i32 s23, s22, 31
	v_lshl_add_u64 v[112:113], s[6:7], 0, v[112:113]
	v_lshl_add_u64 v[112:113], s[22:23], 2, v[112:113]
	s_lshl_b32 s12, s37, 2
	v_lshl_add_u64 v[112:113], v[112:113], 0, s[12:13]
	global_store_dword v[112:113], v114, off
.LBB0_687:
	s_or_b64 exec, exec, s[4:5]
	s_waitcnt vmcnt(15)
	v_lshlrev_b32_e32 v112, 16, v148
	s_waitcnt lgkmcnt(0)
	v_and_b32_e32 v113, 0xffff0000, v148
	v_lshlrev_b32_e32 v116, 16, v150
	v_and_b32_e32 v117, 0xffff0000, v150
	v_lshlrev_b32_e32 v118, 16, v151
	v_and_b32_e32 v119, 0xffff0000, v151
	v_pk_add_f32 v[108:109], v[108:109], v[112:113]
	v_lshlrev_b32_e32 v114, 16, v149
	v_and_b32_e32 v115, 0xffff0000, v149
	v_pk_add_f32 v[112:113], v[106:107], v[118:119]
	v_pk_add_f32 v[106:107], v[104:105], v[116:117]
	v_mul_f32_e32 v116, v109, v109
	v_pk_add_f32 v[110:111], v[110:111], v[114:115]
	v_fmac_f32_e32 v116, v108, v108
	v_fmac_f32_e32 v116, v110, v110
	v_fmac_f32_e32 v116, v111, v111
	v_fmac_f32_e32 v116, v106, v106
	v_fmac_f32_e32 v116, v107, v107
	v_fmac_f32_e32 v116, v112, v112
	v_cvt_pk_bf16_f32 v104, v108, v109
	s_waitcnt vmcnt(14)
	v_lshlrev_b32_e32 v108, 16, v144
	v_and_b32_e32 v109, 0xffff0000, v144
	v_fmac_f32_e32 v116, v113, v113
	v_cvt_pk_bf16_f32 v105, v110, v111
	v_cvt_pk_bf16_f32 v106, v106, v107
	v_cvt_pk_bf16_f32 v107, v112, v113
	v_lshlrev_b32_e32 v110, 16, v145
	v_and_b32_e32 v111, 0xffff0000, v145
	v_lshlrev_b32_e32 v112, 16, v146
	v_and_b32_e32 v113, 0xffff0000, v146
	v_pk_add_f32 v[100:101], v[100:101], v[108:109]
	v_pk_add_f32 v[102:103], v[102:103], v[110:111]
	v_pk_add_f32 v[110:111], v[96:97], v[112:113]
	v_mul_f32_e32 v96, v101, v101
	v_fmac_f32_e32 v96, v100, v100
	v_fmac_f32_e32 v96, v102, v102
	v_fmac_f32_e32 v96, v103, v103
	v_lshlrev_b32_e32 v114, 16, v147
	v_and_b32_e32 v115, 0xffff0000, v147
	v_fmac_f32_e32 v96, v110, v110
	v_pk_add_f32 v[108:109], v[98:99], v[114:115]
	v_fmac_f32_e32 v96, v111, v111
	v_fmac_f32_e32 v96, v108, v108
	v_fmac_f32_e32 v96, v109, v109
	v_add_f32_e32 v99, v116, v96
	ds_bpermute_b32 v114, v196, v99
	v_lshl_add_u64 v[96:97], s[76:77], 0, v[186:187]
	v_lshl_add_u64 v[112:113], v[170:171], 1, v[96:97]
	v_cvt_pk_bf16_f32 v98, v100, v101
	v_cvt_pk_bf16_f32 v100, v110, v111
	s_waitcnt lgkmcnt(0)
	v_add_f32_e32 v96, v99, v114
	ds_bpermute_b32 v97, v195, v96
	v_cvt_pk_bf16_f32 v99, v102, v103
	v_cvt_pk_bf16_f32 v101, v108, v109
	global_store_dwordx4 v[112:113], v[104:107], off
	global_store_dwordx4 v[112:113], v[98:101], off offset:256
	s_and_saveexec_b64 s[4:5], s[0:1]
	s_cbranch_execz .LBB0_689
	s_waitcnt lgkmcnt(0)
	v_add_f32_e32 v98, v96, v97
	s_lshl_b32 s22, s10, 2
	v_lshlrev_b64 v[96:97], 6, v[184:185]
	s_ashr_i32 s23, s22, 31
	v_lshl_add_u64 v[96:97], s[6:7], 0, v[96:97]
	v_lshl_add_u64 v[96:97], s[22:23], 2, v[96:97]
	s_lshl_b32 s12, s37, 2
	v_lshl_add_u64 v[96:97], v[96:97], 0, s[12:13]
	global_store_dword v[96:97], v98, off
; __device__ __forceinline__ unsigned pk2(float lo, float hi) { const f32x2 v = (f32x2){lo, hi}; const bf16x2_t b = __builtin_convertvector(v, bf16x2_t); return __builtin_bit_cast(unsigned, b); }
; __device__ __forceinline__ void unpack8(const u32x4 v, float* f) { f[0] = bf_lo(v.x); f[1] = bf_hi(v.x); f[2] = bf_lo(v.y); f[3] = bf_hi(v.y); f[4] = bf_lo(v.z); f[5] = bf_hi(v.z); f[6] = bf_lo(v.w); f[7] = bf_hi(v.w); }
;     __device__ __forceinline__ void operator()(const f32x4 (&acc)[2][2][4][2], const Unit& u, int wr, int wc, int fr, int fq, const float (&)[8]) const {
;     ...
;             for (int m = 0; m < 4; ++m) { const int row = row0 + ai * HALF + m * 16; const size_t ro = (size_t)row * DM + col0; float s = 0.f;
; #pragma unroll
;                 for (int bj = 0; bj < 2; ++bj) { float b8[8]; unpack8(bv[m][bj], b8);
;                     const f32x4 v0 = (f32x4){b8[0], b8[1], b8[2], b8[3]} + acc[ai][bj][m][0], v1 = (f32x4){b8[4], b8[5], b8[6], b8[7]} + acc[ai][bj][m][1];
;                     s += v0[0] * v0[0] + v0[1] * v0[1] + v0[2] * v0[2] + v0[3] * v0[3] + v1[0] * v1[0] + v1[1] * v1[1] + v1[2] * v1[2] + v1[3] * v1[3];
;                     if (LAST) { *(f32x4*)(out + ro + bj * HALF) = v0; *(f32x4*)(out + ro + bj * HALF + 4) = v1; }
;                     else { u32x4 w; w.x = pk2(v0[0], v0[1]); w.y = pk2(v0[2], v0[3]); w.z = pk2(v1[0], v1[1]); w.w = pk2(v1[2], v1[3]); *(u32x4*)(xb + ro + bj * HALF) = w; } }
;                 s += __shfl_xor(s, 16); s += __shfl_xor(s, 32);
;                 if (fq == 0) ss[(size_t)row * 16 + u.pn * 4 + wc] = s; }
.LBB0_689:
	s_or_b64 exec, exec, s[4:5]
	s_waitcnt vmcnt(15)
	v_lshlrev_b32_e32 v96, 16, v140
	s_waitcnt lgkmcnt(0)
	v_and_b32_e32 v97, 0xffff0000, v140
	v_lshlrev_b32_e32 v100, 16, v142
	v_and_b32_e32 v101, 0xffff0000, v142
	v_lshlrev_b32_e32 v102, 16, v143
	v_and_b32_e32 v103, 0xffff0000, v143
	v_pk_add_f32 v[92:93], v[92:93], v[96:97]
	v_lshlrev_b32_e32 v98, 16, v141
	v_and_b32_e32 v99, 0xffff0000, v141
	v_pk_add_f32 v[96:97], v[90:91], v[102:103]
	v_pk_add_f32 v[90:91], v[88:89], v[100:101]
	v_mul_f32_e32 v100, v93, v93
	v_pk_add_f32 v[94:95], v[94:95], v[98:99]
	v_fmac_f32_e32 v100, v92, v92
	v_fmac_f32_e32 v100, v94, v94
	v_fmac_f32_e32 v100, v95, v95
	v_fmac_f32_e32 v100, v90, v90
	v_fmac_f32_e32 v100, v91, v91
	v_fmac_f32_e32 v100, v96, v96
	v_cvt_pk_bf16_f32 v88, v92, v93
	s_waitcnt vmcnt(14)
	v_lshlrev_b32_e32 v92, 16, v136
	v_and_b32_e32 v93, 0xffff0000, v136
	v_fmac_f32_e32 v100, v97, v97
	v_cvt_pk_bf16_f32 v89, v94, v95
	v_cvt_pk_bf16_f32 v90, v90, v91
	v_cvt_pk_bf16_f32 v91, v96, v97
	v_lshlrev_b32_e32 v94, 16, v137
	v_and_b32_e32 v95, 0xffff0000, v137
	v_lshlrev_b32_e32 v96, 16, v138
	v_and_b32_e32 v97, 0xffff0000, v138
	v_pk_add_f32 v[84:85], v[84:85], v[92:93]
	v_pk_add_f32 v[86:87], v[86:87], v[94:95]
	v_pk_add_f32 v[94:95], v[80:81], v[96:97]
	v_mul_f32_e32 v80, v85, v85
	v_fmac_f32_e32 v80, v84, v84
	v_fmac_f32_e32 v80, v86, v86
	v_fmac_f32_e32 v80, v87, v87
	v_lshlrev_b32_e32 v98, 16, v139
	v_and_b32_e32 v99, 0xffff0000, v139
	v_fmac_f32_e32 v80, v94, v94
	v_pk_add_f32 v[92:93], v[82:83], v[98:99]
	v_fmac_f32_e32 v80, v95, v95
	v_fmac_f32_e32 v80, v92, v92
	v_fmac_f32_e32 v80, v93, v93
	v_add_f32_e32 v83, v100, v80
	ds_bpermute_b32 v98, v196, v83
	v_lshl_add_u64 v[80:81], s[76:77], 0, v[182:183]
	v_lshl_add_u64 v[96:97], v[170:171], 1, v[80:81]
	v_cvt_pk_bf16_f32 v82, v84, v85
	v_cvt_pk_bf16_f32 v84, v94, v95
	s_waitcnt lgkmcnt(0)
	v_add_f32_e32 v80, v83, v98
	ds_bpermute_b32 v81, v195, v80
	v_cvt_pk_bf16_f32 v83, v86, v87
	v_cvt_pk_bf16_f32 v85, v92, v93
	global_store_dwordx4 v[96:97], v[88:91], off
	global_store_dwordx4 v[96:97], v[82:85], off offset:256
	s_and_saveexec_b64 s[4:5], s[0:1]
	s_cbranch_execz .LBB0_691
	s_waitcnt lgkmcnt(0)
	v_add_f32_e32 v82, v80, v81
	s_lshl_b32 s22, s10, 2
	v_lshlrev_b64 v[80:81], 6, v[180:181]
	s_ashr_i32 s23, s22, 31
	v_lshl_add_u64 v[80:81], s[6:7], 0, v[80:81]
	v_lshl_add_u64 v[80:81], s[22:23], 2, v[80:81]
	s_lshl_b32 s12, s37, 2
	v_lshl_add_u64 v[80:81], v[80:81], 0, s[12:13]
	global_store_dword v[80:81], v82, off
.LBB0_691:
	s_or_b64 exec, exec, s[4:5]
	s_waitcnt vmcnt(15)
	v_lshlrev_b32_e32 v80, 16, v132
	s_waitcnt lgkmcnt(0)
	v_and_b32_e32 v81, 0xffff0000, v132
	v_lshlrev_b32_e32 v84, 16, v134
	v_and_b32_e32 v85, 0xffff0000, v134
	v_lshlrev_b32_e32 v86, 16, v135
	v_and_b32_e32 v87, 0xffff0000, v135
	v_pk_add_f32 v[76:77], v[76:77], v[80:81]
	v_lshlrev_b32_e32 v82, 16, v133
	v_and_b32_e32 v83, 0xffff0000, v133
	v_pk_add_f32 v[80:81], v[74:75], v[86:87]
	v_pk_add_f32 v[74:75], v[72:73], v[84:85]
	v_mul_f32_e32 v84, v77, v77
	v_pk_add_f32 v[78:79], v[78:79], v[82:83]
	v_fmac_f32_e32 v84, v76, v76
	v_fmac_f32_e32 v84, v78, v78
	v_fmac_f32_e32 v84, v79, v79
	v_fmac_f32_e32 v84, v74, v74
	v_fmac_f32_e32 v84, v75, v75
	v_fmac_f32_e32 v84, v80, v80
	v_cvt_pk_bf16_f32 v72, v76, v77
	s_waitcnt vmcnt(14)
	v_lshlrev_b32_e32 v76, 16, v128
	v_and_b32_e32 v77, 0xffff0000, v128
	v_fmac_f32_e32 v84, v81, v81
	v_cvt_pk_bf16_f32 v73, v78, v79
	v_cvt_pk_bf16_f32 v74, v74, v75
	v_cvt_pk_bf16_f32 v75, v80, v81
	v_lshlrev_b32_e32 v78, 16, v129
	v_and_b32_e32 v79, 0xffff0000, v129
	v_lshlrev_b32_e32 v80, 16, v130
	v_and_b32_e32 v81, 0xffff0000, v130
	v_pk_add_f32 v[68:69], v[68:69], v[76:77]
	v_pk_add_f32 v[70:71], v[70:71], v[78:79]
	v_pk_add_f32 v[78:79], v[64:65], v[80:81]
	v_mul_f32_e32 v64, v69, v69
	v_fmac_f32_e32 v64, v68, v68
	v_fmac_f32_e32 v64, v70, v70
	v_fmac_f32_e32 v64, v71, v71
	v_lshlrev_b32_e32 v82, 16, v131
	v_and_b32_e32 v83, 0xffff0000, v131
	v_fmac_f32_e32 v64, v78, v78
	v_pk_add_f32 v[76:77], v[66:67], v[82:83]
	v_fmac_f32_e32 v64, v79, v79
	v_fmac_f32_e32 v64, v76, v76
	v_fmac_f32_e32 v64, v77, v77
	v_add_f32_e32 v67, v84, v64
	ds_bpermute_b32 v82, v196, v67
	v_lshl_add_u64 v[64:65], s[76:77], 0, v[178:179]
	v_lshl_add_u64 v[80:81], v[170:171], 1, v[64:65]
	v_cvt_pk_bf16_f32 v66, v68, v69
	v_cvt_pk_bf16_f32 v68, v78, v79
	s_waitcnt lgkmcnt(0)
	v_add_f32_e32 v64, v67, v82
	ds_bpermute_b32 v65, v195, v64
	v_cvt_pk_bf16_f32 v67, v70, v71
	v_cvt_pk_bf16_f32 v69, v76, v77
	global_store_dwordx4 v[80:81], v[72:75], off
	global_store_dwordx4 v[80:81], v[66:69], off offset:256
	s_and_saveexec_b64 s[4:5], s[0:1]
	s_cbranch_execz .LBB0_693
	s_waitcnt lgkmcnt(0)
	v_add_f32_e32 v66, v64, v65
	s_lshl_b32 s22, s10, 2
	v_lshlrev_b64 v[64:65], 6, v[176:177]
	s_ashr_i32 s23, s22, 31
	v_lshl_add_u64 v[64:65], s[6:7], 0, v[64:65]
	v_lshl_add_u64 v[64:65], s[22:23], 2, v[64:65]
	s_lshl_b32 s12, s37, 2
	v_lshl_add_u64 v[64:65], v[64:65], 0, s[12:13]
	global_store_dword v[64:65], v66, off
; __device__ __forceinline__ unsigned pk2(float lo, float hi) { const f32x2 v = (f32x2){lo, hi}; const bf16x2_t b = __builtin_convertvector(v, bf16x2_t); return __builtin_bit_cast(unsigned, b); }
; __device__ __forceinline__ void unpack8(const u32x4 v, float* f) { f[0] = bf_lo(v.x); f[1] = bf_hi(v.x); f[2] = bf_lo(v.y); f[3] = bf_hi(v.y); f[4] = bf_lo(v.z); f[5] = bf_hi(v.z); f[6] = bf_lo(v.w); f[7] = bf_hi(v.w); }
;     __device__ __forceinline__ void operator()(const f32x4 (&acc)[2][2][4][2], const Unit& u, int wr, int wc, int fr, int fq, const float (&)[8]) const {
;     ...
;         for (int ai = 0; ai < 2; ++ai) {
;             u32x4 bv[4][2];
; #pragma unroll
;             for (int m = 0; m < 4; ++m)
; #pragma unroll
;                 for (int bj = 0; bj < 2; ++bj) bv[m][bj] = *(const u32x4*)(xb + (size_t)(row0 + ai * HALF + m * 16) * DM + col0 + bj * HALF);
; #pragma unroll
;             for (int m = 0; m < 4; ++m) { const int row = row0 + ai * HALF + m * 16; const size_t ro = (size_t)row * DM + col0; float s = 0.f;
; #pragma unroll
;                 for (int bj = 0; bj < 2; ++bj) { float b8[8]; unpack8(bv[m][bj], b8);
;                     const f32x4 v0 = (f32x4){b8[0], b8[1], b8[2], b8[3]} + acc[ai][bj][m][0], v1 = (f32x4){b8[4], b8[5], b8[6], b8[7]} + acc[ai][bj][m][1];
;                     s += v0[0] * v0[0] + v0[1] * v0[1] + v0[2] * v0[2] + v0[3] * v0[3] + v1[0] * v1[0] + v1[1] * v1[1] + v1[2] * v1[2] + v1[3] * v1[3];
;                     if (LAST) { *(f32x4*)(out + ro + bj * HALF) = v0; *(f32x4*)(out + ro + bj * HALF + 4) = v1; }
;                     else { u32x4 w; w.x = pk2(v0[0], v0[1]); w.y = pk2(v0[2], v0[3]); w.z = pk2(v1[0], v1[1]); w.w = pk2(v1[2], v1[3]); *(u32x4*)(xb + ro + bj * HALF) = w; } }
;                 s += __shfl_xor(s, 16); s += __shfl_xor(s, 32);
;                 if (fq == 0) ss[(size_t)row * 16 + u.pn * 4 + wc] = s; }
.LBB0_693:
	s_or_b64 exec, exec, s[4:5]
	v_add_u32_e32 v100, 0x80, v172
	v_ashrrev_i32_e32 v101, 31, v100
	v_lshlrev_b64 v[110:111], 11, v[100:101]
	s_waitcnt lgkmcnt(0)
	v_lshl_add_u64 v[64:65], v[174:175], 0, v[110:111]
	s_waitcnt vmcnt(15)
	v_mov_b32_e32 v102, v220
	v_mov_b32_e32 v103, v221
	v_mov_b32_e32 v104, v222
	v_mov_b32_e32 v105, v223
	s_waitcnt vmcnt(14)
	v_mov_b32_e32 v106, v224
	v_mov_b32_e32 v107, v225
	v_mov_b32_e32 v108, v226
	v_mov_b32_e32 v109, v227
	v_add_u32_e32 v96, 0x90, v172
	v_add_u32_e32 v92, 0xa0, v172
	v_add_u32_e32 v88, 0xb0, v172
	v_ashrrev_i32_e32 v97, 31, v96
	v_ashrrev_i32_e32 v93, 31, v92
	v_ashrrev_i32_e32 v89, 31, v88
	v_lshlrev_b64 v[98:99], 11, v[96:97]
	v_lshlrev_b64 v[94:95], 11, v[92:93]
	v_lshlrev_b64 v[90:91], 11, v[88:89]
	v_lshl_add_u64 v[64:65], v[174:175], 0, v[98:99]
	v_lshl_add_u64 v[66:67], v[174:175], 0, v[94:95]
	v_lshl_add_u64 v[112:113], v[174:175], 0, v[90:91]
	s_waitcnt vmcnt(13)
	v_mov_b32_e32 v84, v228
	v_mov_b32_e32 v85, v229
	v_mov_b32_e32 v86, v230
	v_mov_b32_e32 v87, v231
	s_waitcnt vmcnt(12)
	v_mov_b32_e32 v80, v232
	v_mov_b32_e32 v81, v233
	v_mov_b32_e32 v82, v234
	v_mov_b32_e32 v83, v235
	s_waitcnt vmcnt(11)
	v_mov_b32_e32 v76, v236
	v_mov_b32_e32 v77, v237
	v_mov_b32_e32 v78, v238
	v_mov_b32_e32 v79, v239
	s_waitcnt vmcnt(10)
	v_mov_b32_e32 v72, v240
	v_mov_b32_e32 v73, v241
	v_mov_b32_e32 v74, v242
	v_mov_b32_e32 v75, v243
	s_waitcnt vmcnt(9)
	v_mov_b32_e32 v68, v244
	v_mov_b32_e32 v69, v245
	v_mov_b32_e32 v70, v246
	v_mov_b32_e32 v71, v247
	s_nop 0
	s_waitcnt vmcnt(8)
	v_mov_b32_e32 v64, v252
	v_mov_b32_e32 v65, v253
	v_mov_b32_e32 v66, v254
	v_mov_b32_e32 v67, v255
	s_nop 0
	v_lshlrev_b32_e32 v112, 16, v102
	v_and_b32_e32 v113, 0xffff0000, v102
	s_nop 0
	v_lshlrev_b32_e32 v116, 16, v106
	v_and_b32_e32 v117, 0xffff0000, v106
	v_lshlrev_b32_e32 v114, 16, v104
	v_and_b32_e32 v115, 0xffff0000, v104
	v_lshlrev_b32_e32 v104, 16, v105
	v_and_b32_e32 v105, 0xffff0000, v105
	v_lshlrev_b32_e32 v106, 16, v107
	v_and_b32_e32 v107, 0xffff0000, v107
	v_lshlrev_b32_e32 v118, 16, v108
	v_and_b32_e32 v119, 0xffff0000, v108
	v_pk_add_f32 v[60:61], v[60:61], v[112:113]
	v_pk_add_f32 v[52:53], v[52:53], v[116:117]
	v_lshlrev_b32_e32 v102, 16, v103
	v_and_b32_e32 v103, 0xffff0000, v103
	v_pk_add_f32 v[58:59], v[58:59], v[104:105]
	v_pk_add_f32 v[54:55], v[54:55], v[106:107]
	v_pk_add_f32 v[104:105], v[48:49], v[118:119]
	v_mul_f32_e32 v106, v61, v61
	v_cvt_pk_bf16_f32 v48, v60, v61
	v_mul_f32_e32 v61, v53, v53
	v_pk_add_f32 v[62:63], v[62:63], v[102:103]
	v_fmac_f32_e32 v106, v60, v60
	v_fmac_f32_e32 v61, v52, v52
	v_fmac_f32_e32 v106, v62, v62
	v_fmac_f32_e32 v61, v54, v54
	v_pk_add_f32 v[56:57], v[56:57], v[114:115]
	v_fmac_f32_e32 v106, v63, v63
	v_fmac_f32_e32 v61, v55, v55
	v_lshlrev_b32_e32 v108, 16, v109
	v_and_b32_e32 v109, 0xffff0000, v109
	v_fmac_f32_e32 v106, v56, v56
	v_fmac_f32_e32 v61, v104, v104
	v_pk_add_f32 v[102:103], v[50:51], v[108:109]
	v_fmac_f32_e32 v106, v57, v57
	v_fmac_f32_e32 v61, v105, v105
	v_fmac_f32_e32 v106, v58, v58
	v_fmac_f32_e32 v61, v102, v102
	v_fmac_f32_e32 v106, v59, v59
	v_fmac_f32_e32 v61, v103, v103
	v_cvt_pk_bf16_f32 v51, v58, v59
	v_add_f32_e32 v58, v106, v61
	ds_bpermute_b32 v59, v196, v58
	v_cvt_pk_bf16_f32 v50, v56, v57
	v_lshl_add_u64 v[56:57], s[76:77], 0, v[110:111]
	v_cvt_pk_bf16_f32 v49, v62, v63
	v_lshl_add_u64 v[56:57], v[170:171], 1, v[56:57]
	global_store_dwordx4 v[56:57], v[48:51], off
	s_waitcnt lgkmcnt(0)
	s_nop 0
	v_add_f32_e32 v48, v58, v59
	ds_bpermute_b32 v49, v195, v48
	v_cvt_pk_bf16_f32 v50, v52, v53
	v_cvt_pk_bf16_f32 v51, v54, v55
	v_cvt_pk_bf16_f32 v52, v104, v105
	v_cvt_pk_bf16_f32 v53, v102, v103
	global_store_dwordx4 v[56:57], v[50:53], off offset:256
	s_and_saveexec_b64 s[4:5], s[0:1]
	s_cbranch_execz .LBB0_695
	s_waitcnt lgkmcnt(0)
	v_add_f32_e32 v50, v48, v49
	s_lshl_b32 s22, s10, 2
	v_lshlrev_b64 v[48:49], 6, v[100:101]
	s_ashr_i32 s23, s22, 31
	v_lshl_add_u64 v[48:49], s[6:7], 0, v[48:49]
	v_lshl_add_u64 v[48:49], s[22:23], 2, v[48:49]
	s_lshl_b32 s12, s37, 2
	v_lshl_add_u64 v[48:49], v[48:49], 0, s[12:13]
	global_store_dword v[48:49], v50, off

; #define PG8_STAGE(bufoff, gbase, voff) do { _Pragma("unroll") for (int _i = 0; _i < 2; ++_i) \
;         __builtin_amdgcn_global_load_lds((const unsigned*)((const char*)(gbase) + (voff)[_i]), (LAS unsigned*)(lds + (bufoff) + ldsw + _i * 8192), 16, 0, 0); } while (0)
; #define PG8_LDA(dst, b, h) do { _Pragma("unroll") for (int m = 0; m < 4; ++m) _Pragma("unroll") for (int k = 0; k < 2; ++k) dst[m][k] = *(const LAS bf16x8*)(lds + PG8_SA(b, h) + aoff + m * 2048 + k * 1024); } while (0)
; #define PG8_LDB(dst, b, h) do { _Pragma("unroll") for (int n = 0; n < 2; ++n) _Pragma("unroll") for (int k = 0; k < 2; ++k) dst[n][k] = *(const LAS bf16x8*)(lds + PG8_SB(b, h) + boff + n * 2048 + k * 1024); } while (0)
; #define PG8_MMA(ai, bj, At, Bt) do { __builtin_amdgcn_s_setprio(1); _Pragma("unroll") for (int m = 0; m < 4; ++m) _Pragma("unroll") for (int n = 0; n < 2; ++n) _Pragma("unroll") for (int k = 0; k < 2; ++k) \
;         acc[ai][bj][m][n] = __builtin_amdgcn_mfma_f32_16x16x32_bf16(Bt[n][k], At[m][k], acc[ai][bj][m][n], 0, 0, 0); __builtin_amdgcn_s_setprio(0); } while (0)
; #define PG8_WAIT_L(n) asm volatile("s_waitcnt lgkmcnt(" #n ")" ::: "memory")
; #define PG8_BAR __builtin_amdgcn_s_barrier()
; #define PG8_SCHED __builtin_amdgcn_sched_barrier(0)
; template <class Epi>
; __device__ __forceinline__ void gemm_phase(LAS unsigned char* lds, const Gemm g, const StaticOrder& S, const Epi& E) {
;     ...
;             PG8_LDB(B0, 0, 0); PG8_SCHED; PG8_LDA(At, 0, 0); PG8_STAGE(PG8_SA(1, 1), a1 + hstepA, voffA);
;             PG8_WAIT_L(8); PG8_BAR; PG8_WAIT_L(0); PG8_MMA(0, 0, At, B0); PG8_BAR; PG8_SCHED;
;             PG8_LDB(B1, 0, 1); PG8_STAGE(PG8_SB(0, 0), b2, voffB);
;             PG8_BAR; PG8_WAIT_L(0); PG8_MMA(0, 1, At, B1); PG8_BAR;
;             PG8_LDA(At, 0, 1); PG8_STAGE(PG8_SA(0, 0), a2, voffA);
;             PG8_BAR; PG8_WAIT_L(0); PG8_MMA(1, 0, At, B0); PG8_BAR; PG8_SCHED;
;             PG8_STAGE(PG8_SB(0, 1), b2 + hstepB, voffB);
.LBB0_844:
	ds_read_b128 v[128:131], v191
	ds_read_b128 v[132:135], v191 offset:1024
	ds_read_b128 v[136:139], v191 offset:2048
	ds_read_b128 v[140:143], v191 offset:3072
	s_add_u32 s24, s22, 0xfff00080
	s_addc_u32 s25, s23, -1
	s_cmp_eq_u32 s48, 60
	s_cselect_b32 s27, s17, s25
	s_cselect_b32 s26, s44, s24
	s_cselect_b32 s25, s15, s47
	s_cselect_b32 s24, s45, s46
	v_lshl_add_u64 v[186:187], s[22:23], 0, v[162:163]
	s_add_i32 m0, s7, 0xc000
	ds_read_b128 v[144:147], v192
	ds_read_b128 v[148:151], v192 offset:1024
	ds_read_b128 v[170:173], v192 offset:2048
	ds_read_b128 v[174:177], v192 offset:3072
	ds_read_b128 v[178:181], v192 offset:4096
	ds_read_b128 v[182:185], v192 offset:5120
	ds_read_b128 v[196:199], v192 offset:6144
	ds_read_b128 v[200:203], v192 offset:7168
	global_load_lds_dwordx4 v[186:187], off
	v_lshl_add_u64 v[186:187], s[22:23], 0, v[164:165]
	s_add_i32 m0, s7, 0xe000
	s_nop 0
	global_load_lds_dwordx4 v[186:187], off
	s_waitcnt lgkmcnt(8)
	s_barrier
	s_waitcnt lgkmcnt(0)
	s_setprio 1
	s_waitcnt lgkmcnt(0)
	v_mfma_f32_16x16x32_bf16 v[124:127], v[128:131], v[144:147], v[124:127]
	v_mfma_f32_16x16x32_bf16 v[120:123], v[136:139], v[144:147], v[120:123]
	v_mfma_f32_16x16x32_bf16 v[108:111], v[128:131], v[170:173], v[108:111]
	v_mfma_f32_16x16x32_bf16 v[104:107], v[136:139], v[170:173], v[104:107]
	v_mfma_f32_16x16x32_bf16 v[92:95], v[128:131], v[178:181], v[92:95]
	v_mfma_f32_16x16x32_bf16 v[88:91], v[136:139], v[178:181], v[88:91]
	v_mfma_f32_16x16x32_bf16 v[76:79], v[128:131], v[196:199], v[76:79]
	v_mfma_f32_16x16x32_bf16 v[72:75], v[136:139], v[196:199], v[72:75]
	v_mfma_f32_16x16x32_bf16 v[124:127], v[132:135], v[148:151], v[124:127]
	v_mfma_f32_16x16x32_bf16 v[120:123], v[140:143], v[148:151], v[120:123]
	v_mfma_f32_16x16x32_bf16 v[108:111], v[132:135], v[174:177], v[108:111]
	v_mfma_f32_16x16x32_bf16 v[104:107], v[140:143], v[174:177], v[104:107]
	v_mfma_f32_16x16x32_bf16 v[92:95], v[132:135], v[182:185], v[92:95]
	v_mfma_f32_16x16x32_bf16 v[88:91], v[140:143], v[182:185], v[88:91]
	v_mfma_f32_16x16x32_bf16 v[76:79], v[132:135], v[200:203], v[76:79]
	v_mfma_f32_16x16x32_bf16 v[72:75], v[140:143], v[200:203], v[72:75]
	s_setprio 0
	s_barrier
	s_add_i32 s49, s42, s31
	v_lshl_add_u64 v[186:187], s[24:25], 0, v[156:157]
	s_mov_b32 m0, s49
	ds_read_b128 v[204:207], v193
	ds_read_b128 v[208:211], v193 offset:1024
	ds_read_b128 v[212:215], v193 offset:2048
	ds_read_b128 v[216:219], v193 offset:3072
	global_load_lds_dwordx4 v[186:187], off
	v_lshl_add_u64 v[220:221], s[24:25], 0, v[160:161]
	s_add_i32 m0, s49, 0x2000
	s_nop 0
	global_load_lds_dwordx4 v[220:221], off
	s_barrier
	s_waitcnt lgkmcnt(0)
	s_setprio 1
	s_waitcnt lgkmcnt(0)
	v_mfma_f32_16x16x32_bf16 v[116:119], v[204:207], v[144:147], v[116:119]
	v_mfma_f32_16x16x32_bf16 v[112:115], v[212:215], v[144:147], v[112:115]
	v_mfma_f32_16x16x32_bf16 v[100:103], v[204:207], v[170:173], v[100:103]
	v_mfma_f32_16x16x32_bf16 v[96:99], v[212:215], v[170:173], v[96:99]
	v_mfma_f32_16x16x32_bf16 v[84:87], v[204:207], v[178:181], v[84:87]
	v_mfma_f32_16x16x32_bf16 v[80:83], v[212:215], v[178:181], v[80:83]
	v_mfma_f32_16x16x32_bf16 v[68:71], v[204:207], v[196:199], v[68:71]
	v_mfma_f32_16x16x32_bf16 v[64:67], v[212:215], v[196:199], v[64:67]
	v_mfma_f32_16x16x32_bf16 v[116:119], v[208:211], v[148:151], v[116:119]
	v_mfma_f32_16x16x32_bf16 v[112:115], v[216:219], v[148:151], v[112:115]
	v_mfma_f32_16x16x32_bf16 v[100:103], v[208:211], v[174:177], v[100:103]
	v_mfma_f32_16x16x32_bf16 v[96:99], v[216:219], v[174:177], v[96:99]
	v_mfma_f32_16x16x32_bf16 v[84:87], v[208:211], v[182:185], v[84:87]
	v_mfma_f32_16x16x32_bf16 v[80:83], v[216:219], v[182:185], v[80:83]
	v_mfma_f32_16x16x32_bf16 v[68:71], v[208:211], v[200:203], v[68:71]
	v_mfma_f32_16x16x32_bf16 v[64:67], v[216:219], v[200:203], v[64:67]
	s_setprio 0
	s_mov_b32 m0, s7
	v_lshl_add_u64 v[222:223], s[26:27], 0, v[154:155]
	s_barrier
	ds_read_b128 v[144:147], v192 offset:16384
	ds_read_b128 v[148:151], v192 offset:17408
	ds_read_b128 v[170:173], v192 offset:18432
	ds_read_b128 v[174:177], v192 offset:19456
	ds_read_b128 v[178:181], v192 offset:20480
	ds_read_b128 v[182:185], v192 offset:21504
	ds_read_b128 v[196:199], v192 offset:22528
	ds_read_b128 v[200:203], v192 offset:23552
	global_load_lds_dwordx4 v[222:223], off
	v_lshl_add_u64 v[224:225], s[26:27], 0, v[158:159]
	s_mov_b32 m0, s34
	s_nop 0
	global_load_lds_dwordx4 v[224:225], off
	s_barrier
	s_waitcnt lgkmcnt(0)
	s_setprio 1
	s_waitcnt lgkmcnt(0)
	v_mfma_f32_16x16x32_bf16 v[60:63], v[128:131], v[144:147], v[60:63]
	v_mfma_f32_16x16x32_bf16 v[56:59], v[136:139], v[144:147], v[56:59]
	v_mfma_f32_16x16x32_bf16 v[44:47], v[128:131], v[170:173], v[44:47]
	v_mfma_f32_16x16x32_bf16 v[40:43], v[136:139], v[170:173], v[40:43]
	v_mfma_f32_16x16x32_bf16 v[28:31], v[128:131], v[178:181], v[28:31]
	v_mfma_f32_16x16x32_bf16 v[24:27], v[136:139], v[178:181], v[24:27]
	v_mfma_f32_16x16x32_bf16 v[12:15], v[128:131], v[196:199], v[12:15]
	v_mfma_f32_16x16x32_bf16 v[8:11], v[136:139], v[196:199], v[8:11]
	v_mfma_f32_16x16x32_bf16 v[60:63], v[132:135], v[148:151], v[60:63]
	v_mfma_f32_16x16x32_bf16 v[56:59], v[140:143], v[148:151], v[56:59]
	v_mfma_f32_16x16x32_bf16 v[44:47], v[132:135], v[174:177], v[44:47]
	v_mfma_f32_16x16x32_bf16 v[40:43], v[140:143], v[174:177], v[40:43]
	v_mfma_f32_16x16x32_bf16 v[28:31], v[132:135], v[182:185], v[28:31]
	v_mfma_f32_16x16x32_bf16 v[24:27], v[140:143], v[182:185], v[24:27]
	v_mfma_f32_16x16x32_bf16 v[12:15], v[132:135], v[200:203], v[12:15]
	v_mfma_f32_16x16x32_bf16 v[8:11], v[140:143], v[200:203], v[8:11]
	s_setprio 0
	s_barrier
; #define PG8_STAGE(bufoff, gbase, voff) do { _Pragma("unroll") for (int _i = 0; _i < 2; ++_i) \
;         __builtin_amdgcn_global_load_lds((const unsigned*)((const char*)(gbase) + (voff)[_i]), (LAS unsigned*)(lds + (bufoff) + ldsw + _i * 8192), 16, 0, 0); } while (0)
; #define PG8_LDA(dst, b, h) do { _Pragma("unroll") for (int m = 0; m < 4; ++m) _Pragma("unroll") for (int k = 0; k < 2; ++k) dst[m][k] = *(const LAS bf16x8*)(lds + PG8_SA(b, h) + aoff + m * 2048 + k * 1024); } while (0)
; #define PG8_LDB(dst, b, h) do { _Pragma("unroll") for (int n = 0; n < 2; ++n) _Pragma("unroll") for (int k = 0; k < 2; ++k) dst[n][k] = *(const LAS bf16x8*)(lds + PG8_SB(b, h) + boff + n * 2048 + k * 1024); } while (0)
; #define PG8_MMA(ai, bj, At, Bt) do { __builtin_amdgcn_s_setprio(1); _Pragma("unroll") for (int m = 0; m < 4; ++m) _Pragma("unroll") for (int n = 0; n < 2; ++n) _Pragma("unroll") for (int k = 0; k < 2; ++k) \
;         acc[ai][bj][m][n] = __builtin_amdgcn_mfma_f32_16x16x32_bf16(Bt[n][k], At[m][k], acc[ai][bj][m][n], 0, 0, 0); __builtin_amdgcn_s_setprio(0); } while (0)
; #define PG8_WAIT_V(n) asm volatile("s_waitcnt vmcnt(" #n ")" ::: "memory")
; #define PG8_WAIT_L(n) asm volatile("s_waitcnt lgkmcnt(" #n ")" ::: "memory")
; #define PG8_BAR __builtin_amdgcn_s_barrier()
; #define PG8_SCHED __builtin_amdgcn_sched_barrier(0)
; template <class Epi>
; __device__ __forceinline__ void gemm_phase(LAS unsigned char* lds, const Gemm g, const StaticOrder& S, const Epi& E) {
;     ...
;             PG8_STAGE(PG8_SB(0, 1), b2 + hstepB, voffB);
;             PG8_WAIT_V(6); PG8_BAR; PG8_MMA(1, 1, At, B1); PG8_BAR;
;             PG8_LDB(B0, 1, 0); PG8_SCHED; PG8_LDA(At, 1, 0); PG8_STAGE(PG8_SA(0, 1), a2 + hstepA, voffA);
;             PG8_WAIT_L(8); PG8_BAR; PG8_WAIT_L(0); PG8_MMA(0, 0, At, B0); PG8_BAR; PG8_SCHED;
;             PG8_LDB(B1, 1, 1); PG8_STAGE(PG8_SB(1, 0), b3, voffB);
;             PG8_BAR; PG8_WAIT_L(0); PG8_MMA(0, 1, At, B1); PG8_BAR;
;             PG8_LDA(At, 1, 1); PG8_STAGE(PG8_SA(1, 0), a3, voffA);
;             PG8_BAR; PG8_WAIT_L(0); PG8_MMA(1, 0, At, B0); PG8_BAR; PG8_SCHED;
	s_add_u32 s50, s24, 0x100000
	s_addc_u32 s51, s25, 0
	s_add_i32 s49, s43, s31
	v_lshl_add_u64 v[128:129], s[50:51], 0, v[156:157]
	s_mov_b32 m0, s49
	s_nop 0
	global_load_lds_dwordx4 v[128:129], off
	v_lshl_add_u64 v[128:129], s[50:51], 0, v[160:161]
	s_add_i32 m0, s49, 0x2000
	s_nop 0
	global_load_lds_dwordx4 v[128:129], off
	s_waitcnt vmcnt(6)
	s_barrier
	s_setprio 1
	v_mfma_f32_16x16x32_bf16 v[52:55], v[204:207], v[144:147], v[52:55]
	v_mfma_f32_16x16x32_bf16 v[48:51], v[212:215], v[144:147], v[48:51]
	v_mfma_f32_16x16x32_bf16 v[36:39], v[204:207], v[170:173], v[36:39]
	v_mfma_f32_16x16x32_bf16 v[32:35], v[212:215], v[170:173], v[32:35]
	v_mfma_f32_16x16x32_bf16 v[20:23], v[204:207], v[178:181], v[20:23]
	v_mfma_f32_16x16x32_bf16 v[16:19], v[212:215], v[178:181], v[16:19]
	v_mfma_f32_16x16x32_bf16 v[4:7], v[204:207], v[196:199], v[4:7]
	v_mfma_f32_16x16x32_bf16 v[0:3], v[212:215], v[196:199], v[0:3]
	v_mfma_f32_16x16x32_bf16 v[52:55], v[208:211], v[148:151], v[52:55]
	v_mfma_f32_16x16x32_bf16 v[48:51], v[216:219], v[148:151], v[48:51]
	v_mfma_f32_16x16x32_bf16 v[36:39], v[208:211], v[174:177], v[36:39]
	v_mfma_f32_16x16x32_bf16 v[32:35], v[216:219], v[174:177], v[32:35]
	v_mfma_f32_16x16x32_bf16 v[20:23], v[208:211], v[182:185], v[20:23]
	v_mfma_f32_16x16x32_bf16 v[16:19], v[216:219], v[182:185], v[16:19]
	v_mfma_f32_16x16x32_bf16 v[4:7], v[208:211], v[200:203], v[4:7]
	v_mfma_f32_16x16x32_bf16 v[0:3], v[216:219], v[200:203], v[0:3]
	s_setprio 0
	s_add_i32 s49, 0, 0x18000
	v_add_u32_e32 v140, s49, v189
	s_barrier
	ds_read_b128 v[128:131], v140
	ds_read_b128 v[132:135], v140 offset:1024
	ds_read_b128 v[136:139], v140 offset:2048
	ds_read_b128 v[140:143], v140 offset:3072
	s_add_u32 s26, s26, 0x100000
	s_addc_u32 s27, s27, 0
	s_mov_b32 m0, s35
	v_lshl_add_u64 v[204:205], s[26:27], 0, v[154:155]
	ds_read_b128 v[144:147], v192 offset:32768
	ds_read_b128 v[148:151], v192 offset:33792
	ds_read_b128 v[170:173], v192 offset:34816
	ds_read_b128 v[174:177], v192 offset:35840
	ds_read_b128 v[178:181], v192 offset:36864
	ds_read_b128 v[182:185], v192 offset:37888
	ds_read_b128 v[196:199], v192 offset:38912
	ds_read_b128 v[200:203], v192 offset:39936
	global_load_lds_dwordx4 v[204:205], off
	v_lshl_add_u64 v[204:205], s[26:27], 0, v[158:159]
	s_mov_b32 m0, s36
	s_nop 0
	global_load_lds_dwordx4 v[204:205], off
	s_waitcnt lgkmcnt(8)
	s_barrier
	s_waitcnt lgkmcnt(0)
	s_setprio 1
	s_waitcnt lgkmcnt(0)
	v_mfma_f32_16x16x32_bf16 v[124:127], v[128:131], v[144:147], v[124:127]
	v_mfma_f32_16x16x32_bf16 v[120:123], v[136:139], v[144:147], v[120:123]
	v_mfma_f32_16x16x32_bf16 v[108:111], v[128:131], v[170:173], v[108:111]
	v_mfma_f32_16x16x32_bf16 v[104:107], v[136:139], v[170:173], v[104:107]
	v_mfma_f32_16x16x32_bf16 v[92:95], v[128:131], v[178:181], v[92:95]
	v_mfma_f32_16x16x32_bf16 v[88:91], v[136:139], v[178:181], v[88:91]
	v_mfma_f32_16x16x32_bf16 v[76:79], v[128:131], v[196:199], v[76:79]
	v_mfma_f32_16x16x32_bf16 v[72:75], v[136:139], v[196:199], v[72:75]
	v_mfma_f32_16x16x32_bf16 v[124:127], v[132:135], v[148:151], v[124:127]
	v_mfma_f32_16x16x32_bf16 v[120:123], v[140:143], v[148:151], v[120:123]
	v_mfma_f32_16x16x32_bf16 v[108:111], v[132:135], v[174:177], v[108:111]
	v_mfma_f32_16x16x32_bf16 v[104:107], v[140:143], v[174:177], v[104:107]
	v_mfma_f32_16x16x32_bf16 v[92:95], v[132:135], v[182:185], v[92:95]
	v_mfma_f32_16x16x32_bf16 v[88:91], v[140:143], v[182:185], v[88:91]
	v_mfma_f32_16x16x32_bf16 v[76:79], v[132:135], v[200:203], v[76:79]
	v_mfma_f32_16x16x32_bf16 v[72:75], v[140:143], v[200:203], v[72:75]
	s_setprio 0
	s_barrier
	s_add_i32 s26, 0, 0x1c000
	s_add_i32 s27, s49, s31
	v_add_u32_e32 v195, s26, v189
	v_lshl_add_u64 v[186:187], v[186:187], 0, s[12:13]
	s_mov_b32 m0, s27
	ds_read_b128 v[204:207], v195
	ds_read_b128 v[208:211], v195 offset:1024
	ds_read_b128 v[212:215], v195 offset:2048
	ds_read_b128 v[216:219], v195 offset:3072
	global_load_lds_dwordx4 v[186:187], off
	v_lshl_add_u64 v[186:187], v[220:221], 0, s[12:13]
	s_add_i32 m0, s27, 0x2000
	s_nop 0
	global_load_lds_dwordx4 v[186:187], off
	s_barrier
	s_waitcnt lgkmcnt(0)
	s_setprio 1
	s_waitcnt lgkmcnt(0)
	v_mfma_f32_16x16x32_bf16 v[116:119], v[204:207], v[144:147], v[116:119]
	v_mfma_f32_16x16x32_bf16 v[112:115], v[212:215], v[144:147], v[112:115]
	v_mfma_f32_16x16x32_bf16 v[100:103], v[204:207], v[170:173], v[100:103]
	v_mfma_f32_16x16x32_bf16 v[96:99], v[212:215], v[170:173], v[96:99]
	v_mfma_f32_16x16x32_bf16 v[84:87], v[204:207], v[178:181], v[84:87]
	v_mfma_f32_16x16x32_bf16 v[80:83], v[212:215], v[178:181], v[80:83]
	v_mfma_f32_16x16x32_bf16 v[68:71], v[204:207], v[196:199], v[68:71]
	v_mfma_f32_16x16x32_bf16 v[64:67], v[212:215], v[196:199], v[64:67]
	v_mfma_f32_16x16x32_bf16 v[116:119], v[208:211], v[148:151], v[116:119]
	v_mfma_f32_16x16x32_bf16 v[112:115], v[216:219], v[148:151], v[112:115]
	v_mfma_f32_16x16x32_bf16 v[100:103], v[208:211], v[174:177], v[100:103]
	v_mfma_f32_16x16x32_bf16 v[96:99], v[216:219], v[174:177], v[96:99]
	v_mfma_f32_16x16x32_bf16 v[84:87], v[208:211], v[182:185], v[84:87]
	v_mfma_f32_16x16x32_bf16 v[80:83], v[216:219], v[182:185], v[80:83]
	v_mfma_f32_16x16x32_bf16 v[68:71], v[208:211], v[200:203], v[68:71]
	v_mfma_f32_16x16x32_bf16 v[64:67], v[216:219], v[200:203], v[64:67]
	s_setprio 0
	s_mov_b32 m0, s38
	v_lshl_add_u64 v[186:187], v[222:223], 0, s[12:13]
	s_barrier
	ds_read_b128 v[144:147], v192 offset:49152
	ds_read_b128 v[148:151], v192 offset:50176
	ds_read_b128 v[170:173], v192 offset:51200
	ds_read_b128 v[174:177], v192 offset:52224
	ds_read_b128 v[178:181], v192 offset:53248
	ds_read_b128 v[182:185], v192 offset:54272
	ds_read_b128 v[196:199], v192 offset:55296
	ds_read_b128 v[200:203], v192 offset:56320
	global_load_lds_dwordx4 v[186:187], off
	v_lshl_add_u64 v[186:187], v[224:225], 0, s[12:13]
	s_mov_b32 m0, s39
	s_nop 0
	global_load_lds_dwordx4 v[186:187], off
	s_barrier
; __device__ __forceinline__ void unpack8(const u32x4 v, float* f) { f[0] = bf_lo(v.x); f[1] = bf_hi(v.x); f[2] = bf_lo(v.y); f[3] = bf_hi(v.y); f[4] = bf_lo(v.z); f[5] = bf_hi(v.z); f[6] = bf_lo(v.w); f[7] = bf_hi(v.w); }
; #define PG8_STAGE(bufoff, gbase, voff) do { _Pragma("unroll") for (int _i = 0; _i < 2; ++_i) \
;         __builtin_amdgcn_global_load_lds((const unsigned*)((const char*)(gbase) + (voff)[_i]), (LAS unsigned*)(lds + (bufoff) + ldsw + _i * 8192), 16, 0, 0); } while (0)
; #define PG8_MMA(ai, bj, At, Bt) do { __builtin_amdgcn_s_setprio(1); _Pragma("unroll") for (int m = 0; m < 4; ++m) _Pragma("unroll") for (int n = 0; n < 2; ++n) _Pragma("unroll") for (int k = 0; k < 2; ++k) \
;         acc[ai][bj][m][n] = __builtin_amdgcn_mfma_f32_16x16x32_bf16(Bt[n][k], At[m][k], acc[ai][bj][m][n], 0, 0, 0); __builtin_amdgcn_s_setprio(0); } while (0)
; #define PG8_WAIT_V(n) asm volatile("s_waitcnt vmcnt(" #n ")" ::: "memory")
; #define PG8_WAIT_L(n) asm volatile("s_waitcnt lgkmcnt(" #n ")" ::: "memory")
;     __device__ __forceinline__ void operator()(const f32x4 (&acc)[2][2][4][2], const Unit& u, int wr, int wc, int fr, int fq, const float (&)[8]) const {
;         const int row0 = u.pm * BM + wr * 64 + fr, col0 = u.pn * BM + wc * 32 + 8 * fq;
; #pragma unroll
;         for (int ai = 0; ai < 2; ++ai) {
;             u32x4 bv[4][2];
; #pragma unroll
;             for (int m = 0; m < 4; ++m)
; #pragma unroll
;                 for (int bj = 0; bj < 2; ++bj) bv[m][bj] = *(const u32x4*)(xb + (size_t)(row0 + ai * HALF + m * 16) * DM + col0 + bj * HALF);
; #pragma unroll
;             for (int m = 0; m < 4; ++m) { const int row = row0 + ai * HALF + m * 16; const size_t ro = (size_t)row * DM + col0; float s = 0.f;
; #pragma unroll
;                 for (int bj = 0; bj < 2; ++bj) { float b8[8]; unpack8(bv[m][bj], b8);
;                     const f32x4 v0 = (f32x4){b8[0], b8[1], b8[2], b8[3]} + acc[ai][bj][m][0], v1 = (f32x4){b8[4], b8[5], b8[6], b8[7]} + acc[ai][bj][m][1];
; template <class Epi>
; __device__ __forceinline__ void gemm_phase(LAS unsigned char* lds, const Gemm g, const StaticOrder& S, const Epi& E) {
;     ...
;             PG8_BAR; PG8_WAIT_L(0); PG8_MMA(1, 0, At, B0); PG8_BAR; PG8_SCHED;
;             PG8_STAGE(PG8_SB(1, 1), b3 + hstepB, voffB);
;             PG8_WAIT_V(6); PG8_BAR; PG8_MMA(1, 1, At, B1); PG8_BAR;
	s_waitcnt lgkmcnt(0)
	s_setprio 1
	s_waitcnt lgkmcnt(0)
	v_mfma_f32_16x16x32_bf16 v[60:63], v[128:131], v[144:147], v[60:63]
	v_mfma_f32_16x16x32_bf16 v[56:59], v[136:139], v[144:147], v[56:59]
	v_mfma_f32_16x16x32_bf16 v[44:47], v[128:131], v[170:173], v[44:47]
	v_mfma_f32_16x16x32_bf16 v[40:43], v[136:139], v[170:173], v[40:43]
	v_mfma_f32_16x16x32_bf16 v[28:31], v[128:131], v[178:181], v[28:31]
	v_mfma_f32_16x16x32_bf16 v[24:27], v[136:139], v[178:181], v[24:27]
	v_mfma_f32_16x16x32_bf16 v[12:15], v[128:131], v[196:199], v[12:15]
	v_mfma_f32_16x16x32_bf16 v[8:11], v[136:139], v[196:199], v[8:11]
	v_mfma_f32_16x16x32_bf16 v[60:63], v[132:135], v[148:151], v[60:63]
	v_mfma_f32_16x16x32_bf16 v[56:59], v[140:143], v[148:151], v[56:59]
	v_mfma_f32_16x16x32_bf16 v[44:47], v[132:135], v[174:177], v[44:47]
	v_mfma_f32_16x16x32_bf16 v[40:43], v[140:143], v[174:177], v[40:43]
	v_mfma_f32_16x16x32_bf16 v[28:31], v[132:135], v[182:185], v[28:31]
	v_mfma_f32_16x16x32_bf16 v[24:27], v[140:143], v[182:185], v[24:27]
	v_mfma_f32_16x16x32_bf16 v[12:15], v[132:135], v[200:203], v[12:15]
	v_mfma_f32_16x16x32_bf16 v[8:11], v[140:143], v[200:203], v[8:11]
	s_setprio 0
	s_barrier
	s_add_u32 s24, s24, 0x100080
	s_addc_u32 s25, s25, 0
	s_add_i32 s26, s26, s31
	v_lshl_add_u64 v[128:129], s[24:25], 0, v[156:157]
	s_mov_b32 m0, s26
	s_nop 0
	global_load_lds_dwordx4 v[128:129], off
	v_lshl_add_u64 v[128:129], s[24:25], 0, v[160:161]
	s_add_i32 m0, s26, 0x2000
	s_nop 0
	global_load_lds_dwordx4 v[128:129], off
	s_waitcnt vmcnt(6)
	s_barrier
	s_setprio 1
	v_mfma_f32_16x16x32_bf16 v[52:55], v[204:207], v[144:147], v[52:55]
	v_mfma_f32_16x16x32_bf16 v[48:51], v[212:215], v[144:147], v[48:51]
	v_mfma_f32_16x16x32_bf16 v[36:39], v[204:207], v[170:173], v[36:39]
	v_mfma_f32_16x16x32_bf16 v[32:35], v[212:215], v[170:173], v[32:35]
	v_mfma_f32_16x16x32_bf16 v[20:23], v[204:207], v[178:181], v[20:23]
	v_mfma_f32_16x16x32_bf16 v[16:19], v[212:215], v[178:181], v[16:19]
	v_mfma_f32_16x16x32_bf16 v[4:7], v[204:207], v[196:199], v[4:7]
	v_mfma_f32_16x16x32_bf16 v[0:3], v[212:215], v[196:199], v[0:3]
	v_mfma_f32_16x16x32_bf16 v[52:55], v[208:211], v[148:151], v[52:55]
	v_mfma_f32_16x16x32_bf16 v[48:51], v[216:219], v[148:151], v[48:51]
	v_mfma_f32_16x16x32_bf16 v[36:39], v[208:211], v[174:177], v[36:39]
	v_mfma_f32_16x16x32_bf16 v[32:35], v[216:219], v[174:177], v[32:35]
	v_mfma_f32_16x16x32_bf16 v[20:23], v[208:211], v[182:185], v[20:23]
	v_mfma_f32_16x16x32_bf16 v[16:19], v[216:219], v[182:185], v[16:19]
	v_mfma_f32_16x16x32_bf16 v[4:7], v[208:211], v[200:203], v[4:7]
	v_mfma_f32_16x16x32_bf16 v[0:3], v[216:219], v[200:203], v[0:3]
	s_setprio 0
	s_add_i32 s48, s48, 2
	s_add_u32 s22, s22, 0x100
	s_addc_u32 s23, s23, 0
	s_add_u32 s46, s46, 0x100
	s_addc_u32 s47, s47, 0
	s_cmp_gt_u32 s48, 61
	s_barrier
	s_cbranch_scc0 .LBB0_844
	v_lshl_or_b32 v170, s6, 8, v190
	v_lshl_add_u32 v172, s8, 8, v188
	v_ashrrev_i32_e32 v171, 31, v170
	v_lshlrev_b64 v[206:207], 1, v[170:171]
	v_ashrrev_i32_e32 v173, 31, v172
	v_lshl_add_u64 v[174:175], s[76:77], 0, v[206:207]
	v_lshlrev_b64 v[208:209], 11, v[172:173]
	v_lshl_add_u64 v[128:129], v[174:175], 0, v[208:209]
	global_load_dwordx4 v[198:201], v[128:129], off
	global_load_dwordx4 v[202:205], v[128:129], off offset:256
	v_or_b32_e32 v184, 16, v172
	v_or_b32_e32 v180, 32, v172
	v_or_b32_e32 v176, 48, v172
	v_ashrrev_i32_e32 v185, 31, v184
	v_ashrrev_i32_e32 v181, 31, v180
	v_ashrrev_i32_e32 v177, 31, v176
	v_lshlrev_b64 v[186:187], 11, v[184:185]
	v_lshlrev_b64 v[182:183], 11, v[180:181]
	v_lshlrev_b64 v[178:179], 11, v[176:177]
	v_lshl_add_u64 v[128:129], v[174:175], 0, v[186:187]
	v_lshl_add_u64 v[130:131], v[174:175], 0, v[182:183]
	v_lshl_add_u64 v[196:197], v[174:175], 0, v[178:179]
	global_load_dwordx4 v[148:151], v[128:129], off
	global_load_dwordx4 v[144:147], v[128:129], off offset:256
	global_load_dwordx4 v[140:143], v[130:131], off
	global_load_dwordx4 v[136:139], v[130:131], off offset:256
	global_load_dwordx4 v[132:135], v[196:197], off
	s_nop 0
	global_load_dwordx4 v[128:131], v[196:197], off offset:256
	v_add_u32_e32 v218, 0x80, v172
	v_ashrrev_i32_e32 v219, 31, v218
	v_lshlrev_b64 v[218:219], 11, v[218:219]
	v_lshl_add_u64 v[218:219], v[174:175], 0, v[218:219]
	global_load_dwordx4 v[220:223], v[218:219], off
	global_load_dwordx4 v[224:227], v[218:219], off offset:256
	v_add_u32_e32 v218, 0x90, v172
	v_ashrrev_i32_e32 v219, 31, v218
	v_lshlrev_b64 v[218:219], 11, v[218:219]
	v_lshl_add_u64 v[218:219], v[174:175], 0, v[218:219]
	global_load_dwordx4 v[228:231], v[218:219], off
	global_load_dwordx4 v[232:235], v[218:219], off offset:256
	v_add_u32_e32 v218, 0xa0, v172
	v_ashrrev_i32_e32 v219, 31, v218
	v_lshlrev_b64 v[218:219], 11, v[218:219]
	v_lshl_add_u64 v[218:219], v[174:175], 0, v[218:219]
	global_load_dwordx4 v[236:239], v[218:219], off
	global_load_dwordx4 v[240:243], v[218:219], off offset:256
	v_add_u32_e32 v218, 0xb0, v172
	v_ashrrev_i32_e32 v219, 31, v218
	v_lshlrev_b64 v[218:219], 11, v[218:219]
	v_lshl_add_u64 v[218:219], v[174:175], 0, v[218:219]
	global_load_dwordx4 v[244:247], v[218:219], off
	global_load_dwordx4 v[252:255], v[218:219], off offset:256
	v_and_b32_e32 v196, 64, v194
	v_xor_b32_e32 v195, 16, v194
	v_add_u32_e32 v196, 64, v196
	v_xor_b32_e32 v197, 32, v194
	v_cmp_lt_i32_e32 vcc, v195, v196
	s_waitcnt vmcnt(15)
	v_lshlrev_b32_e32 v210, 16, v198
	v_cndmask_b32_e32 v195, v194, v195, vcc
	v_cmp_lt_i32_e32 vcc, v197, v196
	v_and_b32_e32 v211, 0xffff0000, v198
	s_waitcnt vmcnt(14)
; __device__ __forceinline__ unsigned pk2(float lo, float hi) { const f32x2 v = (f32x2){lo, hi}; const bf16x2_t b = __builtin_convertvector(v, bf16x2_t); return __builtin_bit_cast(unsigned, b); }
; __device__ __forceinline__ void unpack8(const u32x4 v, float* f) { f[0] = bf_lo(v.x); f[1] = bf_hi(v.x); f[2] = bf_lo(v.y); f[3] = bf_hi(v.y); f[4] = bf_lo(v.z); f[5] = bf_hi(v.z); f[6] = bf_lo(v.w); f[7] = bf_hi(v.w); }
;     __device__ __forceinline__ void operator()(const f32x4 (&acc)[2][2][4][2], const Unit& u, int wr, int wc, int fr, int fq, const float (&)[8]) const {
;     ...
;             for (int m = 0; m < 4; ++m) { const int row = row0 + ai * HALF + m * 16; const size_t ro = (size_t)row * DM + col0; float s = 0.f;
; #pragma unroll
;                 for (int bj = 0; bj < 2; ++bj) { float b8[8]; unpack8(bv[m][bj], b8);
;                     const f32x4 v0 = (f32x4){b8[0], b8[1], b8[2], b8[3]} + acc[ai][bj][m][0], v1 = (f32x4){b8[4], b8[5], b8[6], b8[7]} + acc[ai][bj][m][1];
;                     s += v0[0] * v0[0] + v0[1] * v0[1] + v0[2] * v0[2] + v0[3] * v0[3] + v1[0] * v1[0] + v1[1] * v1[1] + v1[2] * v1[2] + v1[3] * v1[3];
;                     if (LAST) { *(f32x4*)(out + ro + bj * HALF) = v0; *(f32x4*)(out + ro + bj * HALF + 4) = v1; }
;                     else { u32x4 w; w.x = pk2(v0[0], v0[1]); w.y = pk2(v0[2], v0[3]); w.z = pk2(v1[0], v1[1]); w.w = pk2(v1[2], v1[3]); *(u32x4*)(xb + ro + bj * HALF) = w; } }
;                 s += __shfl_xor(s, 16); s += __shfl_xor(s, 32);
;                 if (fq == 0) ss[(size_t)row * 16 + u.pn * 4 + wc] = s; }
	v_lshlrev_b32_e32 v214, 16, v202
	v_and_b32_e32 v215, 0xffff0000, v202
	v_cndmask_b32_e32 v197, v194, v197, vcc
	v_lshlrev_b32_e32 v212, 16, v200
	v_and_b32_e32 v213, 0xffff0000, v200
	v_lshlrev_b32_e32 v200, 16, v201
	v_and_b32_e32 v201, 0xffff0000, v201
	v_lshlrev_b32_e32 v216, 16, v204
	v_and_b32_e32 v217, 0xffff0000, v204
	v_pk_add_f32 v[124:125], v[124:125], v[210:211]
	v_pk_add_f32 v[116:117], v[116:117], v[214:215]
	v_lshlrev_b32_e32 v196, 2, v195
	v_lshlrev_b32_e32 v195, 2, v197
	v_lshlrev_b32_e32 v198, 16, v199
	v_and_b32_e32 v199, 0xffff0000, v199
	v_lshlrev_b32_e32 v202, 16, v203
	v_and_b32_e32 v203, 0xffff0000, v203
	v_pk_add_f32 v[122:123], v[122:123], v[200:201]
	v_pk_add_f32 v[200:201], v[112:113], v[216:217]
	v_mul_f32_e32 v197, v125, v125
	v_cvt_pk_bf16_f32 v112, v124, v125
	v_mul_f32_e32 v125, v117, v117
	v_pk_add_f32 v[126:127], v[126:127], v[198:199]
	v_pk_add_f32 v[118:119], v[118:119], v[202:203]
	v_fmac_f32_e32 v197, v124, v124
	v_fmac_f32_e32 v125, v116, v116
	v_fmac_f32_e32 v197, v126, v126
	v_fmac_f32_e32 v125, v118, v118
	v_pk_add_f32 v[120:121], v[120:121], v[212:213]
	v_fmac_f32_e32 v197, v127, v127
	v_fmac_f32_e32 v125, v119, v119
	v_lshlrev_b32_e32 v204, 16, v205
	v_and_b32_e32 v205, 0xffff0000, v205
	v_fmac_f32_e32 v197, v120, v120
	v_fmac_f32_e32 v125, v200, v200
	v_pk_add_f32 v[198:199], v[114:115], v[204:205]
	v_fmac_f32_e32 v197, v121, v121
	v_fmac_f32_e32 v125, v201, v201
	v_fmac_f32_e32 v197, v122, v122
	v_fmac_f32_e32 v125, v198, v198
	v_fmac_f32_e32 v197, v123, v123
	v_fmac_f32_e32 v125, v199, v199
	v_cvt_pk_bf16_f32 v115, v122, v123
	v_add_f32_e32 v122, v197, v125
	ds_bpermute_b32 v123, v196, v122
	v_cvt_pk_bf16_f32 v114, v120, v121
	v_lshl_add_u64 v[120:121], s[76:77], 0, v[208:209]
	v_cvt_pk_bf16_f32 v113, v126, v127
	v_lshl_add_u64 v[120:121], v[120:121], 0, v[206:207]
	global_store_dwordx4 v[120:121], v[112:115], off
	s_waitcnt lgkmcnt(0)
	s_nop 0
	v_add_f32_e32 v112, v122, v123
	ds_bpermute_b32 v113, v195, v112
	v_cvt_pk_bf16_f32 v114, v116, v117
	v_cvt_pk_bf16_f32 v115, v118, v119
	v_cvt_pk_bf16_f32 v116, v200, v201
	v_cvt_pk_bf16_f32 v117, v198, v199
	global_store_dwordx4 v[120:121], v[114:117], off offset:256
	s_and_saveexec_b64 s[22:23], s[0:1]
	s_cbranch_execz .LBB0_847
	s_waitcnt lgkmcnt(0)
	v_add_f32_e32 v114, v112, v113
	s_lshl_b32 s24, s6, 2
	v_lshlrev_b64 v[112:113], 6, v[172:173]
	s_ashr_i32 s25, s24, 31
	v_lshl_add_u64 v[112:113], s[10:11], 0, v[112:113]
	v_lshl_add_u64 v[112:113], s[24:25], 2, v[112:113]
	s_lshl_b32 s8, s37, 2
	v_lshl_add_u64 v[112:113], v[112:113], 0, s[8:9]
	global_store_dword v[112:113], v114, off
.LBB0_847:
	s_or_b64 exec, exec, s[22:23]
	s_waitcnt vmcnt(15)
	v_lshlrev_b32_e32 v112, 16, v148
	s_waitcnt lgkmcnt(0)
	v_and_b32_e32 v113, 0xffff0000, v148
	v_lshlrev_b32_e32 v116, 16, v150
	v_and_b32_e32 v117, 0xffff0000, v150
	v_lshlrev_b32_e32 v118, 16, v151
	v_and_b32_e32 v119, 0xffff0000, v151
	v_pk_add_f32 v[108:109], v[108:109], v[112:113]
	v_lshlrev_b32_e32 v114, 16, v149
	v_and_b32_e32 v115, 0xffff0000, v149
	v_pk_add_f32 v[112:113], v[106:107], v[118:119]
	v_pk_add_f32 v[106:107], v[104:105], v[116:117]
	v_mul_f32_e32 v116, v109, v109
	v_pk_add_f32 v[110:111], v[110:111], v[114:115]
	v_fmac_f32_e32 v116, v108, v108
	v_fmac_f32_e32 v116, v110, v110
	v_fmac_f32_e32 v116, v111, v111
	v_fmac_f32_e32 v116, v106, v106
	v_fmac_f32_e32 v116, v107, v107
	v_fmac_f32_e32 v116, v112, v112
	v_cvt_pk_bf16_f32 v104, v108, v109
	s_waitcnt vmcnt(14)
	v_lshlrev_b32_e32 v108, 16, v144
	v_and_b32_e32 v109, 0xffff0000, v144
	v_fmac_f32_e32 v116, v113, v113
	v_cvt_pk_bf16_f32 v105, v110, v111
	v_cvt_pk_bf16_f32 v106, v106, v107
	v_cvt_pk_bf16_f32 v107, v112, v113
	v_lshlrev_b32_e32 v110, 16, v145
	v_and_b32_e32 v111, 0xffff0000, v145
	v_lshlrev_b32_e32 v112, 16, v146
	v_and_b32_e32 v113, 0xffff0000, v146
	v_pk_add_f32 v[100:101], v[100:101], v[108:109]
	v_pk_add_f32 v[102:103], v[102:103], v[110:111]
	v_pk_add_f32 v[110:111], v[96:97], v[112:113]
	v_mul_f32_e32 v96, v101, v101
	v_fmac_f32_e32 v96, v100, v100
	v_fmac_f32_e32 v96, v102, v102
	v_fmac_f32_e32 v96, v103, v103
	v_lshlrev_b32_e32 v114, 16, v147
	v_and_b32_e32 v115, 0xffff0000, v147
	v_fmac_f32_e32 v96, v110, v110
	v_pk_add_f32 v[108:109], v[98:99], v[114:115]
	v_fmac_f32_e32 v96, v111, v111
	v_fmac_f32_e32 v96, v108, v108
	v_fmac_f32_e32 v96, v109, v109
	v_add_f32_e32 v99, v116, v96
	ds_bpermute_b32 v114, v196, v99
	v_lshl_add_u64 v[96:97], s[76:77], 0, v[186:187]
	v_lshl_add_u64 v[112:113], v[170:171], 1, v[96:97]
	v_cvt_pk_bf16_f32 v98, v100, v101
	v_cvt_pk_bf16_f32 v100, v110, v111
	s_waitcnt lgkmcnt(0)
	v_add_f32_e32 v96, v99, v114
	ds_bpermute_b32 v97, v195, v96
	v_cvt_pk_bf16_f32 v99, v102, v103
	v_cvt_pk_bf16_f32 v101, v108, v109
	global_store_dwordx4 v[112:113], v[104:107], off
	global_store_dwordx4 v[112:113], v[98:101], off offset:256
	s_and_saveexec_b64 s[22:23], s[0:1]
	s_cbranch_execz .LBB0_849
	s_waitcnt lgkmcnt(0)
	v_add_f32_e32 v98, v96, v97
	s_lshl_b32 s24, s6, 2
	v_lshlrev_b64 v[96:97], 6, v[184:185]
	s_ashr_i32 s25, s24, 31
	v_lshl_add_u64 v[96:97], s[10:11], 0, v[96:97]
	v_lshl_add_u64 v[96:97], s[24:25], 2, v[96:97]
	s_lshl_b32 s8, s37, 2
	v_lshl_add_u64 v[96:97], v[96:97], 0, s[8:9]
	global_store_dword v[96:97], v98, off
; __device__ __forceinline__ unsigned pk2(float lo, float hi) { const f32x2 v = (f32x2){lo, hi}; const bf16x2_t b = __builtin_convertvector(v, bf16x2_t); return __builtin_bit_cast(unsigned, b); }
; __device__ __forceinline__ void unpack8(const u32x4 v, float* f) { f[0] = bf_lo(v.x); f[1] = bf_hi(v.x); f[2] = bf_lo(v.y); f[3] = bf_hi(v.y); f[4] = bf_lo(v.z); f[5] = bf_hi(v.z); f[6] = bf_lo(v.w); f[7] = bf_hi(v.w); }
;     __device__ __forceinline__ void operator()(const f32x4 (&acc)[2][2][4][2], const Unit& u, int wr, int wc, int fr, int fq, const float (&)[8]) const {
;     ...
;             for (int m = 0; m < 4; ++m) { const int row = row0 + ai * HALF + m * 16; const size_t ro = (size_t)row * DM + col0; float s = 0.f;
; #pragma unroll
;                 for (int bj = 0; bj < 2; ++bj) { float b8[8]; unpack8(bv[m][bj], b8);
;                     const f32x4 v0 = (f32x4){b8[0], b8[1], b8[2], b8[3]} + acc[ai][bj][m][0], v1 = (f32x4){b8[4], b8[5], b8[6], b8[7]} + acc[ai][bj][m][1];
;                     s += v0[0] * v0[0] + v0[1] * v0[1] + v0[2] * v0[2] + v0[3] * v0[3] + v1[0] * v1[0] + v1[1] * v1[1] + v1[2] * v1[2] + v1[3] * v1[3];
;                     if (LAST) { *(f32x4*)(out + ro + bj * HALF) = v0; *(f32x4*)(out + ro + bj * HALF + 4) = v1; }
;                     else { u32x4 w; w.x = pk2(v0[0], v0[1]); w.y = pk2(v0[2], v0[3]); w.z = pk2(v1[0], v1[1]); w.w = pk2(v1[2], v1[3]); *(u32x4*)(xb + ro + bj * HALF) = w; } }
;                 s += __shfl_xor(s, 16); s += __shfl_xor(s, 32);
;                 if (fq == 0) ss[(size_t)row * 16 + u.pn * 4 + wc] = s; }
.LBB0_849:
	s_or_b64 exec, exec, s[22:23]
	s_waitcnt vmcnt(15)
	v_lshlrev_b32_e32 v96, 16, v140
	s_waitcnt lgkmcnt(0)
	v_and_b32_e32 v97, 0xffff0000, v140
	v_lshlrev_b32_e32 v100, 16, v142
	v_and_b32_e32 v101, 0xffff0000, v142
	v_lshlrev_b32_e32 v102, 16, v143
	v_and_b32_e32 v103, 0xffff0000, v143
	v_pk_add_f32 v[92:93], v[92:93], v[96:97]
	v_lshlrev_b32_e32 v98, 16, v141
	v_and_b32_e32 v99, 0xffff0000, v141
	v_pk_add_f32 v[96:97], v[90:91], v[102:103]
	v_pk_add_f32 v[90:91], v[88:89], v[100:101]
	v_mul_f32_e32 v100, v93, v93
	v_pk_add_f32 v[94:95], v[94:95], v[98:99]
	v_fmac_f32_e32 v100, v92, v92
	v_fmac_f32_e32 v100, v94, v94
	v_fmac_f32_e32 v100, v95, v95
	v_fmac_f32_e32 v100, v90, v90
	v_fmac_f32_e32 v100, v91, v91
	v_fmac_f32_e32 v100, v96, v96
	v_cvt_pk_bf16_f32 v88, v92, v93
	s_waitcnt vmcnt(14)
	v_lshlrev_b32_e32 v92, 16, v136
	v_and_b32_e32 v93, 0xffff0000, v136
	v_fmac_f32_e32 v100, v97, v97
	v_cvt_pk_bf16_f32 v89, v94, v95
	v_cvt_pk_bf16_f32 v90, v90, v91
	v_cvt_pk_bf16_f32 v91, v96, v97
	v_lshlrev_b32_e32 v94, 16, v137
	v_and_b32_e32 v95, 0xffff0000, v137
	v_lshlrev_b32_e32 v96, 16, v138
	v_and_b32_e32 v97, 0xffff0000, v138
	v_pk_add_f32 v[84:85], v[84:85], v[92:93]
	v_pk_add_f32 v[86:87], v[86:87], v[94:95]
	v_pk_add_f32 v[94:95], v[80:81], v[96:97]
	v_mul_f32_e32 v80, v85, v85
	v_fmac_f32_e32 v80, v84, v84
	v_fmac_f32_e32 v80, v86, v86
	v_fmac_f32_e32 v80, v87, v87
	v_lshlrev_b32_e32 v98, 16, v139
	v_and_b32_e32 v99, 0xffff0000, v139
	v_fmac_f32_e32 v80, v94, v94
	v_pk_add_f32 v[92:93], v[82:83], v[98:99]
	v_fmac_f32_e32 v80, v95, v95
	v_fmac_f32_e32 v80, v92, v92
	v_fmac_f32_e32 v80, v93, v93
	v_add_f32_e32 v83, v100, v80
	ds_bpermute_b32 v98, v196, v83
	v_lshl_add_u64 v[80:81], s[76:77], 0, v[182:183]
	v_lshl_add_u64 v[96:97], v[170:171], 1, v[80:81]
	v_cvt_pk_bf16_f32 v82, v84, v85
	v_cvt_pk_bf16_f32 v84, v94, v95
	s_waitcnt lgkmcnt(0)
	v_add_f32_e32 v80, v83, v98
	ds_bpermute_b32 v81, v195, v80
	v_cvt_pk_bf16_f32 v83, v86, v87
	v_cvt_pk_bf16_f32 v85, v92, v93
	global_store_dwordx4 v[96:97], v[88:91], off
	global_store_dwordx4 v[96:97], v[82:85], off offset:256
	s_and_saveexec_b64 s[22:23], s[0:1]
	s_cbranch_execz .LBB0_851
	s_waitcnt lgkmcnt(0)
	v_add_f32_e32 v82, v80, v81
	s_lshl_b32 s24, s6, 2
	v_lshlrev_b64 v[80:81], 6, v[180:181]
	s_ashr_i32 s25, s24, 31
	v_lshl_add_u64 v[80:81], s[10:11], 0, v[80:81]
	v_lshl_add_u64 v[80:81], s[24:25], 2, v[80:81]
	s_lshl_b32 s8, s37, 2
	v_lshl_add_u64 v[80:81], v[80:81], 0, s[8:9]
	global_store_dword v[80:81], v82, off
.LBB0_851:
	s_or_b64 exec, exec, s[22:23]
	s_waitcnt vmcnt(15)
	v_lshlrev_b32_e32 v80, 16, v132
	s_waitcnt lgkmcnt(0)
	v_and_b32_e32 v81, 0xffff0000, v132
	v_lshlrev_b32_e32 v84, 16, v134
	v_and_b32_e32 v85, 0xffff0000, v134
	v_lshlrev_b32_e32 v86, 16, v135
	v_and_b32_e32 v87, 0xffff0000, v135
	v_pk_add_f32 v[76:77], v[76:77], v[80:81]
	v_lshlrev_b32_e32 v82, 16, v133
	v_and_b32_e32 v83, 0xffff0000, v133
	v_pk_add_f32 v[80:81], v[74:75], v[86:87]
	v_pk_add_f32 v[74:75], v[72:73], v[84:85]
	v_mul_f32_e32 v84, v77, v77
	v_pk_add_f32 v[78:79], v[78:79], v[82:83]
	v_fmac_f32_e32 v84, v76, v76
	v_fmac_f32_e32 v84, v78, v78
	v_fmac_f32_e32 v84, v79, v79
	v_fmac_f32_e32 v84, v74, v74
	v_fmac_f32_e32 v84, v75, v75
	v_fmac_f32_e32 v84, v80, v80
	v_cvt_pk_bf16_f32 v72, v76, v77
	s_waitcnt vmcnt(14)
	v_lshlrev_b32_e32 v76, 16, v128
	v_and_b32_e32 v77, 0xffff0000, v128
	v_fmac_f32_e32 v84, v81, v81
	v_cvt_pk_bf16_f32 v73, v78, v79
	v_cvt_pk_bf16_f32 v74, v74, v75
	v_cvt_pk_bf16_f32 v75, v80, v81
	v_lshlrev_b32_e32 v78, 16, v129
	v_and_b32_e32 v79, 0xffff0000, v129
	v_lshlrev_b32_e32 v80, 16, v130
	v_and_b32_e32 v81, 0xffff0000, v130
	v_pk_add_f32 v[68:69], v[68:69], v[76:77]
	v_pk_add_f32 v[70:71], v[70:71], v[78:79]
	v_pk_add_f32 v[78:79], v[64:65], v[80:81]
	v_mul_f32_e32 v64, v69, v69
	v_fmac_f32_e32 v64, v68, v68
	v_fmac_f32_e32 v64, v70, v70
	v_fmac_f32_e32 v64, v71, v71
	v_lshlrev_b32_e32 v82, 16, v131
	v_and_b32_e32 v83, 0xffff0000, v131
	v_fmac_f32_e32 v64, v78, v78
	v_pk_add_f32 v[76:77], v[66:67], v[82:83]
	v_fmac_f32_e32 v64, v79, v79
	v_fmac_f32_e32 v64, v76, v76
	v_fmac_f32_e32 v64, v77, v77
	v_add_f32_e32 v67, v84, v64
	ds_bpermute_b32 v82, v196, v67
	v_lshl_add_u64 v[64:65], s[76:77], 0, v[178:179]
	v_lshl_add_u64 v[80:81], v[170:171], 1, v[64:65]
	v_cvt_pk_bf16_f32 v66, v68, v69
	v_cvt_pk_bf16_f32 v68, v78, v79
	s_waitcnt lgkmcnt(0)
	v_add_f32_e32 v64, v67, v82
	ds_bpermute_b32 v65, v195, v64
	v_cvt_pk_bf16_f32 v67, v70, v71
	v_cvt_pk_bf16_f32 v69, v76, v77
	global_store_dwordx4 v[80:81], v[72:75], off
	global_store_dwordx4 v[80:81], v[66:69], off offset:256
	s_and_saveexec_b64 s[22:23], s[0:1]
	s_cbranch_execz .LBB0_853
	s_waitcnt lgkmcnt(0)
	v_add_f32_e32 v66, v64, v65
	s_lshl_b32 s24, s6, 2
	v_lshlrev_b64 v[64:65], 6, v[176:177]
	s_ashr_i32 s25, s24, 31
	v_lshl_add_u64 v[64:65], s[10:11], 0, v[64:65]
	v_lshl_add_u64 v[64:65], s[24:25], 2, v[64:65]
	s_lshl_b32 s8, s37, 2
	v_lshl_add_u64 v[64:65], v[64:65], 0, s[8:9]
	global_store_dword v[64:65], v66, off
; __device__ __forceinline__ unsigned pk2(float lo, float hi) { const f32x2 v = (f32x2){lo, hi}; const bf16x2_t b = __builtin_convertvector(v, bf16x2_t); return __builtin_bit_cast(unsigned, b); }
; __device__ __forceinline__ void unpack8(const u32x4 v, float* f) { f[0] = bf_lo(v.x); f[1] = bf_hi(v.x); f[2] = bf_lo(v.y); f[3] = bf_hi(v.y); f[4] = bf_lo(v.z); f[5] = bf_hi(v.z); f[6] = bf_lo(v.w); f[7] = bf_hi(v.w); }
;     __device__ __forceinline__ void operator()(const f32x4 (&acc)[2][2][4][2], const Unit& u, int wr, int wc, int fr, int fq, const float (&)[8]) const {
;     ...
;         for (int ai = 0; ai < 2; ++ai) {
;             u32x4 bv[4][2];
; #pragma unroll
;             for (int m = 0; m < 4; ++m)
; #pragma unroll
;                 for (int bj = 0; bj < 2; ++bj) bv[m][bj] = *(const u32x4*)(xb + (size_t)(row0 + ai * HALF + m * 16) * DM + col0 + bj * HALF);
; #pragma unroll
;             for (int m = 0; m < 4; ++m) { const int row = row0 + ai * HALF + m * 16; const size_t ro = (size_t)row * DM + col0; float s = 0.f;
; #pragma unroll
;                 for (int bj = 0; bj < 2; ++bj) { float b8[8]; unpack8(bv[m][bj], b8);
;                     const f32x4 v0 = (f32x4){b8[0], b8[1], b8[2], b8[3]} + acc[ai][bj][m][0], v1 = (f32x4){b8[4], b8[5], b8[6], b8[7]} + acc[ai][bj][m][1];
;                     s += v0[0] * v0[0] + v0[1] * v0[1] + v0[2] * v0[2] + v0[3] * v0[3] + v1[0] * v1[0] + v1[1] * v1[1] + v1[2] * v1[2] + v1[3] * v1[3];
;                     if (LAST) { *(f32x4*)(out + ro + bj * HALF) = v0; *(f32x4*)(out + ro + bj * HALF + 4) = v1; }
;                     else { u32x4 w; w.x = pk2(v0[0], v0[1]); w.y = pk2(v0[2], v0[3]); w.z = pk2(v1[0], v1[1]); w.w = pk2(v1[2], v1[3]); *(u32x4*)(xb + ro + bj * HALF) = w; } }
;                 s += __shfl_xor(s, 16); s += __shfl_xor(s, 32);
;                 if (fq == 0) ss[(size_t)row * 16 + u.pn * 4 + wc] = s; }
.LBB0_853:
	s_or_b64 exec, exec, s[22:23]
	v_add_u32_e32 v100, 0x80, v172
	v_ashrrev_i32_e32 v101, 31, v100
	v_lshlrev_b64 v[110:111], 11, v[100:101]
	s_waitcnt lgkmcnt(0)
	v_lshl_add_u64 v[64:65], v[174:175], 0, v[110:111]
	s_waitcnt vmcnt(15)
	v_mov_b32_e32 v102, v220
	v_mov_b32_e32 v103, v221
	v_mov_b32_e32 v104, v222
	v_mov_b32_e32 v105, v223
	s_waitcnt vmcnt(14)
	v_mov_b32_e32 v106, v224
	v_mov_b32_e32 v107, v225
	v_mov_b32_e32 v108, v226
	v_mov_b32_e32 v109, v227
	v_add_u32_e32 v96, 0x90, v172
	v_add_u32_e32 v92, 0xa0, v172
	v_add_u32_e32 v88, 0xb0, v172
	v_ashrrev_i32_e32 v97, 31, v96
	v_ashrrev_i32_e32 v93, 31, v92
	v_ashrrev_i32_e32 v89, 31, v88
	v_lshlrev_b64 v[98:99], 11, v[96:97]
	v_lshlrev_b64 v[94:95], 11, v[92:93]
	v_lshlrev_b64 v[90:91], 11, v[88:89]
	v_lshl_add_u64 v[64:65], v[174:175], 0, v[98:99]
	v_lshl_add_u64 v[66:67], v[174:175], 0, v[94:95]
	v_lshl_add_u64 v[112:113], v[174:175], 0, v[90:91]
	s_waitcnt vmcnt(13)
	v_mov_b32_e32 v84, v228
	v_mov_b32_e32 v85, v229
	v_mov_b32_e32 v86, v230
	v_mov_b32_e32 v87, v231
	s_waitcnt vmcnt(12)
	v_mov_b32_e32 v80, v232
	v_mov_b32_e32 v81, v233
	v_mov_b32_e32 v82, v234
	v_mov_b32_e32 v83, v235
	s_waitcnt vmcnt(11)
	v_mov_b32_e32 v76, v236
	v_mov_b32_e32 v77, v237
	v_mov_b32_e32 v78, v238
	v_mov_b32_e32 v79, v239
	s_waitcnt vmcnt(10)
	v_mov_b32_e32 v72, v240
	v_mov_b32_e32 v73, v241
	v_mov_b32_e32 v74, v242
	v_mov_b32_e32 v75, v243
	s_waitcnt vmcnt(9)
	v_mov_b32_e32 v68, v244
	v_mov_b32_e32 v69, v245
	v_mov_b32_e32 v70, v246
	v_mov_b32_e32 v71, v247
	s_nop 0
	s_waitcnt vmcnt(8)
	v_mov_b32_e32 v64, v252
	v_mov_b32_e32 v65, v253
	v_mov_b32_e32 v66, v254
	v_mov_b32_e32 v67, v255
	s_nop 0
	v_lshlrev_b32_e32 v112, 16, v102
	v_and_b32_e32 v113, 0xffff0000, v102
	s_nop 0
	v_lshlrev_b32_e32 v116, 16, v106
	v_and_b32_e32 v117, 0xffff0000, v106
	v_lshlrev_b32_e32 v114, 16, v104
	v_and_b32_e32 v115, 0xffff0000, v104
	v_lshlrev_b32_e32 v104, 16, v105
	v_and_b32_e32 v105, 0xffff0000, v105
	v_lshlrev_b32_e32 v106, 16, v107
	v_and_b32_e32 v107, 0xffff0000, v107
	v_lshlrev_b32_e32 v118, 16, v108
	v_and_b32_e32 v119, 0xffff0000, v108
	v_pk_add_f32 v[60:61], v[60:61], v[112:113]
	v_pk_add_f32 v[52:53], v[52:53], v[116:117]
	v_lshlrev_b32_e32 v102, 16, v103
	v_and_b32_e32 v103, 0xffff0000, v103
	v_pk_add_f32 v[58:59], v[58:59], v[104:105]
	v_pk_add_f32 v[54:55], v[54:55], v[106:107]
	v_pk_add_f32 v[104:105], v[48:49], v[118:119]
	v_mul_f32_e32 v106, v61, v61
	v_cvt_pk_bf16_f32 v48, v60, v61
	v_mul_f32_e32 v61, v53, v53
	v_pk_add_f32 v[62:63], v[62:63], v[102:103]
	v_fmac_f32_e32 v106, v60, v60
	v_fmac_f32_e32 v61, v52, v52
	v_fmac_f32_e32 v106, v62, v62
	v_fmac_f32_e32 v61, v54, v54
	v_pk_add_f32 v[56:57], v[56:57], v[114:115]
	v_fmac_f32_e32 v106, v63, v63
	v_fmac_f32_e32 v61, v55, v55
	v_lshlrev_b32_e32 v108, 16, v109
	v_and_b32_e32 v109, 0xffff0000, v109
	v_fmac_f32_e32 v106, v56, v56
	v_fmac_f32_e32 v61, v104, v104
	v_pk_add_f32 v[102:103], v[50:51], v[108:109]
	v_fmac_f32_e32 v106, v57, v57
	v_fmac_f32_e32 v61, v105, v105
	v_fmac_f32_e32 v106, v58, v58
	v_fmac_f32_e32 v61, v102, v102
	v_fmac_f32_e32 v106, v59, v59
	v_fmac_f32_e32 v61, v103, v103
	v_cvt_pk_bf16_f32 v51, v58, v59
	v_add_f32_e32 v58, v106, v61
	ds_bpermute_b32 v59, v196, v58
	v_cvt_pk_bf16_f32 v50, v56, v57
	v_lshl_add_u64 v[56:57], s[76:77], 0, v[110:111]
	v_cvt_pk_bf16_f32 v49, v62, v63
	v_lshl_add_u64 v[56:57], v[170:171], 1, v[56:57]
	global_store_dwordx4 v[56:57], v[48:51], off
	s_waitcnt lgkmcnt(0)
	s_nop 0
	v_add_f32_e32 v48, v58, v59
	ds_bpermute_b32 v49, v195, v48
	v_cvt_pk_bf16_f32 v50, v52, v53
	v_cvt_pk_bf16_f32 v51, v54, v55
	v_cvt_pk_bf16_f32 v52, v104, v105
	v_cvt_pk_bf16_f32 v53, v102, v103
	global_store_dwordx4 v[56:57], v[50:53], off offset:256
	s_and_saveexec_b64 s[22:23], s[0:1]
	s_cbranch_execz .LBB0_855
	s_waitcnt lgkmcnt(0)
	v_add_f32_e32 v50, v48, v49
	s_lshl_b32 s24, s6, 2
	v_lshlrev_b64 v[48:49], 6, v[100:101]
	s_ashr_i32 s25, s24, 31
	v_lshl_add_u64 v[48:49], s[10:11], 0, v[48:49]
	v_lshl_add_u64 v[48:49], s[24:25], 2, v[48:49]
	s_lshl_b32 s8, s37, 2
	v_lshl_add_u64 v[48:49], v[48:49], 0, s[8:9]
	global_store_dword v[48:49], v50, off

; #define PG8_STAGE(bufoff, gbase, voff) do { _Pragma("unroll") for (int _i = 0; _i < 2; ++_i) \
;         __builtin_amdgcn_global_load_lds((const unsigned*)((const char*)(gbase) + (voff)[_i]), (LAS unsigned*)(lds + (bufoff) + ldsw + _i * 8192), 16, 0, 0); } while (0)
; #define PG8_LDA(dst, b, h) do { _Pragma("unroll") for (int m = 0; m < 4; ++m) _Pragma("unroll") for (int k = 0; k < 2; ++k) dst[m][k] = *(const LAS bf16x8*)(lds + PG8_SA(b, h) + aoff + m * 2048 + k * 1024); } while (0)
; #define PG8_LDB(dst, b, h) do { _Pragma("unroll") for (int n = 0; n < 2; ++n) _Pragma("unroll") for (int k = 0; k < 2; ++k) dst[n][k] = *(const LAS bf16x8*)(lds + PG8_SB(b, h) + boff + n * 2048 + k * 1024); } while (0)
; #define PG8_MMA(ai, bj, At, Bt) do { __builtin_amdgcn_s_setprio(1); _Pragma("unroll") for (int m = 0; m < 4; ++m) _Pragma("unroll") for (int n = 0; n < 2; ++n) _Pragma("unroll") for (int k = 0; k < 2; ++k) \
;         acc[ai][bj][m][n] = __builtin_amdgcn_mfma_f32_16x16x32_bf16(Bt[n][k], At[m][k], acc[ai][bj][m][n], 0, 0, 0); __builtin_amdgcn_s_setprio(0); } while (0)
; #define PG8_WAIT_L(n) asm volatile("s_waitcnt lgkmcnt(" #n ")" ::: "memory")
; #define PG8_BAR __builtin_amdgcn_s_barrier()
; #define PG8_SCHED __builtin_amdgcn_sched_barrier(0)
; template <class Epi>
; __device__ __forceinline__ void gemm_phase(LAS unsigned char* lds, const Gemm g, const StaticOrder& S, const Epi& E) {
;     ...
;             PG8_LDB(B0, 0, 0); PG8_SCHED; PG8_LDA(At, 0, 0); PG8_STAGE(PG8_SA(1, 1), a1 + hstepA, voffA);
;             PG8_WAIT_L(8); PG8_BAR; PG8_WAIT_L(0); PG8_MMA(0, 0, At, B0); PG8_BAR; PG8_SCHED;
;             PG8_LDB(B1, 0, 1); PG8_STAGE(PG8_SB(0, 0), b2, voffB);
;             PG8_BAR; PG8_WAIT_L(0); PG8_MMA(0, 1, At, B1); PG8_BAR;
;             PG8_LDA(At, 0, 1); PG8_STAGE(PG8_SA(0, 0), a2, voffA);
;             PG8_BAR; PG8_WAIT_L(0); PG8_MMA(1, 0, At, B0); PG8_BAR; PG8_SCHED;
;             PG8_STAGE(PG8_SB(0, 1), b2 + hstepB, voffB);
.LBB0_1118:
	ds_read_b128 v[128:131], v190
	ds_read_b128 v[132:135], v190 offset:1024
	ds_read_b128 v[136:139], v190 offset:2048
	ds_read_b128 v[140:143], v190 offset:3072
	s_add_u32 s22, s4, 0xffec0080
	s_addc_u32 s23, s5, -1
	s_cmp_eq_u32 s46, 12
	s_cselect_b32 s25, s19, s23
	s_cselect_b32 s24, s18, s22
	s_cselect_b32 s23, s17, s45
	s_cselect_b32 s22, s43, s44
	v_lshl_add_u64 v[186:187], s[4:5], 0, v[162:163]
	s_add_i32 m0, s9, 0xc000
	ds_read_b128 v[144:147], v191
	ds_read_b128 v[148:151], v191 offset:1024
	ds_read_b128 v[170:173], v191 offset:2048
	ds_read_b128 v[174:177], v191 offset:3072
	ds_read_b128 v[178:181], v191 offset:4096
	ds_read_b128 v[182:185], v191 offset:5120
	ds_read_b128 v[194:197], v191 offset:6144
	ds_read_b128 v[198:201], v191 offset:7168
	global_load_lds_dwordx4 v[186:187], off
	v_lshl_add_u64 v[186:187], s[4:5], 0, v[164:165]
	s_add_i32 m0, s9, 0xe000
	s_nop 0
	global_load_lds_dwordx4 v[186:187], off
	s_waitcnt lgkmcnt(8)
	s_barrier
	s_waitcnt lgkmcnt(0)
	s_setprio 1
	s_waitcnt lgkmcnt(0)
	v_mfma_f32_16x16x32_bf16 v[124:127], v[128:131], v[144:147], v[124:127]
	v_mfma_f32_16x16x32_bf16 v[120:123], v[136:139], v[144:147], v[120:123]
	v_mfma_f32_16x16x32_bf16 v[108:111], v[128:131], v[170:173], v[108:111]
	v_mfma_f32_16x16x32_bf16 v[104:107], v[136:139], v[170:173], v[104:107]
	v_mfma_f32_16x16x32_bf16 v[92:95], v[128:131], v[178:181], v[92:95]
	v_mfma_f32_16x16x32_bf16 v[88:91], v[136:139], v[178:181], v[88:91]
	v_mfma_f32_16x16x32_bf16 v[76:79], v[128:131], v[194:197], v[76:79]
	v_mfma_f32_16x16x32_bf16 v[72:75], v[136:139], v[194:197], v[72:75]
	v_mfma_f32_16x16x32_bf16 v[124:127], v[132:135], v[148:151], v[124:127]
	v_mfma_f32_16x16x32_bf16 v[120:123], v[140:143], v[148:151], v[120:123]
	v_mfma_f32_16x16x32_bf16 v[108:111], v[132:135], v[174:177], v[108:111]
	v_mfma_f32_16x16x32_bf16 v[104:107], v[140:143], v[174:177], v[104:107]
	v_mfma_f32_16x16x32_bf16 v[92:95], v[132:135], v[182:185], v[92:95]
	v_mfma_f32_16x16x32_bf16 v[88:91], v[140:143], v[182:185], v[88:91]
	v_mfma_f32_16x16x32_bf16 v[76:79], v[132:135], v[198:201], v[76:79]
	v_mfma_f32_16x16x32_bf16 v[72:75], v[140:143], v[198:201], v[72:75]
	s_setprio 0
	s_barrier
	s_add_i32 s47, s40, s29
	v_lshl_add_u64 v[186:187], s[22:23], 0, v[156:157]
	s_mov_b32 m0, s47
	ds_read_b128 v[202:205], v192
	ds_read_b128 v[206:209], v192 offset:1024
	ds_read_b128 v[210:213], v192 offset:2048
	ds_read_b128 v[214:217], v192 offset:3072
	global_load_lds_dwordx4 v[186:187], off
	v_lshl_add_u64 v[218:219], s[22:23], 0, v[160:161]
	s_add_i32 m0, s47, 0x2000
	s_nop 0
	global_load_lds_dwordx4 v[218:219], off
	s_barrier
	s_waitcnt lgkmcnt(0)
	s_setprio 1
	s_waitcnt lgkmcnt(0)
	v_mfma_f32_16x16x32_bf16 v[116:119], v[202:205], v[144:147], v[116:119]
	v_mfma_f32_16x16x32_bf16 v[112:115], v[210:213], v[144:147], v[112:115]
	v_mfma_f32_16x16x32_bf16 v[100:103], v[202:205], v[170:173], v[100:103]
	v_mfma_f32_16x16x32_bf16 v[96:99], v[210:213], v[170:173], v[96:99]
	v_mfma_f32_16x16x32_bf16 v[84:87], v[202:205], v[178:181], v[84:87]
	v_mfma_f32_16x16x32_bf16 v[80:83], v[210:213], v[178:181], v[80:83]
	v_mfma_f32_16x16x32_bf16 v[68:71], v[202:205], v[194:197], v[68:71]
	v_mfma_f32_16x16x32_bf16 v[64:67], v[210:213], v[194:197], v[64:67]
	v_mfma_f32_16x16x32_bf16 v[116:119], v[206:209], v[148:151], v[116:119]
	v_mfma_f32_16x16x32_bf16 v[112:115], v[214:217], v[148:151], v[112:115]
	v_mfma_f32_16x16x32_bf16 v[100:103], v[206:209], v[174:177], v[100:103]
	v_mfma_f32_16x16x32_bf16 v[96:99], v[214:217], v[174:177], v[96:99]
	v_mfma_f32_16x16x32_bf16 v[84:87], v[206:209], v[182:185], v[84:87]
	v_mfma_f32_16x16x32_bf16 v[80:83], v[214:217], v[182:185], v[80:83]
	v_mfma_f32_16x16x32_bf16 v[68:71], v[206:209], v[198:201], v[68:71]
	v_mfma_f32_16x16x32_bf16 v[64:67], v[214:217], v[198:201], v[64:67]
	s_setprio 0
	s_mov_b32 m0, s9
	v_lshl_add_u64 v[220:221], s[24:25], 0, v[154:155]
	s_barrier
	ds_read_b128 v[144:147], v191 offset:16384
	ds_read_b128 v[148:151], v191 offset:17408
	ds_read_b128 v[170:173], v191 offset:18432
	ds_read_b128 v[174:177], v191 offset:19456
	ds_read_b128 v[178:181], v191 offset:20480
	ds_read_b128 v[182:185], v191 offset:21504
	ds_read_b128 v[194:197], v191 offset:22528
	ds_read_b128 v[198:201], v191 offset:23552
	global_load_lds_dwordx4 v[220:221], off
	v_lshl_add_u64 v[222:223], s[24:25], 0, v[158:159]
	s_mov_b32 m0, s30
	s_nop 0
	global_load_lds_dwordx4 v[222:223], off
	s_barrier
	s_waitcnt lgkmcnt(0)
	s_setprio 1
	s_waitcnt lgkmcnt(0)
	v_mfma_f32_16x16x32_bf16 v[60:63], v[128:131], v[144:147], v[60:63]
	v_mfma_f32_16x16x32_bf16 v[56:59], v[136:139], v[144:147], v[56:59]
	v_mfma_f32_16x16x32_bf16 v[44:47], v[128:131], v[170:173], v[44:47]
	v_mfma_f32_16x16x32_bf16 v[40:43], v[136:139], v[170:173], v[40:43]
	v_mfma_f32_16x16x32_bf16 v[28:31], v[128:131], v[178:181], v[28:31]
	v_mfma_f32_16x16x32_bf16 v[24:27], v[136:139], v[178:181], v[24:27]
	v_mfma_f32_16x16x32_bf16 v[12:15], v[128:131], v[194:197], v[12:15]
	v_mfma_f32_16x16x32_bf16 v[8:11], v[136:139], v[194:197], v[8:11]
	v_mfma_f32_16x16x32_bf16 v[60:63], v[132:135], v[148:151], v[60:63]
	v_mfma_f32_16x16x32_bf16 v[56:59], v[140:143], v[148:151], v[56:59]
	v_mfma_f32_16x16x32_bf16 v[44:47], v[132:135], v[174:177], v[44:47]
	v_mfma_f32_16x16x32_bf16 v[40:43], v[140:143], v[174:177], v[40:43]
	v_mfma_f32_16x16x32_bf16 v[28:31], v[132:135], v[182:185], v[28:31]
	v_mfma_f32_16x16x32_bf16 v[24:27], v[140:143], v[182:185], v[24:27]
	v_mfma_f32_16x16x32_bf16 v[12:15], v[132:135], v[198:201], v[12:15]
	v_mfma_f32_16x16x32_bf16 v[8:11], v[140:143], v[198:201], v[8:11]
	s_setprio 0
	s_barrier
; #define PG8_STAGE(bufoff, gbase, voff) do { _Pragma("unroll") for (int _i = 0; _i < 2; ++_i) \
;         __builtin_amdgcn_global_load_lds((const unsigned*)((const char*)(gbase) + (voff)[_i]), (LAS unsigned*)(lds + (bufoff) + ldsw + _i * 8192), 16, 0, 0); } while (0)
; #define PG8_LDA(dst, b, h) do { _Pragma("unroll") for (int m = 0; m < 4; ++m) _Pragma("unroll") for (int k = 0; k < 2; ++k) dst[m][k] = *(const LAS bf16x8*)(lds + PG8_SA(b, h) + aoff + m * 2048 + k * 1024); } while (0)
; #define PG8_LDB(dst, b, h) do { _Pragma("unroll") for (int n = 0; n < 2; ++n) _Pragma("unroll") for (int k = 0; k < 2; ++k) dst[n][k] = *(const LAS bf16x8*)(lds + PG8_SB(b, h) + boff + n * 2048 + k * 1024); } while (0)
; #define PG8_MMA(ai, bj, At, Bt) do { __builtin_amdgcn_s_setprio(1); _Pragma("unroll") for (int m = 0; m < 4; ++m) _Pragma("unroll") for (int n = 0; n < 2; ++n) _Pragma("unroll") for (int k = 0; k < 2; ++k) \
;         acc[ai][bj][m][n] = __builtin_amdgcn_mfma_f32_16x16x32_bf16(Bt[n][k], At[m][k], acc[ai][bj][m][n], 0, 0, 0); __builtin_amdgcn_s_setprio(0); } while (0)
; #define PG8_WAIT_V(n) asm volatile("s_waitcnt vmcnt(" #n ")" ::: "memory")
; #define PG8_WAIT_L(n) asm volatile("s_waitcnt lgkmcnt(" #n ")" ::: "memory")
; #define PG8_BAR __builtin_amdgcn_s_barrier()
; #define PG8_SCHED __builtin_amdgcn_sched_barrier(0)
; template <class Epi>
; __device__ __forceinline__ void gemm_phase(LAS unsigned char* lds, const Gemm g, const StaticOrder& S, const Epi& E) {
;     ...
;             PG8_STAGE(PG8_SB(0, 1), b2 + hstepB, voffB);
;             PG8_WAIT_V(6); PG8_BAR; PG8_MMA(1, 1, At, B1); PG8_BAR;
;             PG8_LDB(B0, 1, 0); PG8_SCHED; PG8_LDA(At, 1, 0); PG8_STAGE(PG8_SA(0, 1), a2 + hstepA, voffA);
;             PG8_WAIT_L(8); PG8_BAR; PG8_WAIT_L(0); PG8_MMA(0, 0, At, B0); PG8_BAR; PG8_SCHED;
;             PG8_LDB(B1, 1, 1); PG8_STAGE(PG8_SB(1, 0), b3, voffB);
;             PG8_BAR; PG8_WAIT_L(0); PG8_MMA(0, 1, At, B1); PG8_BAR;
;             PG8_LDA(At, 1, 1); PG8_STAGE(PG8_SA(1, 0), a3, voffA);
;             PG8_BAR; PG8_WAIT_L(0); PG8_MMA(1, 0, At, B0); PG8_BAR; PG8_SCHED;
	s_add_u32 s48, s22, 0x40000
	s_addc_u32 s49, s23, 0
	s_add_i32 s47, s41, s29
	v_lshl_add_u64 v[128:129], s[48:49], 0, v[156:157]
	s_mov_b32 m0, s47
	s_nop 0
	global_load_lds_dwordx4 v[128:129], off
	v_lshl_add_u64 v[128:129], s[48:49], 0, v[160:161]
	s_add_i32 m0, s47, 0x2000
	s_nop 0
	global_load_lds_dwordx4 v[128:129], off
	s_waitcnt vmcnt(6)
	s_barrier
	s_setprio 1
	v_mfma_f32_16x16x32_bf16 v[52:55], v[202:205], v[144:147], v[52:55]
	v_mfma_f32_16x16x32_bf16 v[48:51], v[210:213], v[144:147], v[48:51]
	v_mfma_f32_16x16x32_bf16 v[36:39], v[202:205], v[170:173], v[36:39]
	v_mfma_f32_16x16x32_bf16 v[32:35], v[210:213], v[170:173], v[32:35]
	v_mfma_f32_16x16x32_bf16 v[20:23], v[202:205], v[178:181], v[20:23]
	v_mfma_f32_16x16x32_bf16 v[16:19], v[210:213], v[178:181], v[16:19]
	v_mfma_f32_16x16x32_bf16 v[4:7], v[202:205], v[194:197], v[4:7]
	v_mfma_f32_16x16x32_bf16 v[0:3], v[210:213], v[194:197], v[0:3]
	v_mfma_f32_16x16x32_bf16 v[52:55], v[206:209], v[148:151], v[52:55]
	v_mfma_f32_16x16x32_bf16 v[48:51], v[214:217], v[148:151], v[48:51]
	v_mfma_f32_16x16x32_bf16 v[36:39], v[206:209], v[174:177], v[36:39]
	v_mfma_f32_16x16x32_bf16 v[32:35], v[214:217], v[174:177], v[32:35]
	v_mfma_f32_16x16x32_bf16 v[20:23], v[206:209], v[182:185], v[20:23]
	v_mfma_f32_16x16x32_bf16 v[16:19], v[214:217], v[182:185], v[16:19]
	v_mfma_f32_16x16x32_bf16 v[4:7], v[206:209], v[198:201], v[4:7]
	v_mfma_f32_16x16x32_bf16 v[0:3], v[214:217], v[198:201], v[0:3]
	s_setprio 0
	s_add_i32 s47, 0, 0x18000
	v_add_u32_e32 v140, s47, v188
	s_barrier
	ds_read_b128 v[128:131], v140
	ds_read_b128 v[132:135], v140 offset:1024
	ds_read_b128 v[136:139], v140 offset:2048
	ds_read_b128 v[140:143], v140 offset:3072
	s_add_u32 s24, s24, 0x140000
	s_addc_u32 s25, s25, 0
	s_mov_b32 m0, s31
	v_lshl_add_u64 v[202:203], s[24:25], 0, v[154:155]
	ds_read_b128 v[144:147], v191 offset:32768
	ds_read_b128 v[148:151], v191 offset:33792
	ds_read_b128 v[170:173], v191 offset:34816
	ds_read_b128 v[174:177], v191 offset:35840
	ds_read_b128 v[178:181], v191 offset:36864
	ds_read_b128 v[182:185], v191 offset:37888
	ds_read_b128 v[194:197], v191 offset:38912
	ds_read_b128 v[198:201], v191 offset:39936
	global_load_lds_dwordx4 v[202:203], off
	v_lshl_add_u64 v[202:203], s[24:25], 0, v[158:159]
	s_mov_b32 m0, s34
	s_nop 0
	global_load_lds_dwordx4 v[202:203], off
	s_waitcnt lgkmcnt(8)
	s_barrier
	s_waitcnt lgkmcnt(0)
	s_setprio 1
	s_waitcnt lgkmcnt(0)
	v_mfma_f32_16x16x32_bf16 v[124:127], v[128:131], v[144:147], v[124:127]
	v_mfma_f32_16x16x32_bf16 v[120:123], v[136:139], v[144:147], v[120:123]
	v_mfma_f32_16x16x32_bf16 v[108:111], v[128:131], v[170:173], v[108:111]
	v_mfma_f32_16x16x32_bf16 v[104:107], v[136:139], v[170:173], v[104:107]
	v_mfma_f32_16x16x32_bf16 v[92:95], v[128:131], v[178:181], v[92:95]
	v_mfma_f32_16x16x32_bf16 v[88:91], v[136:139], v[178:181], v[88:91]
	v_mfma_f32_16x16x32_bf16 v[76:79], v[128:131], v[194:197], v[76:79]
	v_mfma_f32_16x16x32_bf16 v[72:75], v[136:139], v[194:197], v[72:75]
	v_mfma_f32_16x16x32_bf16 v[124:127], v[132:135], v[148:151], v[124:127]
	v_mfma_f32_16x16x32_bf16 v[120:123], v[140:143], v[148:151], v[120:123]
	v_mfma_f32_16x16x32_bf16 v[108:111], v[132:135], v[174:177], v[108:111]
	v_mfma_f32_16x16x32_bf16 v[104:107], v[140:143], v[174:177], v[104:107]
	v_mfma_f32_16x16x32_bf16 v[92:95], v[132:135], v[182:185], v[92:95]
	v_mfma_f32_16x16x32_bf16 v[88:91], v[140:143], v[182:185], v[88:91]
	v_mfma_f32_16x16x32_bf16 v[76:79], v[132:135], v[198:201], v[76:79]
	v_mfma_f32_16x16x32_bf16 v[72:75], v[140:143], v[198:201], v[72:75]
	s_setprio 0
	s_barrier
	s_add_i32 s24, 0, 0x1c000
	s_add_i32 s25, s47, s29
	v_add_u32_e32 v214, s24, v188
	v_lshl_add_u64 v[186:187], v[186:187], 0, s[14:15]
	s_mov_b32 m0, s25
	ds_read_b128 v[202:205], v214
	ds_read_b128 v[206:209], v214 offset:1024
	ds_read_b128 v[210:213], v214 offset:2048
	ds_read_b128 v[214:217], v214 offset:3072
	global_load_lds_dwordx4 v[186:187], off
	v_lshl_add_u64 v[186:187], v[218:219], 0, s[14:15]
	s_add_i32 m0, s25, 0x2000
	s_nop 0
	global_load_lds_dwordx4 v[186:187], off
	s_barrier
	s_waitcnt lgkmcnt(0)
	s_setprio 1
	s_waitcnt lgkmcnt(0)
	v_mfma_f32_16x16x32_bf16 v[116:119], v[202:205], v[144:147], v[116:119]
	v_mfma_f32_16x16x32_bf16 v[112:115], v[210:213], v[144:147], v[112:115]
	v_mfma_f32_16x16x32_bf16 v[100:103], v[202:205], v[170:173], v[100:103]
	v_mfma_f32_16x16x32_bf16 v[96:99], v[210:213], v[170:173], v[96:99]
	v_mfma_f32_16x16x32_bf16 v[84:87], v[202:205], v[178:181], v[84:87]
	v_mfma_f32_16x16x32_bf16 v[80:83], v[210:213], v[178:181], v[80:83]
	v_mfma_f32_16x16x32_bf16 v[68:71], v[202:205], v[194:197], v[68:71]
	v_mfma_f32_16x16x32_bf16 v[64:67], v[210:213], v[194:197], v[64:67]
	v_mfma_f32_16x16x32_bf16 v[116:119], v[206:209], v[148:151], v[116:119]
	v_mfma_f32_16x16x32_bf16 v[112:115], v[214:217], v[148:151], v[112:115]
	v_mfma_f32_16x16x32_bf16 v[100:103], v[206:209], v[174:177], v[100:103]
	v_mfma_f32_16x16x32_bf16 v[96:99], v[214:217], v[174:177], v[96:99]
	v_mfma_f32_16x16x32_bf16 v[84:87], v[206:209], v[182:185], v[84:87]
	v_mfma_f32_16x16x32_bf16 v[80:83], v[214:217], v[182:185], v[80:83]
	v_mfma_f32_16x16x32_bf16 v[68:71], v[206:209], v[198:201], v[68:71]
	v_mfma_f32_16x16x32_bf16 v[64:67], v[214:217], v[198:201], v[64:67]
	s_setprio 0
	s_mov_b32 m0, s36
	v_lshl_add_u64 v[186:187], v[220:221], 0, s[14:15]
	s_barrier
	ds_read_b128 v[144:147], v191 offset:49152
	ds_read_b128 v[148:151], v191 offset:50176
	ds_read_b128 v[170:173], v191 offset:51200
	ds_read_b128 v[174:177], v191 offset:52224
	ds_read_b128 v[178:181], v191 offset:53248
	ds_read_b128 v[182:185], v191 offset:54272
	ds_read_b128 v[194:197], v191 offset:55296
	ds_read_b128 v[198:201], v191 offset:56320
	global_load_lds_dwordx4 v[186:187], off
	v_lshl_add_u64 v[186:187], v[222:223], 0, s[14:15]
	s_mov_b32 m0, s37
	s_nop 0
	global_load_lds_dwordx4 v[186:187], off
	s_barrier
; __device__ __forceinline__ void unpack8(const u32x4 v, float* f) { f[0] = bf_lo(v.x); f[1] = bf_hi(v.x); f[2] = bf_lo(v.y); f[3] = bf_hi(v.y); f[4] = bf_lo(v.z); f[5] = bf_hi(v.z); f[6] = bf_lo(v.w); f[7] = bf_hi(v.w); }
; #define PG8_STAGE(bufoff, gbase, voff) do { _Pragma("unroll") for (int _i = 0; _i < 2; ++_i) \
;         __builtin_amdgcn_global_load_lds((const unsigned*)((const char*)(gbase) + (voff)[_i]), (LAS unsigned*)(lds + (bufoff) + ldsw + _i * 8192), 16, 0, 0); } while (0)
; #define PG8_MMA(ai, bj, At, Bt) do { __builtin_amdgcn_s_setprio(1); _Pragma("unroll") for (int m = 0; m < 4; ++m) _Pragma("unroll") for (int n = 0; n < 2; ++n) _Pragma("unroll") for (int k = 0; k < 2; ++k) \
;         acc[ai][bj][m][n] = __builtin_amdgcn_mfma_f32_16x16x32_bf16(Bt[n][k], At[m][k], acc[ai][bj][m][n], 0, 0, 0); __builtin_amdgcn_s_setprio(0); } while (0)
; #define PG8_WAIT_V(n) asm volatile("s_waitcnt vmcnt(" #n ")" ::: "memory")
; #define PG8_WAIT_L(n) asm volatile("s_waitcnt lgkmcnt(" #n ")" ::: "memory")
;     __device__ __forceinline__ void operator()(const f32x4 (&acc)[2][2][4][2], const Unit& u, int wr, int wc, int fr, int fq, const float (&)[8]) const {
;         const int row0 = u.pm * BM + wr * 64 + fr, col0 = u.pn * BM + wc * 32 + 8 * fq;
; #pragma unroll
;         for (int ai = 0; ai < 2; ++ai) {
;             u32x4 bv[4][2];
; #pragma unroll
;             for (int m = 0; m < 4; ++m)
; #pragma unroll
;                 for (int bj = 0; bj < 2; ++bj) bv[m][bj] = *(const u32x4*)(xb + (size_t)(row0 + ai * HALF + m * 16) * DM + col0 + bj * HALF);
; #pragma unroll
;             for (int m = 0; m < 4; ++m) { const int row = row0 + ai * HALF + m * 16; const size_t ro = (size_t)row * DM + col0; float s = 0.f;
; #pragma unroll
;                 for (int bj = 0; bj < 2; ++bj) { float b8[8]; unpack8(bv[m][bj], b8);
;                     const f32x4 v0 = (f32x4){b8[0], b8[1], b8[2], b8[3]} + acc[ai][bj][m][0], v1 = (f32x4){b8[4], b8[5], b8[6], b8[7]} + acc[ai][bj][m][1];
; template <class Epi>
; __device__ __forceinline__ void gemm_phase(LAS unsigned char* lds, const Gemm g, const StaticOrder& S, const Epi& E) {
;     ...
;             PG8_BAR; PG8_WAIT_L(0); PG8_MMA(1, 0, At, B0); PG8_BAR; PG8_SCHED;
;             PG8_STAGE(PG8_SB(1, 1), b3 + hstepB, voffB);
;             PG8_WAIT_V(6); PG8_BAR; PG8_MMA(1, 1, At, B1); PG8_BAR;
	s_waitcnt lgkmcnt(0)
	s_setprio 1
	s_waitcnt lgkmcnt(0)
	v_mfma_f32_16x16x32_bf16 v[60:63], v[128:131], v[144:147], v[60:63]
	v_mfma_f32_16x16x32_bf16 v[56:59], v[136:139], v[144:147], v[56:59]
	v_mfma_f32_16x16x32_bf16 v[44:47], v[128:131], v[170:173], v[44:47]
	v_mfma_f32_16x16x32_bf16 v[40:43], v[136:139], v[170:173], v[40:43]
	v_mfma_f32_16x16x32_bf16 v[28:31], v[128:131], v[178:181], v[28:31]
	v_mfma_f32_16x16x32_bf16 v[24:27], v[136:139], v[178:181], v[24:27]
	v_mfma_f32_16x16x32_bf16 v[12:15], v[128:131], v[194:197], v[12:15]
	v_mfma_f32_16x16x32_bf16 v[8:11], v[136:139], v[194:197], v[8:11]
	v_mfma_f32_16x16x32_bf16 v[60:63], v[132:135], v[148:151], v[60:63]
	v_mfma_f32_16x16x32_bf16 v[56:59], v[140:143], v[148:151], v[56:59]
	v_mfma_f32_16x16x32_bf16 v[44:47], v[132:135], v[174:177], v[44:47]
	v_mfma_f32_16x16x32_bf16 v[40:43], v[140:143], v[174:177], v[40:43]
	v_mfma_f32_16x16x32_bf16 v[28:31], v[132:135], v[182:185], v[28:31]
	v_mfma_f32_16x16x32_bf16 v[24:27], v[140:143], v[182:185], v[24:27]
	v_mfma_f32_16x16x32_bf16 v[12:15], v[132:135], v[198:201], v[12:15]
	v_mfma_f32_16x16x32_bf16 v[8:11], v[140:143], v[198:201], v[8:11]
	s_setprio 0
	s_barrier
	s_add_u32 s22, s22, 0x40080
	s_addc_u32 s23, s23, 0
	s_add_i32 s24, s24, s29
	v_lshl_add_u64 v[128:129], s[22:23], 0, v[156:157]
	s_mov_b32 m0, s24
	s_nop 0
	global_load_lds_dwordx4 v[128:129], off
	v_lshl_add_u64 v[128:129], s[22:23], 0, v[160:161]
	s_add_i32 m0, s24, 0x2000
	s_nop 0
	global_load_lds_dwordx4 v[128:129], off
	s_waitcnt vmcnt(6)
	s_barrier
	s_setprio 1
	v_mfma_f32_16x16x32_bf16 v[52:55], v[202:205], v[144:147], v[52:55]
	v_mfma_f32_16x16x32_bf16 v[48:51], v[210:213], v[144:147], v[48:51]
	v_mfma_f32_16x16x32_bf16 v[36:39], v[202:205], v[170:173], v[36:39]
	v_mfma_f32_16x16x32_bf16 v[32:35], v[210:213], v[170:173], v[32:35]
	v_mfma_f32_16x16x32_bf16 v[20:23], v[202:205], v[178:181], v[20:23]
	v_mfma_f32_16x16x32_bf16 v[16:19], v[210:213], v[178:181], v[16:19]
	v_mfma_f32_16x16x32_bf16 v[4:7], v[202:205], v[194:197], v[4:7]
	v_mfma_f32_16x16x32_bf16 v[0:3], v[210:213], v[194:197], v[0:3]
	v_mfma_f32_16x16x32_bf16 v[52:55], v[206:209], v[148:151], v[52:55]
	v_mfma_f32_16x16x32_bf16 v[48:51], v[214:217], v[148:151], v[48:51]
	v_mfma_f32_16x16x32_bf16 v[36:39], v[206:209], v[174:177], v[36:39]
	v_mfma_f32_16x16x32_bf16 v[32:35], v[214:217], v[174:177], v[32:35]
	v_mfma_f32_16x16x32_bf16 v[20:23], v[206:209], v[182:185], v[20:23]
	v_mfma_f32_16x16x32_bf16 v[16:19], v[214:217], v[182:185], v[16:19]
	v_mfma_f32_16x16x32_bf16 v[4:7], v[206:209], v[198:201], v[4:7]
	v_mfma_f32_16x16x32_bf16 v[0:3], v[214:217], v[198:201], v[0:3]
	s_setprio 0
	s_add_i32 s46, s46, 2
	s_add_u32 s4, s4, 0x100
	s_addc_u32 s5, s5, 0
	s_add_u32 s44, s44, 0x100
	s_addc_u32 s45, s45, 0
	s_cmp_gt_u32 s46, 13
	s_barrier
	s_cbranch_scc0 .LBB0_1118
	v_lshl_or_b32 v170, s8, 8, v189
	v_lshl_add_u32 v172, s10, 8, v153
	v_ashrrev_i32_e32 v171, 31, v170
	v_lshlrev_b64 v[204:205], 1, v[170:171]
	v_ashrrev_i32_e32 v173, 31, v172
	v_lshl_add_u64 v[174:175], s[76:77], 0, v[204:205]
	v_lshlrev_b64 v[206:207], 11, v[172:173]
	v_lshl_add_u64 v[128:129], v[174:175], 0, v[206:207]
	global_load_dwordx4 v[196:199], v[128:129], off
	global_load_dwordx4 v[200:203], v[128:129], off offset:256
	v_or_b32_e32 v184, 16, v172
	v_or_b32_e32 v180, 32, v172
	v_or_b32_e32 v176, 48, v172
	v_ashrrev_i32_e32 v185, 31, v184
	v_ashrrev_i32_e32 v181, 31, v180
	v_ashrrev_i32_e32 v177, 31, v176
	v_lshlrev_b64 v[186:187], 11, v[184:185]
	v_lshlrev_b64 v[182:183], 11, v[180:181]
	v_lshlrev_b64 v[178:179], 11, v[176:177]
	v_lshl_add_u64 v[128:129], v[174:175], 0, v[186:187]
	v_lshl_add_u64 v[130:131], v[174:175], 0, v[182:183]
	v_lshl_add_u64 v[194:195], v[174:175], 0, v[178:179]
	global_load_dwordx4 v[148:151], v[128:129], off
	global_load_dwordx4 v[144:147], v[128:129], off offset:256
	global_load_dwordx4 v[140:143], v[130:131], off
	global_load_dwordx4 v[136:139], v[130:131], off offset:256
	global_load_dwordx4 v[132:135], v[194:195], off
	s_nop 0
	global_load_dwordx4 v[128:131], v[194:195], off offset:256
	v_add_u32_e32 v226, 0x80, v172
	v_ashrrev_i32_e32 v227, 31, v226
	v_lshlrev_b64 v[226:227], 11, v[226:227]
	v_lshl_add_u64 v[226:227], v[174:175], 0, v[226:227]
	global_load_dwordx4 v[216:219], v[226:227], off
	global_load_dwordx4 v[220:223], v[226:227], off offset:256
	v_add_u32_e32 v226, 0x90, v172
	v_ashrrev_i32_e32 v227, 31, v226
	v_lshlrev_b64 v[226:227], 11, v[226:227]
	v_lshl_add_u64 v[226:227], v[174:175], 0, v[226:227]
	global_load_dwordx4 v[228:231], v[226:227], off
	global_load_dwordx4 v[232:235], v[226:227], off offset:256
	v_add_u32_e32 v226, 0xa0, v172
	v_ashrrev_i32_e32 v227, 31, v226
	v_lshlrev_b64 v[226:227], 11, v[226:227]
	v_lshl_add_u64 v[226:227], v[174:175], 0, v[226:227]
	global_load_dwordx4 v[236:239], v[226:227], off
	global_load_dwordx4 v[240:243], v[226:227], off offset:256
	v_add_u32_e32 v226, 0xb0, v172
	v_ashrrev_i32_e32 v227, 31, v226
	v_lshlrev_b64 v[226:227], 11, v[226:227]
	v_lshl_add_u64 v[226:227], v[174:175], 0, v[226:227]
	global_load_dwordx4 v[244:247], v[226:227], off
	global_load_dwordx4 v[252:255], v[226:227], off offset:256
	v_and_b32_e32 v195, 64, v193
	v_xor_b32_e32 v194, 16, v193
	v_add_u32_e32 v195, 64, v195
	v_xor_b32_e32 v208, 32, v193
	v_cmp_lt_i32_e32 vcc, v194, v195
	s_waitcnt vmcnt(15)
	v_and_b32_e32 v209, 0xffff0000, v196
	v_cndmask_b32_e32 v194, v193, v194, vcc
	v_cmp_lt_i32_e32 vcc, v208, v195
	v_lshlrev_b32_e32 v195, 2, v194
	s_waitcnt vmcnt(14)
; __device__ __forceinline__ unsigned pk2(float lo, float hi) { const f32x2 v = (f32x2){lo, hi}; const bf16x2_t b = __builtin_convertvector(v, bf16x2_t); return __builtin_bit_cast(unsigned, b); }
; __device__ __forceinline__ void unpack8(const u32x4 v, float* f) { f[0] = bf_lo(v.x); f[1] = bf_hi(v.x); f[2] = bf_lo(v.y); f[3] = bf_hi(v.y); f[4] = bf_lo(v.z); f[5] = bf_hi(v.z); f[6] = bf_lo(v.w); f[7] = bf_hi(v.w); }
;     __device__ __forceinline__ void operator()(const f32x4 (&acc)[2][2][4][2], const Unit& u, int wr, int wc, int fr, int fq, const float (&)[8]) const {
;     ...
;             for (int m = 0; m < 4; ++m) { const int row = row0 + ai * HALF + m * 16; const size_t ro = (size_t)row * DM + col0; float s = 0.f;
; #pragma unroll
;                 for (int bj = 0; bj < 2; ++bj) { float b8[8]; unpack8(bv[m][bj], b8);
;                     const f32x4 v0 = (f32x4){b8[0], b8[1], b8[2], b8[3]} + acc[ai][bj][m][0], v1 = (f32x4){b8[4], b8[5], b8[6], b8[7]} + acc[ai][bj][m][1];
;                     s += v0[0] * v0[0] + v0[1] * v0[1] + v0[2] * v0[2] + v0[3] * v0[3] + v1[0] * v1[0] + v1[1] * v1[1] + v1[2] * v1[2] + v1[3] * v1[3];
;                     if (LAST) { *(f32x4*)(out + ro + bj * HALF) = v0; *(f32x4*)(out + ro + bj * HALF + 4) = v1; }
;                     else { u32x4 w; w.x = pk2(v0[0], v0[1]); w.y = pk2(v0[2], v0[3]); w.z = pk2(v1[0], v1[1]); w.w = pk2(v1[2], v1[3]); *(u32x4*)(xb + ro + bj * HALF) = w; } }
;                 s += __shfl_xor(s, 16); s += __shfl_xor(s, 32);
;                 if (fq == 0) ss[(size_t)row * 16 + u.pn * 4 + wc] = s; }
	v_lshlrev_b32_e32 v212, 16, v200
	v_cndmask_b32_e32 v208, v193, v208, vcc
	v_lshlrev_b32_e32 v194, 2, v208
	v_lshlrev_b32_e32 v208, 16, v196
	v_and_b32_e32 v213, 0xffff0000, v200
	v_lshlrev_b32_e32 v210, 16, v198
	v_and_b32_e32 v211, 0xffff0000, v198
	v_lshlrev_b32_e32 v198, 16, v199
	v_and_b32_e32 v199, 0xffff0000, v199
	v_lshlrev_b32_e32 v200, 16, v201
	v_and_b32_e32 v201, 0xffff0000, v201
	v_lshlrev_b32_e32 v214, 16, v202
	v_and_b32_e32 v215, 0xffff0000, v202
	v_pk_add_f32 v[124:125], v[124:125], v[208:209]
	v_pk_add_f32 v[116:117], v[116:117], v[212:213]
	v_lshlrev_b32_e32 v196, 16, v197
	v_and_b32_e32 v197, 0xffff0000, v197
	v_pk_add_f32 v[122:123], v[122:123], v[198:199]
	v_pk_add_f32 v[118:119], v[118:119], v[200:201]
	v_pk_add_f32 v[198:199], v[112:113], v[214:215]
	v_mul_f32_e32 v200, v125, v125
	v_cvt_pk_bf16_f32 v112, v124, v125
	v_mul_f32_e32 v125, v117, v117
	v_pk_add_f32 v[126:127], v[126:127], v[196:197]
	v_fmac_f32_e32 v200, v124, v124
	v_fmac_f32_e32 v125, v116, v116
	v_fmac_f32_e32 v200, v126, v126
	v_fmac_f32_e32 v125, v118, v118
	v_pk_add_f32 v[120:121], v[120:121], v[210:211]
	v_fmac_f32_e32 v200, v127, v127
	v_fmac_f32_e32 v125, v119, v119
	v_lshlrev_b32_e32 v202, 16, v203
	v_and_b32_e32 v203, 0xffff0000, v203
	v_fmac_f32_e32 v200, v120, v120
	v_fmac_f32_e32 v125, v198, v198
	v_pk_add_f32 v[196:197], v[114:115], v[202:203]
	v_fmac_f32_e32 v200, v121, v121
	v_fmac_f32_e32 v125, v199, v199
	v_fmac_f32_e32 v200, v122, v122
	v_fmac_f32_e32 v125, v196, v196
	v_fmac_f32_e32 v200, v123, v123
	v_fmac_f32_e32 v125, v197, v197
	v_cvt_pk_bf16_f32 v115, v122, v123
	v_add_f32_e32 v122, v200, v125
	ds_bpermute_b32 v123, v195, v122
	v_cvt_pk_bf16_f32 v114, v120, v121
	v_lshl_add_u64 v[120:121], s[76:77], 0, v[206:207]
	v_cvt_pk_bf16_f32 v113, v126, v127
	v_lshl_add_u64 v[120:121], v[120:121], 0, v[204:205]
	global_store_dwordx4 v[120:121], v[112:115], off
	s_waitcnt lgkmcnt(0)
	s_nop 0
	v_add_f32_e32 v112, v122, v123
	ds_bpermute_b32 v113, v194, v112
	v_cvt_pk_bf16_f32 v114, v116, v117
	v_cvt_pk_bf16_f32 v115, v118, v119
	v_cvt_pk_bf16_f32 v116, v198, v199
	v_cvt_pk_bf16_f32 v117, v196, v197
	global_store_dwordx4 v[120:121], v[114:117], off offset:256
	s_and_saveexec_b64 s[4:5], s[0:1]
	s_cbranch_execz .LBB0_1121
	s_waitcnt lgkmcnt(0)
	v_add_f32_e32 v114, v112, v113
	s_lshl_b32 s22, s8, 2
	v_lshlrev_b64 v[112:113], 6, v[172:173]
	s_ashr_i32 s23, s22, 31
	v_lshl_add_u64 v[112:113], s[12:13], 0, v[112:113]
	v_lshl_add_u64 v[112:113], s[22:23], 2, v[112:113]
	s_lshl_b32 s10, s35, 2
	v_lshl_add_u64 v[112:113], v[112:113], 0, s[10:11]
	global_store_dword v[112:113], v114, off
.LBB0_1121:
	s_or_b64 exec, exec, s[4:5]
	s_waitcnt vmcnt(15)
	v_lshlrev_b32_e32 v112, 16, v148
	s_waitcnt lgkmcnt(0)
	v_and_b32_e32 v113, 0xffff0000, v148
	v_lshlrev_b32_e32 v116, 16, v150
	v_and_b32_e32 v117, 0xffff0000, v150
	v_lshlrev_b32_e32 v118, 16, v151
	v_and_b32_e32 v119, 0xffff0000, v151
	v_pk_add_f32 v[108:109], v[108:109], v[112:113]
	v_lshlrev_b32_e32 v114, 16, v149
	v_and_b32_e32 v115, 0xffff0000, v149
	v_pk_add_f32 v[112:113], v[106:107], v[118:119]
	v_pk_add_f32 v[106:107], v[104:105], v[116:117]
	v_mul_f32_e32 v116, v109, v109
	v_pk_add_f32 v[110:111], v[110:111], v[114:115]
	v_fmac_f32_e32 v116, v108, v108
	v_fmac_f32_e32 v116, v110, v110
	v_fmac_f32_e32 v116, v111, v111
	v_fmac_f32_e32 v116, v106, v106
	v_fmac_f32_e32 v116, v107, v107
	v_fmac_f32_e32 v116, v112, v112
	v_cvt_pk_bf16_f32 v104, v108, v109
	s_waitcnt vmcnt(14)
	v_lshlrev_b32_e32 v108, 16, v144
	v_and_b32_e32 v109, 0xffff0000, v144
	v_fmac_f32_e32 v116, v113, v113
	v_cvt_pk_bf16_f32 v105, v110, v111
	v_cvt_pk_bf16_f32 v106, v106, v107
	v_cvt_pk_bf16_f32 v107, v112, v113
	v_lshlrev_b32_e32 v110, 16, v145
	v_and_b32_e32 v111, 0xffff0000, v145
	v_lshlrev_b32_e32 v112, 16, v146
	v_and_b32_e32 v113, 0xffff0000, v146
	v_pk_add_f32 v[100:101], v[100:101], v[108:109]
	v_pk_add_f32 v[102:103], v[102:103], v[110:111]
	v_pk_add_f32 v[110:111], v[96:97], v[112:113]
	v_mul_f32_e32 v96, v101, v101
	v_fmac_f32_e32 v96, v100, v100
	v_fmac_f32_e32 v96, v102, v102
	v_fmac_f32_e32 v96, v103, v103
	v_lshlrev_b32_e32 v114, 16, v147
	v_and_b32_e32 v115, 0xffff0000, v147
	v_fmac_f32_e32 v96, v110, v110
	v_pk_add_f32 v[108:109], v[98:99], v[114:115]
	v_fmac_f32_e32 v96, v111, v111
	v_fmac_f32_e32 v96, v108, v108
	v_fmac_f32_e32 v96, v109, v109
	v_add_f32_e32 v99, v116, v96
	ds_bpermute_b32 v114, v195, v99
	v_lshl_add_u64 v[96:97], s[76:77], 0, v[186:187]
	v_lshl_add_u64 v[112:113], v[170:171], 1, v[96:97]
	v_cvt_pk_bf16_f32 v98, v100, v101
	v_cvt_pk_bf16_f32 v100, v110, v111
	s_waitcnt lgkmcnt(0)
	v_add_f32_e32 v96, v99, v114
	ds_bpermute_b32 v97, v194, v96
	v_cvt_pk_bf16_f32 v99, v102, v103
	v_cvt_pk_bf16_f32 v101, v108, v109
	global_store_dwordx4 v[112:113], v[104:107], off
	global_store_dwordx4 v[112:113], v[98:101], off offset:256
	s_and_saveexec_b64 s[4:5], s[0:1]
	s_cbranch_execz .LBB0_1123
	s_waitcnt lgkmcnt(0)
	v_add_f32_e32 v98, v96, v97
	s_lshl_b32 s22, s8, 2
	v_lshlrev_b64 v[96:97], 6, v[184:185]
	s_ashr_i32 s23, s22, 31
	v_lshl_add_u64 v[96:97], s[12:13], 0, v[96:97]
	v_lshl_add_u64 v[96:97], s[22:23], 2, v[96:97]
	s_lshl_b32 s10, s35, 2
	v_lshl_add_u64 v[96:97], v[96:97], 0, s[10:11]
	global_store_dword v[96:97], v98, off
; __device__ __forceinline__ unsigned pk2(float lo, float hi) { const f32x2 v = (f32x2){lo, hi}; const bf16x2_t b = __builtin_convertvector(v, bf16x2_t); return __builtin_bit_cast(unsigned, b); }
; __device__ __forceinline__ void unpack8(const u32x4 v, float* f) { f[0] = bf_lo(v.x); f[1] = bf_hi(v.x); f[2] = bf_lo(v.y); f[3] = bf_hi(v.y); f[4] = bf_lo(v.z); f[5] = bf_hi(v.z); f[6] = bf_lo(v.w); f[7] = bf_hi(v.w); }
;     __device__ __forceinline__ void operator()(const f32x4 (&acc)[2][2][4][2], const Unit& u, int wr, int wc, int fr, int fq, const float (&)[8]) const {
;     ...
;             for (int m = 0; m < 4; ++m) { const int row = row0 + ai * HALF + m * 16; const size_t ro = (size_t)row * DM + col0; float s = 0.f;
; #pragma unroll
;                 for (int bj = 0; bj < 2; ++bj) { float b8[8]; unpack8(bv[m][bj], b8);
;                     const f32x4 v0 = (f32x4){b8[0], b8[1], b8[2], b8[3]} + acc[ai][bj][m][0], v1 = (f32x4){b8[4], b8[5], b8[6], b8[7]} + acc[ai][bj][m][1];
;                     s += v0[0] * v0[0] + v0[1] * v0[1] + v0[2] * v0[2] + v0[3] * v0[3] + v1[0] * v1[0] + v1[1] * v1[1] + v1[2] * v1[2] + v1[3] * v1[3];
;                     if (LAST) { *(f32x4*)(out + ro + bj * HALF) = v0; *(f32x4*)(out + ro + bj * HALF + 4) = v1; }
;                     else { u32x4 w; w.x = pk2(v0[0], v0[1]); w.y = pk2(v0[2], v0[3]); w.z = pk2(v1[0], v1[1]); w.w = pk2(v1[2], v1[3]); *(u32x4*)(xb + ro + bj * HALF) = w; } }
;                 s += __shfl_xor(s, 16); s += __shfl_xor(s, 32);
;                 if (fq == 0) ss[(size_t)row * 16 + u.pn * 4 + wc] = s; }
.LBB0_1123:
	s_or_b64 exec, exec, s[4:5]
	s_waitcnt vmcnt(15)
	v_lshlrev_b32_e32 v96, 16, v140
	s_waitcnt lgkmcnt(0)
	v_and_b32_e32 v97, 0xffff0000, v140
	v_lshlrev_b32_e32 v100, 16, v142
	v_and_b32_e32 v101, 0xffff0000, v142
	v_lshlrev_b32_e32 v102, 16, v143
	v_and_b32_e32 v103, 0xffff0000, v143
	v_pk_add_f32 v[92:93], v[92:93], v[96:97]
	v_lshlrev_b32_e32 v98, 16, v141
	v_and_b32_e32 v99, 0xffff0000, v141
	v_pk_add_f32 v[96:97], v[90:91], v[102:103]
	v_pk_add_f32 v[90:91], v[88:89], v[100:101]
	v_mul_f32_e32 v100, v93, v93
	v_pk_add_f32 v[94:95], v[94:95], v[98:99]
	v_fmac_f32_e32 v100, v92, v92
	v_fmac_f32_e32 v100, v94, v94
	v_fmac_f32_e32 v100, v95, v95
	v_fmac_f32_e32 v100, v90, v90
	v_fmac_f32_e32 v100, v91, v91
	v_fmac_f32_e32 v100, v96, v96
	v_cvt_pk_bf16_f32 v88, v92, v93
	s_waitcnt vmcnt(14)
	v_lshlrev_b32_e32 v92, 16, v136
	v_and_b32_e32 v93, 0xffff0000, v136
	v_fmac_f32_e32 v100, v97, v97
	v_cvt_pk_bf16_f32 v89, v94, v95
	v_cvt_pk_bf16_f32 v90, v90, v91
	v_cvt_pk_bf16_f32 v91, v96, v97
	v_lshlrev_b32_e32 v94, 16, v137
	v_and_b32_e32 v95, 0xffff0000, v137
	v_lshlrev_b32_e32 v96, 16, v138
	v_and_b32_e32 v97, 0xffff0000, v138
	v_pk_add_f32 v[84:85], v[84:85], v[92:93]
	v_pk_add_f32 v[86:87], v[86:87], v[94:95]
	v_pk_add_f32 v[94:95], v[80:81], v[96:97]
	v_mul_f32_e32 v80, v85, v85
	v_fmac_f32_e32 v80, v84, v84
	v_fmac_f32_e32 v80, v86, v86
	v_fmac_f32_e32 v80, v87, v87
	v_lshlrev_b32_e32 v98, 16, v139
	v_and_b32_e32 v99, 0xffff0000, v139
	v_fmac_f32_e32 v80, v94, v94
	v_pk_add_f32 v[92:93], v[82:83], v[98:99]
	v_fmac_f32_e32 v80, v95, v95
	v_fmac_f32_e32 v80, v92, v92
	v_fmac_f32_e32 v80, v93, v93
	v_add_f32_e32 v83, v100, v80
	ds_bpermute_b32 v98, v195, v83
	v_lshl_add_u64 v[80:81], s[76:77], 0, v[182:183]
	v_lshl_add_u64 v[96:97], v[170:171], 1, v[80:81]
	v_cvt_pk_bf16_f32 v82, v84, v85
	v_cvt_pk_bf16_f32 v84, v94, v95
	s_waitcnt lgkmcnt(0)
	v_add_f32_e32 v80, v83, v98
	ds_bpermute_b32 v81, v194, v80
	v_cvt_pk_bf16_f32 v83, v86, v87
	v_cvt_pk_bf16_f32 v85, v92, v93
	global_store_dwordx4 v[96:97], v[88:91], off
	global_store_dwordx4 v[96:97], v[82:85], off offset:256
	s_and_saveexec_b64 s[4:5], s[0:1]
	s_cbranch_execz .LBB0_1125
	s_waitcnt lgkmcnt(0)
	v_add_f32_e32 v82, v80, v81
	s_lshl_b32 s22, s8, 2
	v_lshlrev_b64 v[80:81], 6, v[180:181]
	s_ashr_i32 s23, s22, 31
	v_lshl_add_u64 v[80:81], s[12:13], 0, v[80:81]
	v_lshl_add_u64 v[80:81], s[22:23], 2, v[80:81]
	s_lshl_b32 s10, s35, 2
	v_lshl_add_u64 v[80:81], v[80:81], 0, s[10:11]
	global_store_dword v[80:81], v82, off
.LBB0_1125:
	s_or_b64 exec, exec, s[4:5]
	s_waitcnt vmcnt(15)
	v_lshlrev_b32_e32 v80, 16, v132
	s_waitcnt lgkmcnt(0)
	v_and_b32_e32 v81, 0xffff0000, v132
	v_lshlrev_b32_e32 v84, 16, v134
	v_and_b32_e32 v85, 0xffff0000, v134
	v_lshlrev_b32_e32 v86, 16, v135
	v_and_b32_e32 v87, 0xffff0000, v135
	v_pk_add_f32 v[76:77], v[76:77], v[80:81]
	v_lshlrev_b32_e32 v82, 16, v133
	v_and_b32_e32 v83, 0xffff0000, v133
	v_pk_add_f32 v[80:81], v[74:75], v[86:87]
	v_pk_add_f32 v[74:75], v[72:73], v[84:85]
	v_mul_f32_e32 v84, v77, v77
	v_pk_add_f32 v[78:79], v[78:79], v[82:83]
	v_fmac_f32_e32 v84, v76, v76
	v_fmac_f32_e32 v84, v78, v78
	v_fmac_f32_e32 v84, v79, v79
	v_fmac_f32_e32 v84, v74, v74
	v_fmac_f32_e32 v84, v75, v75
	v_fmac_f32_e32 v84, v80, v80
	v_cvt_pk_bf16_f32 v72, v76, v77
	s_waitcnt vmcnt(14)
	v_lshlrev_b32_e32 v76, 16, v128
	v_and_b32_e32 v77, 0xffff0000, v128
	v_fmac_f32_e32 v84, v81, v81
	v_cvt_pk_bf16_f32 v73, v78, v79
	v_cvt_pk_bf16_f32 v74, v74, v75
	v_cvt_pk_bf16_f32 v75, v80, v81
	v_lshlrev_b32_e32 v78, 16, v129
	v_and_b32_e32 v79, 0xffff0000, v129
	v_lshlrev_b32_e32 v80, 16, v130
	v_and_b32_e32 v81, 0xffff0000, v130
	v_pk_add_f32 v[68:69], v[68:69], v[76:77]
	v_pk_add_f32 v[70:71], v[70:71], v[78:79]
	v_pk_add_f32 v[78:79], v[64:65], v[80:81]
	v_mul_f32_e32 v64, v69, v69
	v_fmac_f32_e32 v64, v68, v68
	v_fmac_f32_e32 v64, v70, v70
	v_fmac_f32_e32 v64, v71, v71
	v_lshlrev_b32_e32 v82, 16, v131
	v_and_b32_e32 v83, 0xffff0000, v131
	v_fmac_f32_e32 v64, v78, v78
	v_pk_add_f32 v[76:77], v[66:67], v[82:83]
	v_fmac_f32_e32 v64, v79, v79
	v_fmac_f32_e32 v64, v76, v76
	v_fmac_f32_e32 v64, v77, v77
	v_add_f32_e32 v67, v84, v64
	ds_bpermute_b32 v82, v195, v67
	v_lshl_add_u64 v[64:65], s[76:77], 0, v[178:179]
	v_lshl_add_u64 v[80:81], v[170:171], 1, v[64:65]
	v_cvt_pk_bf16_f32 v66, v68, v69
	v_cvt_pk_bf16_f32 v68, v78, v79
	s_waitcnt lgkmcnt(0)
	v_add_f32_e32 v64, v67, v82
	ds_bpermute_b32 v65, v194, v64
	v_cvt_pk_bf16_f32 v67, v70, v71
	v_cvt_pk_bf16_f32 v69, v76, v77
	global_store_dwordx4 v[80:81], v[72:75], off
	global_store_dwordx4 v[80:81], v[66:69], off offset:256
	s_and_saveexec_b64 s[4:5], s[0:1]
	s_cbranch_execz .LBB0_1127
	s_waitcnt lgkmcnt(0)
	v_add_f32_e32 v66, v64, v65
	s_lshl_b32 s22, s8, 2
	v_lshlrev_b64 v[64:65], 6, v[176:177]
	s_ashr_i32 s23, s22, 31
	v_lshl_add_u64 v[64:65], s[12:13], 0, v[64:65]
	v_lshl_add_u64 v[64:65], s[22:23], 2, v[64:65]
	s_lshl_b32 s10, s35, 2
	v_lshl_add_u64 v[64:65], v[64:65], 0, s[10:11]
	global_store_dword v[64:65], v66, off
; __device__ __forceinline__ unsigned pk2(float lo, float hi) { const f32x2 v = (f32x2){lo, hi}; const bf16x2_t b = __builtin_convertvector(v, bf16x2_t); return __builtin_bit_cast(unsigned, b); }
; __device__ __forceinline__ void unpack8(const u32x4 v, float* f) { f[0] = bf_lo(v.x); f[1] = bf_hi(v.x); f[2] = bf_lo(v.y); f[3] = bf_hi(v.y); f[4] = bf_lo(v.z); f[5] = bf_hi(v.z); f[6] = bf_lo(v.w); f[7] = bf_hi(v.w); }
;     __device__ __forceinline__ void operator()(const f32x4 (&acc)[2][2][4][2], const Unit& u, int wr, int wc, int fr, int fq, const float (&)[8]) const {
;     ...
;         for (int ai = 0; ai < 2; ++ai) {
;             u32x4 bv[4][2];
; #pragma unroll
;             for (int m = 0; m < 4; ++m)
; #pragma unroll
;                 for (int bj = 0; bj < 2; ++bj) bv[m][bj] = *(const u32x4*)(xb + (size_t)(row0 + ai * HALF + m * 16) * DM + col0 + bj * HALF);
; #pragma unroll
;             for (int m = 0; m < 4; ++m) { const int row = row0 + ai * HALF + m * 16; const size_t ro = (size_t)row * DM + col0; float s = 0.f;
; #pragma unroll
;                 for (int bj = 0; bj < 2; ++bj) { float b8[8]; unpack8(bv[m][bj], b8);
;                     const f32x4 v0 = (f32x4){b8[0], b8[1], b8[2], b8[3]} + acc[ai][bj][m][0], v1 = (f32x4){b8[4], b8[5], b8[6], b8[7]} + acc[ai][bj][m][1];
;                     s += v0[0] * v0[0] + v0[1] * v0[1] + v0[2] * v0[2] + v0[3] * v0[3] + v1[0] * v1[0] + v1[1] * v1[1] + v1[2] * v1[2] + v1[3] * v1[3];
;                     if (LAST) { *(f32x4*)(out + ro + bj * HALF) = v0; *(f32x4*)(out + ro + bj * HALF + 4) = v1; }
;                     else { u32x4 w; w.x = pk2(v0[0], v0[1]); w.y = pk2(v0[2], v0[3]); w.z = pk2(v1[0], v1[1]); w.w = pk2(v1[2], v1[3]); *(u32x4*)(xb + ro + bj * HALF) = w; } }
;                 s += __shfl_xor(s, 16); s += __shfl_xor(s, 32);
;                 if (fq == 0) ss[(size_t)row * 16 + u.pn * 4 + wc] = s; }
.LBB0_1127:
	s_or_b64 exec, exec, s[4:5]
	v_add_u32_e32 v100, 0x80, v172
	v_ashrrev_i32_e32 v101, 31, v100
	v_lshlrev_b64 v[110:111], 11, v[100:101]
	s_waitcnt lgkmcnt(0)
	v_lshl_add_u64 v[64:65], v[174:175], 0, v[110:111]
	s_waitcnt vmcnt(15)
	v_mov_b32_e32 v102, v216
	v_mov_b32_e32 v103, v217
	v_mov_b32_e32 v104, v218
	v_mov_b32_e32 v105, v219
	s_waitcnt vmcnt(14)
	v_mov_b32_e32 v106, v220
	v_mov_b32_e32 v107, v221
	v_mov_b32_e32 v108, v222
	v_mov_b32_e32 v109, v223
	v_add_u32_e32 v96, 0x90, v172
	v_add_u32_e32 v92, 0xa0, v172
	v_add_u32_e32 v88, 0xb0, v172
	v_ashrrev_i32_e32 v97, 31, v96
	v_ashrrev_i32_e32 v93, 31, v92
	v_ashrrev_i32_e32 v89, 31, v88
	v_lshlrev_b64 v[98:99], 11, v[96:97]
	v_lshlrev_b64 v[94:95], 11, v[92:93]
	v_lshlrev_b64 v[90:91], 11, v[88:89]
	v_lshl_add_u64 v[64:65], v[174:175], 0, v[98:99]
	v_lshl_add_u64 v[66:67], v[174:175], 0, v[94:95]
	v_lshl_add_u64 v[112:113], v[174:175], 0, v[90:91]
	s_waitcnt vmcnt(13)
	v_mov_b32_e32 v84, v228
	v_mov_b32_e32 v85, v229
	v_mov_b32_e32 v86, v230
	v_mov_b32_e32 v87, v231
	s_waitcnt vmcnt(12)
	v_mov_b32_e32 v80, v232
	v_mov_b32_e32 v81, v233
	v_mov_b32_e32 v82, v234
	v_mov_b32_e32 v83, v235
	s_waitcnt vmcnt(11)
	v_mov_b32_e32 v76, v236
	v_mov_b32_e32 v77, v237
	v_mov_b32_e32 v78, v238
	v_mov_b32_e32 v79, v239
	s_waitcnt vmcnt(10)
	v_mov_b32_e32 v72, v240
	v_mov_b32_e32 v73, v241
	v_mov_b32_e32 v74, v242
	v_mov_b32_e32 v75, v243
	s_waitcnt vmcnt(9)
	v_mov_b32_e32 v68, v244
	v_mov_b32_e32 v69, v245
	v_mov_b32_e32 v70, v246
	v_mov_b32_e32 v71, v247
	s_nop 0
	s_waitcnt vmcnt(8)
	v_mov_b32_e32 v64, v252
	v_mov_b32_e32 v65, v253
	v_mov_b32_e32 v66, v254
	v_mov_b32_e32 v67, v255
	s_nop 0
	v_lshlrev_b32_e32 v112, 16, v102
	v_and_b32_e32 v113, 0xffff0000, v102
	s_nop 0
	v_lshlrev_b32_e32 v116, 16, v106
	v_and_b32_e32 v117, 0xffff0000, v106
	v_lshlrev_b32_e32 v114, 16, v104
	v_and_b32_e32 v115, 0xffff0000, v104
	v_lshlrev_b32_e32 v104, 16, v105
	v_and_b32_e32 v105, 0xffff0000, v105
	v_lshlrev_b32_e32 v106, 16, v107
	v_and_b32_e32 v107, 0xffff0000, v107
	v_lshlrev_b32_e32 v118, 16, v108
	v_and_b32_e32 v119, 0xffff0000, v108
	v_pk_add_f32 v[60:61], v[60:61], v[112:113]
	v_pk_add_f32 v[52:53], v[52:53], v[116:117]
	v_lshlrev_b32_e32 v102, 16, v103
	v_and_b32_e32 v103, 0xffff0000, v103
	v_pk_add_f32 v[58:59], v[58:59], v[104:105]
	v_pk_add_f32 v[54:55], v[54:55], v[106:107]
	v_pk_add_f32 v[104:105], v[48:49], v[118:119]
	v_mul_f32_e32 v106, v61, v61
	v_cvt_pk_bf16_f32 v48, v60, v61
	v_mul_f32_e32 v61, v53, v53
	v_pk_add_f32 v[62:63], v[62:63], v[102:103]
	v_fmac_f32_e32 v106, v60, v60
	v_fmac_f32_e32 v61, v52, v52
	v_fmac_f32_e32 v106, v62, v62
	v_fmac_f32_e32 v61, v54, v54
	v_pk_add_f32 v[56:57], v[56:57], v[114:115]
	v_fmac_f32_e32 v106, v63, v63
	v_fmac_f32_e32 v61, v55, v55
	v_lshlrev_b32_e32 v108, 16, v109
	v_and_b32_e32 v109, 0xffff0000, v109
	v_fmac_f32_e32 v106, v56, v56
	v_fmac_f32_e32 v61, v104, v104
	v_pk_add_f32 v[102:103], v[50:51], v[108:109]
	v_fmac_f32_e32 v106, v57, v57
	v_fmac_f32_e32 v61, v105, v105
	v_fmac_f32_e32 v106, v58, v58
	v_fmac_f32_e32 v61, v102, v102
	v_fmac_f32_e32 v106, v59, v59
	v_fmac_f32_e32 v61, v103, v103
	v_cvt_pk_bf16_f32 v51, v58, v59
	v_add_f32_e32 v58, v106, v61
	ds_bpermute_b32 v59, v195, v58
	v_cvt_pk_bf16_f32 v50, v56, v57
	v_lshl_add_u64 v[56:57], s[76:77], 0, v[110:111]
	v_cvt_pk_bf16_f32 v49, v62, v63
	v_lshl_add_u64 v[56:57], v[170:171], 1, v[56:57]
	global_store_dwordx4 v[56:57], v[48:51], off
	s_waitcnt lgkmcnt(0)
	s_nop 0
	v_add_f32_e32 v48, v58, v59
	ds_bpermute_b32 v49, v194, v48
	v_cvt_pk_bf16_f32 v50, v52, v53
	v_cvt_pk_bf16_f32 v51, v54, v55
	v_cvt_pk_bf16_f32 v52, v104, v105
	v_cvt_pk_bf16_f32 v53, v102, v103
	global_store_dwordx4 v[56:57], v[50:53], off offset:256
	s_and_saveexec_b64 s[4:5], s[0:1]
	s_cbranch_execz .LBB0_1129
	s_waitcnt lgkmcnt(0)
	v_add_f32_e32 v50, v48, v49
	s_lshl_b32 s22, s8, 2
	v_lshlrev_b64 v[48:49], 6, v[100:101]
	s_ashr_i32 s23, s22, 31
	v_lshl_add_u64 v[48:49], s[12:13], 0, v[48:49]
	v_lshl_add_u64 v[48:49], s[22:23], 2, v[48:49]
	s_lshl_b32 s10, s35, 2
	v_lshl_add_u64 v[48:49], v[48:49], 0, s[10:11]
	global_store_dword v[48:49], v50, off

; #define PG8_STAGE(bufoff, gbase, voff) do { _Pragma("unroll") for (int _i = 0; _i < 2; ++_i) \
;         __builtin_amdgcn_global_load_lds((const unsigned*)((const char*)(gbase) + (voff)[_i]), (LAS unsigned*)(lds + (bufoff) + ldsw + _i * 8192), 16, 0, 0); } while (0)
; #define PG8_LDA(dst, b, h) do { _Pragma("unroll") for (int m = 0; m < 4; ++m) _Pragma("unroll") for (int k = 0; k < 2; ++k) dst[m][k] = *(const LAS bf16x8*)(lds + PG8_SA(b, h) + aoff + m * 2048 + k * 1024); } while (0)
; #define PG8_LDB(dst, b, h) do { _Pragma("unroll") for (int n = 0; n < 2; ++n) _Pragma("unroll") for (int k = 0; k < 2; ++k) dst[n][k] = *(const LAS bf16x8*)(lds + PG8_SB(b, h) + boff + n * 2048 + k * 1024); } while (0)
; #define PG8_MMA(ai, bj, At, Bt) do { __builtin_amdgcn_s_setprio(1); _Pragma("unroll") for (int m = 0; m < 4; ++m) _Pragma("unroll") for (int n = 0; n < 2; ++n) _Pragma("unroll") for (int k = 0; k < 2; ++k) \
;         acc[ai][bj][m][n] = __builtin_amdgcn_mfma_f32_16x16x32_bf16(Bt[n][k], At[m][k], acc[ai][bj][m][n], 0, 0, 0); __builtin_amdgcn_s_setprio(0); } while (0)
; #define PG8_WAIT_L(n) asm volatile("s_waitcnt lgkmcnt(" #n ")" ::: "memory")
; #define PG8_BAR __builtin_amdgcn_s_barrier()
; #define PG8_SCHED __builtin_amdgcn_sched_barrier(0)
; template <class Epi>
; __device__ __forceinline__ void gemm_phase(LAS unsigned char* lds, const Gemm g, const StaticOrder& S, const Epi& E) {
;     ...
;             PG8_LDB(B0, 0, 0); PG8_SCHED; PG8_LDA(At, 0, 0); PG8_STAGE(PG8_SA(1, 1), a1 + hstepA, voffA);
;             PG8_WAIT_L(8); PG8_BAR; PG8_WAIT_L(0); PG8_MMA(0, 0, At, B0); PG8_BAR; PG8_SCHED;
;             PG8_LDB(B1, 0, 1); PG8_STAGE(PG8_SB(0, 0), b2, voffB);
;             PG8_BAR; PG8_WAIT_L(0); PG8_MMA(0, 1, At, B1); PG8_BAR;
;             PG8_LDA(At, 0, 1); PG8_STAGE(PG8_SA(0, 0), a2, voffA);
;             PG8_BAR; PG8_WAIT_L(0); PG8_MMA(1, 0, At, B0); PG8_BAR; PG8_SCHED;
;             PG8_STAGE(PG8_SB(0, 1), b2 + hstepB, voffB);
.LBB0_1278:
	ds_read_b128 v[128:131], v190
	ds_read_b128 v[132:135], v190 offset:1024
	ds_read_b128 v[136:139], v190 offset:2048
	ds_read_b128 v[140:143], v190 offset:3072
	s_add_u32 s24, s22, 0xfff00080
	s_addc_u32 s25, s23, -1
	s_cmp_eq_u32 s48, 60
	s_cselect_b32 s27, s17, s25
	s_cselect_b32 s26, s44, s24
	s_cselect_b32 s25, s15, s47
	s_cselect_b32 s24, s45, s46
	v_lshl_add_u64 v[186:187], s[22:23], 0, v[162:163]
	s_add_i32 m0, s7, 0xc000
	ds_read_b128 v[144:147], v191
	ds_read_b128 v[148:151], v191 offset:1024
	ds_read_b128 v[170:173], v191 offset:2048
	ds_read_b128 v[174:177], v191 offset:3072
	ds_read_b128 v[178:181], v191 offset:4096
	ds_read_b128 v[182:185], v191 offset:5120
	ds_read_b128 v[194:197], v191 offset:6144
	ds_read_b128 v[198:201], v191 offset:7168
	global_load_lds_dwordx4 v[186:187], off
	v_lshl_add_u64 v[186:187], s[22:23], 0, v[164:165]
	s_add_i32 m0, s7, 0xe000
	s_nop 0
	global_load_lds_dwordx4 v[186:187], off
	s_waitcnt lgkmcnt(8)
	s_barrier
	s_waitcnt lgkmcnt(0)
	s_setprio 1
	s_waitcnt lgkmcnt(0)
	v_mfma_f32_16x16x32_bf16 v[124:127], v[128:131], v[144:147], v[124:127]
	v_mfma_f32_16x16x32_bf16 v[120:123], v[136:139], v[144:147], v[120:123]
	v_mfma_f32_16x16x32_bf16 v[108:111], v[128:131], v[170:173], v[108:111]
	v_mfma_f32_16x16x32_bf16 v[104:107], v[136:139], v[170:173], v[104:107]
	v_mfma_f32_16x16x32_bf16 v[92:95], v[128:131], v[178:181], v[92:95]
	v_mfma_f32_16x16x32_bf16 v[88:91], v[136:139], v[178:181], v[88:91]
	v_mfma_f32_16x16x32_bf16 v[76:79], v[128:131], v[194:197], v[76:79]
	v_mfma_f32_16x16x32_bf16 v[72:75], v[136:139], v[194:197], v[72:75]
	v_mfma_f32_16x16x32_bf16 v[124:127], v[132:135], v[148:151], v[124:127]
	v_mfma_f32_16x16x32_bf16 v[120:123], v[140:143], v[148:151], v[120:123]
	v_mfma_f32_16x16x32_bf16 v[108:111], v[132:135], v[174:177], v[108:111]
	v_mfma_f32_16x16x32_bf16 v[104:107], v[140:143], v[174:177], v[104:107]
	v_mfma_f32_16x16x32_bf16 v[92:95], v[132:135], v[182:185], v[92:95]
	v_mfma_f32_16x16x32_bf16 v[88:91], v[140:143], v[182:185], v[88:91]
	v_mfma_f32_16x16x32_bf16 v[76:79], v[132:135], v[198:201], v[76:79]
	v_mfma_f32_16x16x32_bf16 v[72:75], v[140:143], v[198:201], v[72:75]
	s_setprio 0
	s_barrier
	s_add_i32 s49, s42, s31
	v_lshl_add_u64 v[186:187], s[24:25], 0, v[156:157]
	s_mov_b32 m0, s49
	ds_read_b128 v[202:205], v192
	ds_read_b128 v[206:209], v192 offset:1024
	ds_read_b128 v[210:213], v192 offset:2048
	ds_read_b128 v[214:217], v192 offset:3072
	global_load_lds_dwordx4 v[186:187], off
	v_lshl_add_u64 v[218:219], s[24:25], 0, v[160:161]
	s_add_i32 m0, s49, 0x2000
	s_nop 0
	global_load_lds_dwordx4 v[218:219], off
	s_barrier
	s_waitcnt lgkmcnt(0)
	s_setprio 1
	s_waitcnt lgkmcnt(0)
	v_mfma_f32_16x16x32_bf16 v[116:119], v[202:205], v[144:147], v[116:119]
	v_mfma_f32_16x16x32_bf16 v[112:115], v[210:213], v[144:147], v[112:115]
	v_mfma_f32_16x16x32_bf16 v[100:103], v[202:205], v[170:173], v[100:103]
	v_mfma_f32_16x16x32_bf16 v[96:99], v[210:213], v[170:173], v[96:99]
	v_mfma_f32_16x16x32_bf16 v[84:87], v[202:205], v[178:181], v[84:87]
	v_mfma_f32_16x16x32_bf16 v[80:83], v[210:213], v[178:181], v[80:83]
	v_mfma_f32_16x16x32_bf16 v[68:71], v[202:205], v[194:197], v[68:71]
	v_mfma_f32_16x16x32_bf16 v[64:67], v[210:213], v[194:197], v[64:67]
	v_mfma_f32_16x16x32_bf16 v[116:119], v[206:209], v[148:151], v[116:119]
	v_mfma_f32_16x16x32_bf16 v[112:115], v[214:217], v[148:151], v[112:115]
	v_mfma_f32_16x16x32_bf16 v[100:103], v[206:209], v[174:177], v[100:103]
	v_mfma_f32_16x16x32_bf16 v[96:99], v[214:217], v[174:177], v[96:99]
	v_mfma_f32_16x16x32_bf16 v[84:87], v[206:209], v[182:185], v[84:87]
	v_mfma_f32_16x16x32_bf16 v[80:83], v[214:217], v[182:185], v[80:83]
	v_mfma_f32_16x16x32_bf16 v[68:71], v[206:209], v[198:201], v[68:71]
	v_mfma_f32_16x16x32_bf16 v[64:67], v[214:217], v[198:201], v[64:67]
	s_setprio 0
	s_mov_b32 m0, s7
	v_lshl_add_u64 v[220:221], s[26:27], 0, v[154:155]
	s_barrier
	ds_read_b128 v[144:147], v191 offset:16384
	ds_read_b128 v[148:151], v191 offset:17408
	ds_read_b128 v[170:173], v191 offset:18432
	ds_read_b128 v[174:177], v191 offset:19456
	ds_read_b128 v[178:181], v191 offset:20480
	ds_read_b128 v[182:185], v191 offset:21504
	ds_read_b128 v[194:197], v191 offset:22528
	ds_read_b128 v[198:201], v191 offset:23552
	global_load_lds_dwordx4 v[220:221], off
	v_lshl_add_u64 v[222:223], s[26:27], 0, v[158:159]
	s_mov_b32 m0, s34
	s_nop 0
	global_load_lds_dwordx4 v[222:223], off
	s_barrier
	s_waitcnt lgkmcnt(0)
	s_setprio 1
	s_waitcnt lgkmcnt(0)
	v_mfma_f32_16x16x32_bf16 v[60:63], v[128:131], v[144:147], v[60:63]
	v_mfma_f32_16x16x32_bf16 v[56:59], v[136:139], v[144:147], v[56:59]
	v_mfma_f32_16x16x32_bf16 v[44:47], v[128:131], v[170:173], v[44:47]
	v_mfma_f32_16x16x32_bf16 v[40:43], v[136:139], v[170:173], v[40:43]
	v_mfma_f32_16x16x32_bf16 v[28:31], v[128:131], v[178:181], v[28:31]
	v_mfma_f32_16x16x32_bf16 v[24:27], v[136:139], v[178:181], v[24:27]
	v_mfma_f32_16x16x32_bf16 v[12:15], v[128:131], v[194:197], v[12:15]
	v_mfma_f32_16x16x32_bf16 v[8:11], v[136:139], v[194:197], v[8:11]
	v_mfma_f32_16x16x32_bf16 v[60:63], v[132:135], v[148:151], v[60:63]
	v_mfma_f32_16x16x32_bf16 v[56:59], v[140:143], v[148:151], v[56:59]
	v_mfma_f32_16x16x32_bf16 v[44:47], v[132:135], v[174:177], v[44:47]
	v_mfma_f32_16x16x32_bf16 v[40:43], v[140:143], v[174:177], v[40:43]
	v_mfma_f32_16x16x32_bf16 v[28:31], v[132:135], v[182:185], v[28:31]
	v_mfma_f32_16x16x32_bf16 v[24:27], v[140:143], v[182:185], v[24:27]
	v_mfma_f32_16x16x32_bf16 v[12:15], v[132:135], v[198:201], v[12:15]
	v_mfma_f32_16x16x32_bf16 v[8:11], v[140:143], v[198:201], v[8:11]
	s_setprio 0
	s_barrier
; #define PG8_STAGE(bufoff, gbase, voff) do { _Pragma("unroll") for (int _i = 0; _i < 2; ++_i) \
;         __builtin_amdgcn_global_load_lds((const unsigned*)((const char*)(gbase) + (voff)[_i]), (LAS unsigned*)(lds + (bufoff) + ldsw + _i * 8192), 16, 0, 0); } while (0)
; #define PG8_LDA(dst, b, h) do { _Pragma("unroll") for (int m = 0; m < 4; ++m) _Pragma("unroll") for (int k = 0; k < 2; ++k) dst[m][k] = *(const LAS bf16x8*)(lds + PG8_SA(b, h) + aoff + m * 2048 + k * 1024); } while (0)
; #define PG8_LDB(dst, b, h) do { _Pragma("unroll") for (int n = 0; n < 2; ++n) _Pragma("unroll") for (int k = 0; k < 2; ++k) dst[n][k] = *(const LAS bf16x8*)(lds + PG8_SB(b, h) + boff + n * 2048 + k * 1024); } while (0)
; #define PG8_MMA(ai, bj, At, Bt) do { __builtin_amdgcn_s_setprio(1); _Pragma("unroll") for (int m = 0; m < 4; ++m) _Pragma("unroll") for (int n = 0; n < 2; ++n) _Pragma("unroll") for (int k = 0; k < 2; ++k) \
;         acc[ai][bj][m][n] = __builtin_amdgcn_mfma_f32_16x16x32_bf16(Bt[n][k], At[m][k], acc[ai][bj][m][n], 0, 0, 0); __builtin_amdgcn_s_setprio(0); } while (0)
; #define PG8_WAIT_V(n) asm volatile("s_waitcnt vmcnt(" #n ")" ::: "memory")
; #define PG8_WAIT_L(n) asm volatile("s_waitcnt lgkmcnt(" #n ")" ::: "memory")
; #define PG8_BAR __builtin_amdgcn_s_barrier()
; #define PG8_SCHED __builtin_amdgcn_sched_barrier(0)
; template <class Epi>
; __device__ __forceinline__ void gemm_phase(LAS unsigned char* lds, const Gemm g, const StaticOrder& S, const Epi& E) {
;     ...
;             PG8_STAGE(PG8_SB(0, 1), b2 + hstepB, voffB);
;             PG8_WAIT_V(6); PG8_BAR; PG8_MMA(1, 1, At, B1); PG8_BAR;
;             PG8_LDB(B0, 1, 0); PG8_SCHED; PG8_LDA(At, 1, 0); PG8_STAGE(PG8_SA(0, 1), a2 + hstepA, voffA);
;             PG8_WAIT_L(8); PG8_BAR; PG8_WAIT_L(0); PG8_MMA(0, 0, At, B0); PG8_BAR; PG8_SCHED;
;             PG8_LDB(B1, 1, 1); PG8_STAGE(PG8_SB(1, 0), b3, voffB);
;             PG8_BAR; PG8_WAIT_L(0); PG8_MMA(0, 1, At, B1); PG8_BAR;
;             PG8_LDA(At, 1, 1); PG8_STAGE(PG8_SA(1, 0), a3, voffA);
;             PG8_BAR; PG8_WAIT_L(0); PG8_MMA(1, 0, At, B0); PG8_BAR; PG8_SCHED;
	s_add_u32 s50, s24, 0x100000
	s_addc_u32 s51, s25, 0
	s_add_i32 s49, s43, s31
	v_lshl_add_u64 v[128:129], s[50:51], 0, v[156:157]
	s_mov_b32 m0, s49
	s_nop 0
	global_load_lds_dwordx4 v[128:129], off
	v_lshl_add_u64 v[128:129], s[50:51], 0, v[160:161]
	s_add_i32 m0, s49, 0x2000
	s_nop 0
	global_load_lds_dwordx4 v[128:129], off
	s_waitcnt vmcnt(6)
	s_barrier
	s_setprio 1
	v_mfma_f32_16x16x32_bf16 v[52:55], v[202:205], v[144:147], v[52:55]
	v_mfma_f32_16x16x32_bf16 v[48:51], v[210:213], v[144:147], v[48:51]
	v_mfma_f32_16x16x32_bf16 v[36:39], v[202:205], v[170:173], v[36:39]
	v_mfma_f32_16x16x32_bf16 v[32:35], v[210:213], v[170:173], v[32:35]
	v_mfma_f32_16x16x32_bf16 v[20:23], v[202:205], v[178:181], v[20:23]
	v_mfma_f32_16x16x32_bf16 v[16:19], v[210:213], v[178:181], v[16:19]
	v_mfma_f32_16x16x32_bf16 v[4:7], v[202:205], v[194:197], v[4:7]
	v_mfma_f32_16x16x32_bf16 v[0:3], v[210:213], v[194:197], v[0:3]
	v_mfma_f32_16x16x32_bf16 v[52:55], v[206:209], v[148:151], v[52:55]
	v_mfma_f32_16x16x32_bf16 v[48:51], v[214:217], v[148:151], v[48:51]
	v_mfma_f32_16x16x32_bf16 v[36:39], v[206:209], v[174:177], v[36:39]
	v_mfma_f32_16x16x32_bf16 v[32:35], v[214:217], v[174:177], v[32:35]
	v_mfma_f32_16x16x32_bf16 v[20:23], v[206:209], v[182:185], v[20:23]
	v_mfma_f32_16x16x32_bf16 v[16:19], v[214:217], v[182:185], v[16:19]
	v_mfma_f32_16x16x32_bf16 v[4:7], v[206:209], v[198:201], v[4:7]
	v_mfma_f32_16x16x32_bf16 v[0:3], v[214:217], v[198:201], v[0:3]
	s_setprio 0
	s_add_i32 s49, 0, 0x18000
	v_add_u32_e32 v140, s49, v188
	s_barrier
	ds_read_b128 v[128:131], v140
	ds_read_b128 v[132:135], v140 offset:1024
	ds_read_b128 v[136:139], v140 offset:2048
	ds_read_b128 v[140:143], v140 offset:3072
	s_add_u32 s26, s26, 0x100000
	s_addc_u32 s27, s27, 0
	s_mov_b32 m0, s35
	v_lshl_add_u64 v[202:203], s[26:27], 0, v[154:155]
	ds_read_b128 v[144:147], v191 offset:32768
	ds_read_b128 v[148:151], v191 offset:33792
	ds_read_b128 v[170:173], v191 offset:34816
	ds_read_b128 v[174:177], v191 offset:35840
	ds_read_b128 v[178:181], v191 offset:36864
	ds_read_b128 v[182:185], v191 offset:37888
	ds_read_b128 v[194:197], v191 offset:38912
	ds_read_b128 v[198:201], v191 offset:39936
	global_load_lds_dwordx4 v[202:203], off
	v_lshl_add_u64 v[202:203], s[26:27], 0, v[158:159]
	s_mov_b32 m0, s36
	s_nop 0
	global_load_lds_dwordx4 v[202:203], off
	s_waitcnt lgkmcnt(8)
	s_barrier
	s_waitcnt lgkmcnt(0)
	s_setprio 1
	s_waitcnt lgkmcnt(0)
	v_mfma_f32_16x16x32_bf16 v[124:127], v[128:131], v[144:147], v[124:127]
	v_mfma_f32_16x16x32_bf16 v[120:123], v[136:139], v[144:147], v[120:123]
	v_mfma_f32_16x16x32_bf16 v[108:111], v[128:131], v[170:173], v[108:111]
	v_mfma_f32_16x16x32_bf16 v[104:107], v[136:139], v[170:173], v[104:107]
	v_mfma_f32_16x16x32_bf16 v[92:95], v[128:131], v[178:181], v[92:95]
	v_mfma_f32_16x16x32_bf16 v[88:91], v[136:139], v[178:181], v[88:91]
	v_mfma_f32_16x16x32_bf16 v[76:79], v[128:131], v[194:197], v[76:79]
	v_mfma_f32_16x16x32_bf16 v[72:75], v[136:139], v[194:197], v[72:75]
	v_mfma_f32_16x16x32_bf16 v[124:127], v[132:135], v[148:151], v[124:127]
	v_mfma_f32_16x16x32_bf16 v[120:123], v[140:143], v[148:151], v[120:123]
	v_mfma_f32_16x16x32_bf16 v[108:111], v[132:135], v[174:177], v[108:111]
	v_mfma_f32_16x16x32_bf16 v[104:107], v[140:143], v[174:177], v[104:107]
	v_mfma_f32_16x16x32_bf16 v[92:95], v[132:135], v[182:185], v[92:95]
	v_mfma_f32_16x16x32_bf16 v[88:91], v[140:143], v[182:185], v[88:91]
	v_mfma_f32_16x16x32_bf16 v[76:79], v[132:135], v[198:201], v[76:79]
	v_mfma_f32_16x16x32_bf16 v[72:75], v[140:143], v[198:201], v[72:75]
	s_setprio 0
	s_barrier
	s_add_i32 s26, 0, 0x1c000
	s_add_i32 s27, s49, s31
	v_add_u32_e32 v214, s26, v188
	v_lshl_add_u64 v[186:187], v[186:187], 0, s[12:13]
	s_mov_b32 m0, s27
	ds_read_b128 v[202:205], v214
	ds_read_b128 v[206:209], v214 offset:1024
	ds_read_b128 v[210:213], v214 offset:2048
	ds_read_b128 v[214:217], v214 offset:3072
	global_load_lds_dwordx4 v[186:187], off
	v_lshl_add_u64 v[186:187], v[218:219], 0, s[12:13]
	s_add_i32 m0, s27, 0x2000
	s_nop 0
	global_load_lds_dwordx4 v[186:187], off
	s_barrier
	s_waitcnt lgkmcnt(0)
	s_setprio 1
	s_waitcnt lgkmcnt(0)
	v_mfma_f32_16x16x32_bf16 v[116:119], v[202:205], v[144:147], v[116:119]
	v_mfma_f32_16x16x32_bf16 v[112:115], v[210:213], v[144:147], v[112:115]
	v_mfma_f32_16x16x32_bf16 v[100:103], v[202:205], v[170:173], v[100:103]
	v_mfma_f32_16x16x32_bf16 v[96:99], v[210:213], v[170:173], v[96:99]
	v_mfma_f32_16x16x32_bf16 v[84:87], v[202:205], v[178:181], v[84:87]
	v_mfma_f32_16x16x32_bf16 v[80:83], v[210:213], v[178:181], v[80:83]
	v_mfma_f32_16x16x32_bf16 v[68:71], v[202:205], v[194:197], v[68:71]
	v_mfma_f32_16x16x32_bf16 v[64:67], v[210:213], v[194:197], v[64:67]
	v_mfma_f32_16x16x32_bf16 v[116:119], v[206:209], v[148:151], v[116:119]
	v_mfma_f32_16x16x32_bf16 v[112:115], v[214:217], v[148:151], v[112:115]
	v_mfma_f32_16x16x32_bf16 v[100:103], v[206:209], v[174:177], v[100:103]
	v_mfma_f32_16x16x32_bf16 v[96:99], v[214:217], v[174:177], v[96:99]
	v_mfma_f32_16x16x32_bf16 v[84:87], v[206:209], v[182:185], v[84:87]
	v_mfma_f32_16x16x32_bf16 v[80:83], v[214:217], v[182:185], v[80:83]
	v_mfma_f32_16x16x32_bf16 v[68:71], v[206:209], v[198:201], v[68:71]
	v_mfma_f32_16x16x32_bf16 v[64:67], v[214:217], v[198:201], v[64:67]
	s_setprio 0
	s_mov_b32 m0, s38
	v_lshl_add_u64 v[186:187], v[220:221], 0, s[12:13]
	s_barrier
	ds_read_b128 v[144:147], v191 offset:49152
	ds_read_b128 v[148:151], v191 offset:50176
	ds_read_b128 v[170:173], v191 offset:51200
	ds_read_b128 v[174:177], v191 offset:52224
	ds_read_b128 v[178:181], v191 offset:53248
	ds_read_b128 v[182:185], v191 offset:54272
	ds_read_b128 v[194:197], v191 offset:55296
	ds_read_b128 v[198:201], v191 offset:56320
	global_load_lds_dwordx4 v[186:187], off
	v_lshl_add_u64 v[186:187], v[222:223], 0, s[12:13]
	s_mov_b32 m0, s39
	s_nop 0
	global_load_lds_dwordx4 v[186:187], off
	s_barrier
; __device__ __forceinline__ void unpack8(const u32x4 v, float* f) { f[0] = bf_lo(v.x); f[1] = bf_hi(v.x); f[2] = bf_lo(v.y); f[3] = bf_hi(v.y); f[4] = bf_lo(v.z); f[5] = bf_hi(v.z); f[6] = bf_lo(v.w); f[7] = bf_hi(v.w); }
; #define PG8_STAGE(bufoff, gbase, voff) do { _Pragma("unroll") for (int _i = 0; _i < 2; ++_i) \
;         __builtin_amdgcn_global_load_lds((const unsigned*)((const char*)(gbase) + (voff)[_i]), (LAS unsigned*)(lds + (bufoff) + ldsw + _i * 8192), 16, 0, 0); } while (0)
; #define PG8_MMA(ai, bj, At, Bt) do { __builtin_amdgcn_s_setprio(1); _Pragma("unroll") for (int m = 0; m < 4; ++m) _Pragma("unroll") for (int n = 0; n < 2; ++n) _Pragma("unroll") for (int k = 0; k < 2; ++k) \
;         acc[ai][bj][m][n] = __builtin_amdgcn_mfma_f32_16x16x32_bf16(Bt[n][k], At[m][k], acc[ai][bj][m][n], 0, 0, 0); __builtin_amdgcn_s_setprio(0); } while (0)
; #define PG8_WAIT_V(n) asm volatile("s_waitcnt vmcnt(" #n ")" ::: "memory")
; #define PG8_WAIT_L(n) asm volatile("s_waitcnt lgkmcnt(" #n ")" ::: "memory")
;     __device__ __forceinline__ void operator()(const f32x4 (&acc)[2][2][4][2], const Unit& u, int wr, int wc, int fr, int fq, const float (&)[8]) const {
;         const int row0 = u.pm * BM + wr * 64 + fr, col0 = u.pn * BM + wc * 32 + 8 * fq;
; #pragma unroll
;         for (int ai = 0; ai < 2; ++ai) {
;             u32x4 bv[4][2];
; #pragma unroll
;             for (int m = 0; m < 4; ++m)
; #pragma unroll
;                 for (int bj = 0; bj < 2; ++bj) bv[m][bj] = *(const u32x4*)(xb + (size_t)(row0 + ai * HALF + m * 16) * DM + col0 + bj * HALF);
; #pragma unroll
;             for (int m = 0; m < 4; ++m) { const int row = row0 + ai * HALF + m * 16; const size_t ro = (size_t)row * DM + col0; float s = 0.f;
; #pragma unroll
;                 for (int bj = 0; bj < 2; ++bj) { float b8[8]; unpack8(bv[m][bj], b8);
;                     const f32x4 v0 = (f32x4){b8[0], b8[1], b8[2], b8[3]} + acc[ai][bj][m][0], v1 = (f32x4){b8[4], b8[5], b8[6], b8[7]} + acc[ai][bj][m][1];
; template <class Epi>
; __device__ __forceinline__ void gemm_phase(LAS unsigned char* lds, const Gemm g, const StaticOrder& S, const Epi& E) {
;     ...
;             PG8_BAR; PG8_WAIT_L(0); PG8_MMA(1, 0, At, B0); PG8_BAR; PG8_SCHED;
;             PG8_STAGE(PG8_SB(1, 1), b3 + hstepB, voffB);
;             PG8_WAIT_V(6); PG8_BAR; PG8_MMA(1, 1, At, B1); PG8_BAR;
	s_waitcnt lgkmcnt(0)
	s_setprio 1
	s_waitcnt lgkmcnt(0)
	v_mfma_f32_16x16x32_bf16 v[60:63], v[128:131], v[144:147], v[60:63]
	v_mfma_f32_16x16x32_bf16 v[56:59], v[136:139], v[144:147], v[56:59]
	v_mfma_f32_16x16x32_bf16 v[44:47], v[128:131], v[170:173], v[44:47]
	v_mfma_f32_16x16x32_bf16 v[40:43], v[136:139], v[170:173], v[40:43]
	v_mfma_f32_16x16x32_bf16 v[28:31], v[128:131], v[178:181], v[28:31]
	v_mfma_f32_16x16x32_bf16 v[24:27], v[136:139], v[178:181], v[24:27]
	v_mfma_f32_16x16x32_bf16 v[12:15], v[128:131], v[194:197], v[12:15]
	v_mfma_f32_16x16x32_bf16 v[8:11], v[136:139], v[194:197], v[8:11]
	v_mfma_f32_16x16x32_bf16 v[60:63], v[132:135], v[148:151], v[60:63]
	v_mfma_f32_16x16x32_bf16 v[56:59], v[140:143], v[148:151], v[56:59]
	v_mfma_f32_16x16x32_bf16 v[44:47], v[132:135], v[174:177], v[44:47]
	v_mfma_f32_16x16x32_bf16 v[40:43], v[140:143], v[174:177], v[40:43]
	v_mfma_f32_16x16x32_bf16 v[28:31], v[132:135], v[182:185], v[28:31]
	v_mfma_f32_16x16x32_bf16 v[24:27], v[140:143], v[182:185], v[24:27]
	v_mfma_f32_16x16x32_bf16 v[12:15], v[132:135], v[198:201], v[12:15]
	v_mfma_f32_16x16x32_bf16 v[8:11], v[140:143], v[198:201], v[8:11]
	s_setprio 0
	s_barrier
	s_add_u32 s24, s24, 0x100080
	s_addc_u32 s25, s25, 0
	s_add_i32 s26, s26, s31
	v_lshl_add_u64 v[128:129], s[24:25], 0, v[156:157]
	s_mov_b32 m0, s26
	s_nop 0
	global_load_lds_dwordx4 v[128:129], off
	v_lshl_add_u64 v[128:129], s[24:25], 0, v[160:161]
	s_add_i32 m0, s26, 0x2000
	s_nop 0
	global_load_lds_dwordx4 v[128:129], off
	s_waitcnt vmcnt(6)
	s_barrier
	s_setprio 1
	v_mfma_f32_16x16x32_bf16 v[52:55], v[202:205], v[144:147], v[52:55]
	v_mfma_f32_16x16x32_bf16 v[48:51], v[210:213], v[144:147], v[48:51]
	v_mfma_f32_16x16x32_bf16 v[36:39], v[202:205], v[170:173], v[36:39]
	v_mfma_f32_16x16x32_bf16 v[32:35], v[210:213], v[170:173], v[32:35]
	v_mfma_f32_16x16x32_bf16 v[20:23], v[202:205], v[178:181], v[20:23]
	v_mfma_f32_16x16x32_bf16 v[16:19], v[210:213], v[178:181], v[16:19]
	v_mfma_f32_16x16x32_bf16 v[4:7], v[202:205], v[194:197], v[4:7]
	v_mfma_f32_16x16x32_bf16 v[0:3], v[210:213], v[194:197], v[0:3]
	v_mfma_f32_16x16x32_bf16 v[52:55], v[206:209], v[148:151], v[52:55]
	v_mfma_f32_16x16x32_bf16 v[48:51], v[214:217], v[148:151], v[48:51]
	v_mfma_f32_16x16x32_bf16 v[36:39], v[206:209], v[174:177], v[36:39]
	v_mfma_f32_16x16x32_bf16 v[32:35], v[214:217], v[174:177], v[32:35]
	v_mfma_f32_16x16x32_bf16 v[20:23], v[206:209], v[182:185], v[20:23]
	v_mfma_f32_16x16x32_bf16 v[16:19], v[214:217], v[182:185], v[16:19]
	v_mfma_f32_16x16x32_bf16 v[4:7], v[206:209], v[198:201], v[4:7]
	v_mfma_f32_16x16x32_bf16 v[0:3], v[214:217], v[198:201], v[0:3]
	s_setprio 0
	s_add_i32 s48, s48, 2
	s_add_u32 s22, s22, 0x100
	s_addc_u32 s23, s23, 0
	s_add_u32 s46, s46, 0x100
	s_addc_u32 s47, s47, 0
	s_cmp_gt_u32 s48, 61
	s_barrier
	s_cbranch_scc0 .LBB0_1278
	v_lshl_or_b32 v170, s6, 8, v189
	v_lshl_add_u32 v172, s8, 8, v153
	v_ashrrev_i32_e32 v171, 31, v170
	v_lshlrev_b64 v[204:205], 1, v[170:171]
	v_ashrrev_i32_e32 v173, 31, v172
	v_lshl_add_u64 v[174:175], s[76:77], 0, v[204:205]
	v_lshlrev_b64 v[206:207], 11, v[172:173]
	v_lshl_add_u64 v[128:129], v[174:175], 0, v[206:207]
	global_load_dwordx4 v[196:199], v[128:129], off
	global_load_dwordx4 v[200:203], v[128:129], off offset:256
	v_or_b32_e32 v184, 16, v172
	v_or_b32_e32 v180, 32, v172
	v_or_b32_e32 v176, 48, v172
	v_ashrrev_i32_e32 v185, 31, v184
	v_ashrrev_i32_e32 v181, 31, v180
	v_ashrrev_i32_e32 v177, 31, v176
	v_lshlrev_b64 v[186:187], 11, v[184:185]
	v_lshlrev_b64 v[182:183], 11, v[180:181]
	v_lshlrev_b64 v[178:179], 11, v[176:177]
	v_lshl_add_u64 v[128:129], v[174:175], 0, v[186:187]
	v_lshl_add_u64 v[130:131], v[174:175], 0, v[182:183]
	v_lshl_add_u64 v[194:195], v[174:175], 0, v[178:179]
	global_load_dwordx4 v[148:151], v[128:129], off
	global_load_dwordx4 v[144:147], v[128:129], off offset:256
	global_load_dwordx4 v[140:143], v[130:131], off
	global_load_dwordx4 v[136:139], v[130:131], off offset:256
	global_load_dwordx4 v[132:135], v[194:195], off
	s_nop 0
	global_load_dwordx4 v[128:131], v[194:195], off offset:256
	v_add_u32_e32 v226, 0x80, v172
	v_ashrrev_i32_e32 v227, 31, v226
	v_lshlrev_b64 v[226:227], 11, v[226:227]
	v_lshl_add_u64 v[226:227], v[174:175], 0, v[226:227]
	global_load_dwordx4 v[216:219], v[226:227], off
	global_load_dwordx4 v[220:223], v[226:227], off offset:256
	v_add_u32_e32 v226, 0x90, v172
	v_ashrrev_i32_e32 v227, 31, v226
	v_lshlrev_b64 v[226:227], 11, v[226:227]
	v_lshl_add_u64 v[226:227], v[174:175], 0, v[226:227]
	global_load_dwordx4 v[228:231], v[226:227], off
	global_load_dwordx4 v[232:235], v[226:227], off offset:256
	v_add_u32_e32 v226, 0xa0, v172
	v_ashrrev_i32_e32 v227, 31, v226
	v_lshlrev_b64 v[226:227], 11, v[226:227]
	v_lshl_add_u64 v[226:227], v[174:175], 0, v[226:227]
	global_load_dwordx4 v[236:239], v[226:227], off
	global_load_dwordx4 v[240:243], v[226:227], off offset:256
	v_add_u32_e32 v226, 0xb0, v172
	v_ashrrev_i32_e32 v227, 31, v226
	v_lshlrev_b64 v[226:227], 11, v[226:227]
	v_lshl_add_u64 v[226:227], v[174:175], 0, v[226:227]
	global_load_dwordx4 v[244:247], v[226:227], off
	global_load_dwordx4 v[252:255], v[226:227], off offset:256
	v_and_b32_e32 v195, 64, v193
	v_xor_b32_e32 v194, 16, v193
	v_add_u32_e32 v195, 64, v195
	v_xor_b32_e32 v208, 32, v193
	v_cmp_lt_i32_e32 vcc, v194, v195
	s_waitcnt vmcnt(15)
	v_and_b32_e32 v209, 0xffff0000, v196
	v_cndmask_b32_e32 v194, v193, v194, vcc
	v_cmp_lt_i32_e32 vcc, v208, v195
	v_lshlrev_b32_e32 v195, 2, v194
	s_waitcnt vmcnt(14)
; __device__ __forceinline__ unsigned pk2(float lo, float hi) { const f32x2 v = (f32x2){lo, hi}; const bf16x2_t b = __builtin_convertvector(v, bf16x2_t); return __builtin_bit_cast(unsigned, b); }
; __device__ __forceinline__ void unpack8(const u32x4 v, float* f) { f[0] = bf_lo(v.x); f[1] = bf_hi(v.x); f[2] = bf_lo(v.y); f[3] = bf_hi(v.y); f[4] = bf_lo(v.z); f[5] = bf_hi(v.z); f[6] = bf_lo(v.w); f[7] = bf_hi(v.w); }
;     __device__ __forceinline__ void operator()(const f32x4 (&acc)[2][2][4][2], const Unit& u, int wr, int wc, int fr, int fq, const float (&)[8]) const {
;     ...
;             for (int m = 0; m < 4; ++m) { const int row = row0 + ai * HALF + m * 16; const size_t ro = (size_t)row * DM + col0; float s = 0.f;
; #pragma unroll
;                 for (int bj = 0; bj < 2; ++bj) { float b8[8]; unpack8(bv[m][bj], b8);
;                     const f32x4 v0 = (f32x4){b8[0], b8[1], b8[2], b8[3]} + acc[ai][bj][m][0], v1 = (f32x4){b8[4], b8[5], b8[6], b8[7]} + acc[ai][bj][m][1];
;                     s += v0[0] * v0[0] + v0[1] * v0[1] + v0[2] * v0[2] + v0[3] * v0[3] + v1[0] * v1[0] + v1[1] * v1[1] + v1[2] * v1[2] + v1[3] * v1[3];
;                     if (LAST) { *(f32x4*)(out + ro + bj * HALF) = v0; *(f32x4*)(out + ro + bj * HALF + 4) = v1; }
;                     else { u32x4 w; w.x = pk2(v0[0], v0[1]); w.y = pk2(v0[2], v0[3]); w.z = pk2(v1[0], v1[1]); w.w = pk2(v1[2], v1[3]); *(u32x4*)(xb + ro + bj * HALF) = w; } }
;                 s += __shfl_xor(s, 16); s += __shfl_xor(s, 32);
;                 if (fq == 0) ss[(size_t)row * 16 + u.pn * 4 + wc] = s; }
	v_lshlrev_b32_e32 v212, 16, v200
	v_cndmask_b32_e32 v208, v193, v208, vcc
	v_lshlrev_b32_e32 v194, 2, v208
	v_lshlrev_b32_e32 v208, 16, v196
	v_and_b32_e32 v213, 0xffff0000, v200
	v_lshlrev_b32_e32 v210, 16, v198
	v_and_b32_e32 v211, 0xffff0000, v198
	v_lshlrev_b32_e32 v198, 16, v199
	v_and_b32_e32 v199, 0xffff0000, v199
	v_lshlrev_b32_e32 v200, 16, v201
	v_and_b32_e32 v201, 0xffff0000, v201
	v_lshlrev_b32_e32 v214, 16, v202
	v_and_b32_e32 v215, 0xffff0000, v202
	v_pk_add_f32 v[124:125], v[124:125], v[208:209]
	v_pk_add_f32 v[116:117], v[116:117], v[212:213]
	v_lshlrev_b32_e32 v196, 16, v197
	v_and_b32_e32 v197, 0xffff0000, v197
	v_pk_add_f32 v[122:123], v[122:123], v[198:199]
	v_pk_add_f32 v[118:119], v[118:119], v[200:201]
	v_pk_add_f32 v[198:199], v[112:113], v[214:215]
	v_mul_f32_e32 v200, v125, v125
	v_cvt_pk_bf16_f32 v112, v124, v125
	v_mul_f32_e32 v125, v117, v117
	v_pk_add_f32 v[126:127], v[126:127], v[196:197]
	v_fmac_f32_e32 v200, v124, v124
	v_fmac_f32_e32 v125, v116, v116
	v_fmac_f32_e32 v200, v126, v126
	v_fmac_f32_e32 v125, v118, v118
	v_pk_add_f32 v[120:121], v[120:121], v[210:211]
	v_fmac_f32_e32 v200, v127, v127
	v_fmac_f32_e32 v125, v119, v119
	v_lshlrev_b32_e32 v202, 16, v203
	v_and_b32_e32 v203, 0xffff0000, v203
	v_fmac_f32_e32 v200, v120, v120
	v_fmac_f32_e32 v125, v198, v198
	v_pk_add_f32 v[196:197], v[114:115], v[202:203]
	v_fmac_f32_e32 v200, v121, v121
	v_fmac_f32_e32 v125, v199, v199
	v_fmac_f32_e32 v200, v122, v122
	v_fmac_f32_e32 v125, v196, v196
	v_fmac_f32_e32 v200, v123, v123
	v_fmac_f32_e32 v125, v197, v197
	v_cvt_pk_bf16_f32 v115, v122, v123
	v_add_f32_e32 v122, v200, v125
	ds_bpermute_b32 v123, v195, v122
	v_cvt_pk_bf16_f32 v114, v120, v121
	v_lshl_add_u64 v[120:121], s[76:77], 0, v[206:207]
	v_cvt_pk_bf16_f32 v113, v126, v127
	v_lshl_add_u64 v[120:121], v[120:121], 0, v[204:205]
	global_store_dwordx4 v[120:121], v[112:115], off
	s_waitcnt lgkmcnt(0)
	s_nop 0
	v_add_f32_e32 v112, v122, v123
	ds_bpermute_b32 v113, v194, v112
	v_cvt_pk_bf16_f32 v114, v116, v117
	v_cvt_pk_bf16_f32 v115, v118, v119
	v_cvt_pk_bf16_f32 v116, v198, v199
	v_cvt_pk_bf16_f32 v117, v196, v197
	global_store_dwordx4 v[120:121], v[114:117], off offset:256
	s_and_saveexec_b64 s[22:23], s[0:1]
	s_cbranch_execz .LBB0_1281
	s_waitcnt lgkmcnt(0)
	v_add_f32_e32 v114, v112, v113
	s_lshl_b32 s24, s6, 2
	v_lshlrev_b64 v[112:113], 6, v[172:173]
	s_ashr_i32 s25, s24, 31
	v_lshl_add_u64 v[112:113], s[10:11], 0, v[112:113]
	v_lshl_add_u64 v[112:113], s[24:25], 2, v[112:113]
	s_lshl_b32 s8, s37, 2
	v_lshl_add_u64 v[112:113], v[112:113], 0, s[8:9]
	global_store_dword v[112:113], v114, off
.LBB0_1281:
	s_or_b64 exec, exec, s[22:23]
	s_waitcnt vmcnt(15)
	v_lshlrev_b32_e32 v112, 16, v148
	s_waitcnt lgkmcnt(0)
	v_and_b32_e32 v113, 0xffff0000, v148
	v_lshlrev_b32_e32 v116, 16, v150
	v_and_b32_e32 v117, 0xffff0000, v150
	v_lshlrev_b32_e32 v118, 16, v151
	v_and_b32_e32 v119, 0xffff0000, v151
	v_pk_add_f32 v[108:109], v[108:109], v[112:113]
	v_lshlrev_b32_e32 v114, 16, v149
	v_and_b32_e32 v115, 0xffff0000, v149
	v_pk_add_f32 v[112:113], v[106:107], v[118:119]
	v_pk_add_f32 v[106:107], v[104:105], v[116:117]
	v_mul_f32_e32 v116, v109, v109
	v_pk_add_f32 v[110:111], v[110:111], v[114:115]
	v_fmac_f32_e32 v116, v108, v108
	v_fmac_f32_e32 v116, v110, v110
	v_fmac_f32_e32 v116, v111, v111
	v_fmac_f32_e32 v116, v106, v106
	v_fmac_f32_e32 v116, v107, v107
	v_fmac_f32_e32 v116, v112, v112
	v_cvt_pk_bf16_f32 v104, v108, v109
	s_waitcnt vmcnt(14)
	v_lshlrev_b32_e32 v108, 16, v144
	v_and_b32_e32 v109, 0xffff0000, v144
	v_fmac_f32_e32 v116, v113, v113
	v_cvt_pk_bf16_f32 v105, v110, v111
	v_cvt_pk_bf16_f32 v106, v106, v107
	v_cvt_pk_bf16_f32 v107, v112, v113
	v_lshlrev_b32_e32 v110, 16, v145
	v_and_b32_e32 v111, 0xffff0000, v145
	v_lshlrev_b32_e32 v112, 16, v146
	v_and_b32_e32 v113, 0xffff0000, v146
	v_pk_add_f32 v[100:101], v[100:101], v[108:109]
	v_pk_add_f32 v[102:103], v[102:103], v[110:111]
	v_pk_add_f32 v[110:111], v[96:97], v[112:113]
	v_mul_f32_e32 v96, v101, v101
	v_fmac_f32_e32 v96, v100, v100
	v_fmac_f32_e32 v96, v102, v102
	v_fmac_f32_e32 v96, v103, v103
	v_lshlrev_b32_e32 v114, 16, v147
	v_and_b32_e32 v115, 0xffff0000, v147
	v_fmac_f32_e32 v96, v110, v110
	v_pk_add_f32 v[108:109], v[98:99], v[114:115]
	v_fmac_f32_e32 v96, v111, v111
	v_fmac_f32_e32 v96, v108, v108
	v_fmac_f32_e32 v96, v109, v109
	v_add_f32_e32 v99, v116, v96
	ds_bpermute_b32 v114, v195, v99
	v_lshl_add_u64 v[96:97], s[76:77], 0, v[186:187]
	v_lshl_add_u64 v[112:113], v[170:171], 1, v[96:97]
	v_cvt_pk_bf16_f32 v98, v100, v101
	v_cvt_pk_bf16_f32 v100, v110, v111
	s_waitcnt lgkmcnt(0)
	v_add_f32_e32 v96, v99, v114
	ds_bpermute_b32 v97, v194, v96
	v_cvt_pk_bf16_f32 v99, v102, v103
	v_cvt_pk_bf16_f32 v101, v108, v109
	global_store_dwordx4 v[112:113], v[104:107], off
	global_store_dwordx4 v[112:113], v[98:101], off offset:256
	s_and_saveexec_b64 s[22:23], s[0:1]
	s_cbranch_execz .LBB0_1283
	s_waitcnt lgkmcnt(0)
	v_add_f32_e32 v98, v96, v97
	s_lshl_b32 s24, s6, 2
	v_lshlrev_b64 v[96:97], 6, v[184:185]
	s_ashr_i32 s25, s24, 31
	v_lshl_add_u64 v[96:97], s[10:11], 0, v[96:97]
	v_lshl_add_u64 v[96:97], s[24:25], 2, v[96:97]
	s_lshl_b32 s8, s37, 2
	v_lshl_add_u64 v[96:97], v[96:97], 0, s[8:9]
	global_store_dword v[96:97], v98, off
; __device__ __forceinline__ unsigned pk2(float lo, float hi) { const f32x2 v = (f32x2){lo, hi}; const bf16x2_t b = __builtin_convertvector(v, bf16x2_t); return __builtin_bit_cast(unsigned, b); }
; __device__ __forceinline__ void unpack8(const u32x4 v, float* f) { f[0] = bf_lo(v.x); f[1] = bf_hi(v.x); f[2] = bf_lo(v.y); f[3] = bf_hi(v.y); f[4] = bf_lo(v.z); f[5] = bf_hi(v.z); f[6] = bf_lo(v.w); f[7] = bf_hi(v.w); }
;     __device__ __forceinline__ void operator()(const f32x4 (&acc)[2][2][4][2], const Unit& u, int wr, int wc, int fr, int fq, const float (&)[8]) const {
;     ...
;             for (int m = 0; m < 4; ++m) { const int row = row0 + ai * HALF + m * 16; const size_t ro = (size_t)row * DM + col0; float s = 0.f;
; #pragma unroll
;                 for (int bj = 0; bj < 2; ++bj) { float b8[8]; unpack8(bv[m][bj], b8);
;                     const f32x4 v0 = (f32x4){b8[0], b8[1], b8[2], b8[3]} + acc[ai][bj][m][0], v1 = (f32x4){b8[4], b8[5], b8[6], b8[7]} + acc[ai][bj][m][1];
;                     s += v0[0] * v0[0] + v0[1] * v0[1] + v0[2] * v0[2] + v0[3] * v0[3] + v1[0] * v1[0] + v1[1] * v1[1] + v1[2] * v1[2] + v1[3] * v1[3];
;                     if (LAST) { *(f32x4*)(out + ro + bj * HALF) = v0; *(f32x4*)(out + ro + bj * HALF + 4) = v1; }
;                     else { u32x4 w; w.x = pk2(v0[0], v0[1]); w.y = pk2(v0[2], v0[3]); w.z = pk2(v1[0], v1[1]); w.w = pk2(v1[2], v1[3]); *(u32x4*)(xb + ro + bj * HALF) = w; } }
;                 s += __shfl_xor(s, 16); s += __shfl_xor(s, 32);
;                 if (fq == 0) ss[(size_t)row * 16 + u.pn * 4 + wc] = s; }
.LBB0_1283:
	s_or_b64 exec, exec, s[22:23]
	s_waitcnt vmcnt(15)
	v_lshlrev_b32_e32 v96, 16, v140
	s_waitcnt lgkmcnt(0)
	v_and_b32_e32 v97, 0xffff0000, v140
	v_lshlrev_b32_e32 v100, 16, v142
	v_and_b32_e32 v101, 0xffff0000, v142
	v_lshlrev_b32_e32 v102, 16, v143
	v_and_b32_e32 v103, 0xffff0000, v143
	v_pk_add_f32 v[92:93], v[92:93], v[96:97]
	v_lshlrev_b32_e32 v98, 16, v141
	v_and_b32_e32 v99, 0xffff0000, v141
	v_pk_add_f32 v[96:97], v[90:91], v[102:103]
	v_pk_add_f32 v[90:91], v[88:89], v[100:101]
	v_mul_f32_e32 v100, v93, v93
	v_pk_add_f32 v[94:95], v[94:95], v[98:99]
	v_fmac_f32_e32 v100, v92, v92
	v_fmac_f32_e32 v100, v94, v94
	v_fmac_f32_e32 v100, v95, v95
	v_fmac_f32_e32 v100, v90, v90
	v_fmac_f32_e32 v100, v91, v91
	v_fmac_f32_e32 v100, v96, v96
	v_cvt_pk_bf16_f32 v88, v92, v93
	s_waitcnt vmcnt(14)
	v_lshlrev_b32_e32 v92, 16, v136
	v_and_b32_e32 v93, 0xffff0000, v136
	v_fmac_f32_e32 v100, v97, v97
	v_cvt_pk_bf16_f32 v89, v94, v95
	v_cvt_pk_bf16_f32 v90, v90, v91
	v_cvt_pk_bf16_f32 v91, v96, v97
	v_lshlrev_b32_e32 v94, 16, v137
	v_and_b32_e32 v95, 0xffff0000, v137
	v_lshlrev_b32_e32 v96, 16, v138
	v_and_b32_e32 v97, 0xffff0000, v138
	v_pk_add_f32 v[84:85], v[84:85], v[92:93]
	v_pk_add_f32 v[86:87], v[86:87], v[94:95]
	v_pk_add_f32 v[94:95], v[80:81], v[96:97]
	v_mul_f32_e32 v80, v85, v85
	v_fmac_f32_e32 v80, v84, v84
	v_fmac_f32_e32 v80, v86, v86
	v_fmac_f32_e32 v80, v87, v87
	v_lshlrev_b32_e32 v98, 16, v139
	v_and_b32_e32 v99, 0xffff0000, v139
	v_fmac_f32_e32 v80, v94, v94
	v_pk_add_f32 v[92:93], v[82:83], v[98:99]
	v_fmac_f32_e32 v80, v95, v95
	v_fmac_f32_e32 v80, v92, v92
	v_fmac_f32_e32 v80, v93, v93
	v_add_f32_e32 v83, v100, v80
	ds_bpermute_b32 v98, v195, v83
	v_lshl_add_u64 v[80:81], s[76:77], 0, v[182:183]
	v_lshl_add_u64 v[96:97], v[170:171], 1, v[80:81]
	v_cvt_pk_bf16_f32 v82, v84, v85
	v_cvt_pk_bf16_f32 v84, v94, v95
	s_waitcnt lgkmcnt(0)
	v_add_f32_e32 v80, v83, v98
	ds_bpermute_b32 v81, v194, v80
	v_cvt_pk_bf16_f32 v83, v86, v87
	v_cvt_pk_bf16_f32 v85, v92, v93
	global_store_dwordx4 v[96:97], v[88:91], off
	global_store_dwordx4 v[96:97], v[82:85], off offset:256
	s_and_saveexec_b64 s[22:23], s[0:1]
	s_cbranch_execz .LBB0_1285
	s_waitcnt lgkmcnt(0)
	v_add_f32_e32 v82, v80, v81
	s_lshl_b32 s24, s6, 2
	v_lshlrev_b64 v[80:81], 6, v[180:181]
	s_ashr_i32 s25, s24, 31
	v_lshl_add_u64 v[80:81], s[10:11], 0, v[80:81]
	v_lshl_add_u64 v[80:81], s[24:25], 2, v[80:81]
	s_lshl_b32 s8, s37, 2
	v_lshl_add_u64 v[80:81], v[80:81], 0, s[8:9]
	global_store_dword v[80:81], v82, off
.LBB0_1285:
	s_or_b64 exec, exec, s[22:23]
	s_waitcnt vmcnt(15)
	v_lshlrev_b32_e32 v80, 16, v132
	s_waitcnt lgkmcnt(0)
	v_and_b32_e32 v81, 0xffff0000, v132
	v_lshlrev_b32_e32 v84, 16, v134
	v_and_b32_e32 v85, 0xffff0000, v134
	v_lshlrev_b32_e32 v86, 16, v135
	v_and_b32_e32 v87, 0xffff0000, v135
	v_pk_add_f32 v[76:77], v[76:77], v[80:81]
	v_lshlrev_b32_e32 v82, 16, v133
	v_and_b32_e32 v83, 0xffff0000, v133
	v_pk_add_f32 v[80:81], v[74:75], v[86:87]
	v_pk_add_f32 v[74:75], v[72:73], v[84:85]
	v_mul_f32_e32 v84, v77, v77
	v_pk_add_f32 v[78:79], v[78:79], v[82:83]
	v_fmac_f32_e32 v84, v76, v76
	v_fmac_f32_e32 v84, v78, v78
	v_fmac_f32_e32 v84, v79, v79
	v_fmac_f32_e32 v84, v74, v74
	v_fmac_f32_e32 v84, v75, v75
	v_fmac_f32_e32 v84, v80, v80
	v_cvt_pk_bf16_f32 v72, v76, v77
	s_waitcnt vmcnt(14)
	v_lshlrev_b32_e32 v76, 16, v128
	v_and_b32_e32 v77, 0xffff0000, v128
	v_fmac_f32_e32 v84, v81, v81
	v_cvt_pk_bf16_f32 v73, v78, v79
	v_cvt_pk_bf16_f32 v74, v74, v75
	v_cvt_pk_bf16_f32 v75, v80, v81
	v_lshlrev_b32_e32 v78, 16, v129
	v_and_b32_e32 v79, 0xffff0000, v129
	v_lshlrev_b32_e32 v80, 16, v130
	v_and_b32_e32 v81, 0xffff0000, v130
	v_pk_add_f32 v[68:69], v[68:69], v[76:77]
	v_pk_add_f32 v[70:71], v[70:71], v[78:79]
	v_pk_add_f32 v[78:79], v[64:65], v[80:81]
	v_mul_f32_e32 v64, v69, v69
	v_fmac_f32_e32 v64, v68, v68
	v_fmac_f32_e32 v64, v70, v70
	v_fmac_f32_e32 v64, v71, v71
	v_lshlrev_b32_e32 v82, 16, v131
	v_and_b32_e32 v83, 0xffff0000, v131
	v_fmac_f32_e32 v64, v78, v78
	v_pk_add_f32 v[76:77], v[66:67], v[82:83]
	v_fmac_f32_e32 v64, v79, v79
	v_fmac_f32_e32 v64, v76, v76
	v_fmac_f32_e32 v64, v77, v77
	v_add_f32_e32 v67, v84, v64
	ds_bpermute_b32 v82, v195, v67
	v_lshl_add_u64 v[64:65], s[76:77], 0, v[178:179]
	v_lshl_add_u64 v[80:81], v[170:171], 1, v[64:65]
	v_cvt_pk_bf16_f32 v66, v68, v69
	v_cvt_pk_bf16_f32 v68, v78, v79
	s_waitcnt lgkmcnt(0)
	v_add_f32_e32 v64, v67, v82
	ds_bpermute_b32 v65, v194, v64
	v_cvt_pk_bf16_f32 v67, v70, v71
	v_cvt_pk_bf16_f32 v69, v76, v77
	global_store_dwordx4 v[80:81], v[72:75], off
	global_store_dwordx4 v[80:81], v[66:69], off offset:256
	s_and_saveexec_b64 s[22:23], s[0:1]
	s_cbranch_execz .LBB0_1287
	s_waitcnt lgkmcnt(0)
	v_add_f32_e32 v66, v64, v65
	s_lshl_b32 s24, s6, 2
	v_lshlrev_b64 v[64:65], 6, v[176:177]
	s_ashr_i32 s25, s24, 31
	v_lshl_add_u64 v[64:65], s[10:11], 0, v[64:65]
	v_lshl_add_u64 v[64:65], s[24:25], 2, v[64:65]
	s_lshl_b32 s8, s37, 2
	v_lshl_add_u64 v[64:65], v[64:65], 0, s[8:9]
	global_store_dword v[64:65], v66, off
; __device__ __forceinline__ unsigned pk2(float lo, float hi) { const f32x2 v = (f32x2){lo, hi}; const bf16x2_t b = __builtin_convertvector(v, bf16x2_t); return __builtin_bit_cast(unsigned, b); }
; __device__ __forceinline__ void unpack8(const u32x4 v, float* f) { f[0] = bf_lo(v.x); f[1] = bf_hi(v.x); f[2] = bf_lo(v.y); f[3] = bf_hi(v.y); f[4] = bf_lo(v.z); f[5] = bf_hi(v.z); f[6] = bf_lo(v.w); f[7] = bf_hi(v.w); }
;     __device__ __forceinline__ void operator()(const f32x4 (&acc)[2][2][4][2], const Unit& u, int wr, int wc, int fr, int fq, const float (&)[8]) const {
;     ...
;             for (int m = 0; m < 4; ++m)
; #pragma unroll
;                 for (int bj = 0; bj < 2; ++bj) bv[m][bj] = *(const u32x4*)(xb + (size_t)(row0 + ai * HALF + m * 16) * DM + col0 + bj * HALF);
; #pragma unroll
;             for (int m = 0; m < 4; ++m) { const int row = row0 + ai * HALF + m * 16; const size_t ro = (size_t)row * DM + col0; float s = 0.f;
; #pragma unroll
;                 for (int bj = 0; bj < 2; ++bj) { float b8[8]; unpack8(bv[m][bj], b8);
;                     const f32x4 v0 = (f32x4){b8[0], b8[1], b8[2], b8[3]} + acc[ai][bj][m][0], v1 = (f32x4){b8[4], b8[5], b8[6], b8[7]} + acc[ai][bj][m][1];
;                     s += v0[0] * v0[0] + v0[1] * v0[1] + v0[2] * v0[2] + v0[3] * v0[3] + v1[0] * v1[0] + v1[1] * v1[1] + v1[2] * v1[2] + v1[3] * v1[3];
;                     if (LAST) { *(f32x4*)(out + ro + bj * HALF) = v0; *(f32x4*)(out + ro + bj * HALF + 4) = v1; }
;                     else { u32x4 w; w.x = pk2(v0[0], v0[1]); w.y = pk2(v0[2], v0[3]); w.z = pk2(v1[0], v1[1]); w.w = pk2(v1[2], v1[3]); *(u32x4*)(xb + ro + bj * HALF) = w; } }
;                 s += __shfl_xor(s, 16); s += __shfl_xor(s, 32);
;                 if (fq == 0) ss[(size_t)row * 16 + u.pn * 4 + wc] = s; }
.LBB0_1287:
	s_or_b64 exec, exec, s[22:23]
	v_add_u32_e32 v100, 0x80, v172
	v_ashrrev_i32_e32 v101, 31, v100
	v_lshlrev_b64 v[110:111], 11, v[100:101]
	s_waitcnt lgkmcnt(0)
	v_lshl_add_u64 v[64:65], v[174:175], 0, v[110:111]
	s_waitcnt vmcnt(15)
	v_mov_b32_e32 v102, v216
	v_mov_b32_e32 v103, v217
	v_mov_b32_e32 v104, v218
	v_mov_b32_e32 v105, v219
	s_waitcnt vmcnt(14)
	v_mov_b32_e32 v106, v220
	v_mov_b32_e32 v107, v221
	v_mov_b32_e32 v108, v222
	v_mov_b32_e32 v109, v223
	v_add_u32_e32 v96, 0x90, v172
	v_add_u32_e32 v92, 0xa0, v172
	v_add_u32_e32 v88, 0xb0, v172
	v_ashrrev_i32_e32 v97, 31, v96
	v_ashrrev_i32_e32 v93, 31, v92
	v_ashrrev_i32_e32 v89, 31, v88
	v_lshlrev_b64 v[98:99], 11, v[96:97]
	v_lshlrev_b64 v[94:95], 11, v[92:93]
	v_lshlrev_b64 v[90:91], 11, v[88:89]
	v_lshl_add_u64 v[64:65], v[174:175], 0, v[98:99]
	v_lshl_add_u64 v[66:67], v[174:175], 0, v[94:95]
	v_lshl_add_u64 v[112:113], v[174:175], 0, v[90:91]
	s_waitcnt vmcnt(13)
	v_mov_b32_e32 v84, v228
	v_mov_b32_e32 v85, v229
	v_mov_b32_e32 v86, v230
	v_mov_b32_e32 v87, v231
	s_waitcnt vmcnt(12)
	v_mov_b32_e32 v80, v232
	v_mov_b32_e32 v81, v233
	v_mov_b32_e32 v82, v234
	v_mov_b32_e32 v83, v235
	s_waitcnt vmcnt(11)
	v_mov_b32_e32 v76, v236
	v_mov_b32_e32 v77, v237
	v_mov_b32_e32 v78, v238
	v_mov_b32_e32 v79, v239
	s_waitcnt vmcnt(10)
	v_mov_b32_e32 v72, v240
	v_mov_b32_e32 v73, v241
	v_mov_b32_e32 v74, v242
	v_mov_b32_e32 v75, v243
	s_waitcnt vmcnt(9)
	v_mov_b32_e32 v68, v244
	v_mov_b32_e32 v69, v245
	v_mov_b32_e32 v70, v246
	v_mov_b32_e32 v71, v247
	s_nop 0
	s_waitcnt vmcnt(8)
	v_mov_b32_e32 v64, v252
	v_mov_b32_e32 v65, v253
	v_mov_b32_e32 v66, v254
	v_mov_b32_e32 v67, v255
	s_nop 0
	v_lshlrev_b32_e32 v112, 16, v102
	v_and_b32_e32 v113, 0xffff0000, v102
	s_nop 0
	v_lshlrev_b32_e32 v116, 16, v106
	v_and_b32_e32 v117, 0xffff0000, v106
	v_lshlrev_b32_e32 v114, 16, v104
	v_and_b32_e32 v115, 0xffff0000, v104
	v_lshlrev_b32_e32 v104, 16, v105
	v_and_b32_e32 v105, 0xffff0000, v105
	v_lshlrev_b32_e32 v106, 16, v107
	v_and_b32_e32 v107, 0xffff0000, v107
	v_lshlrev_b32_e32 v118, 16, v108
	v_and_b32_e32 v119, 0xffff0000, v108
	v_pk_add_f32 v[60:61], v[60:61], v[112:113]
	v_pk_add_f32 v[52:53], v[52:53], v[116:117]
	v_lshlrev_b32_e32 v102, 16, v103
	v_and_b32_e32 v103, 0xffff0000, v103
	v_pk_add_f32 v[58:59], v[58:59], v[104:105]
	v_pk_add_f32 v[54:55], v[54:55], v[106:107]
	v_pk_add_f32 v[104:105], v[48:49], v[118:119]
	v_mul_f32_e32 v106, v61, v61
	v_cvt_pk_bf16_f32 v48, v60, v61
	v_mul_f32_e32 v61, v53, v53
	v_pk_add_f32 v[62:63], v[62:63], v[102:103]
	v_fmac_f32_e32 v106, v60, v60
	v_fmac_f32_e32 v61, v52, v52
	v_fmac_f32_e32 v106, v62, v62
	v_fmac_f32_e32 v61, v54, v54
	v_pk_add_f32 v[56:57], v[56:57], v[114:115]
	v_fmac_f32_e32 v106, v63, v63
	v_fmac_f32_e32 v61, v55, v55
	v_lshlrev_b32_e32 v108, 16, v109
	v_and_b32_e32 v109, 0xffff0000, v109
	v_fmac_f32_e32 v106, v56, v56
	v_fmac_f32_e32 v61, v104, v104
	v_pk_add_f32 v[102:103], v[50:51], v[108:109]
	v_fmac_f32_e32 v106, v57, v57
	v_fmac_f32_e32 v61, v105, v105
	v_fmac_f32_e32 v106, v58, v58
	v_fmac_f32_e32 v61, v102, v102
	v_fmac_f32_e32 v106, v59, v59
	v_fmac_f32_e32 v61, v103, v103
	v_cvt_pk_bf16_f32 v51, v58, v59
	v_add_f32_e32 v58, v106, v61
	ds_bpermute_b32 v59, v195, v58
	v_cvt_pk_bf16_f32 v50, v56, v57
	v_lshl_add_u64 v[56:57], s[76:77], 0, v[110:111]
	v_cvt_pk_bf16_f32 v49, v62, v63
	v_lshl_add_u64 v[56:57], v[170:171], 1, v[56:57]
	global_store_dwordx4 v[56:57], v[48:51], off
	s_waitcnt lgkmcnt(0)
	s_nop 0
	v_add_f32_e32 v48, v58, v59
	ds_bpermute_b32 v49, v194, v48
	v_cvt_pk_bf16_f32 v50, v52, v53
	v_cvt_pk_bf16_f32 v51, v54, v55
	v_cvt_pk_bf16_f32 v52, v104, v105
	v_cvt_pk_bf16_f32 v53, v102, v103
	global_store_dwordx4 v[56:57], v[50:53], off offset:256
	s_and_saveexec_b64 s[22:23], s[0:1]
	s_cbranch_execz .LBB0_1289
	s_waitcnt lgkmcnt(0)
	v_add_f32_e32 v50, v48, v49
	s_lshl_b32 s24, s6, 2
	v_lshlrev_b64 v[48:49], 6, v[100:101]
	s_ashr_i32 s25, s24, 31
	v_lshl_add_u64 v[48:49], s[10:11], 0, v[48:49]
	v_lshl_add_u64 v[48:49], s[24:25], 2, v[48:49]
	s_lshl_b32 s8, s37, 2
	v_lshl_add_u64 v[48:49], v[48:49], 0, s[8:9]
	global_store_dword v[48:49], v50, off
